# GLA/retention y stored as two bf16 halves from lanes 0/8 of each row (global_store_short): drops the DPP mov and its wait-state nops
# speedup vs baseline: 1.0223x; 1.0111x over previous
.Lret2_gw2:
	s_mov_b32 s20, 0xffff0000
	s_mov_b32 s21, -1
	v_mov_b32_e32 v41, v26
	v_mul_f32_e32 v41, v41, v41
	v_mul_f32_e32 v41, v41, v41
	v_mul_f32_e32 v41, v41, v41
	v_mul_f32_e32 v41, v41, v41
	v_mul_f32_e32 v41, v41, v41
	v_mul_f32_e32 v41, v41, v41
	v_mul_f32_e32 v41, v41, v41
	v_mul_f32_e32 v41, v41, v41
	global_load_dword v84, v32, s[10:11]
	global_load_dword v85, v32, s[10:11] offset:-1024
	global_load_dword v86, v33, s[10:11]
	global_load_dword v87, v33, s[10:11] offset:-1024
	global_load_dword v88, v34, s[10:11]
	global_load_dword v90, v35, s[12:13]
	global_load_dword v91, v35, s[12:13] offset:4
	s_add_u32 s10, s10, 0x18000
	s_addc_u32 s11, s11, 0
	s_add_u32 s12, s12, 0x4000
	s_addc_u32 s13, s13, 0
	s_waitcnt vmcnt(0)
	v_lshlrev_b32_e32 v108, 16, v84
	v_lshlrev_b32_e32 v109, 16, v85
	v_and_b32_e32 v110, s17, v84
	v_and_b32_e32 v111, s17, v85
	v_lshlrev_b32_e32 v112, 16, v86
	v_lshlrev_b32_e32 v113, 16, v87
	v_and_b32_e32 v114, s17, v86
	v_and_b32_e32 v115, s17, v87
	v_lshlrev_b32_e32 v116, 16, v88
	v_and_b32_e32 v117, s17, v88
	v_rcp_f32_e32 v25, v24
	v_mul_f32_e32 v113, v24, v113
	v_mul_f32_e32 v115, v24, v115
	v_mul_f32_e32 v109, 0x3db504f3, v109
	v_mul_f32_e32 v111, 0x3db504f3, v111
	v_cndmask_b32_e64 v27, 1.0, v25, s[20:21]
	v_mul_f32_e32 v24, v24, v26
	v_mul_f32_e32 v116, v27, v116
	v_mul_f32_e32 v117, v27, v117
	ds_write_b128 v29, v[108:111] offset:256
	ds_write_b128 v29, v[112:115] offset:8448
	ds_write_b64 v30, v[90:91] offset:256
	ds_write_b64 v31, v[116:117] offset:256
	global_load_dword v84, v32, s[10:11]
	global_load_dword v85, v32, s[10:11] offset:-1024
	global_load_dword v86, v33, s[10:11]
	global_load_dword v87, v33, s[10:11] offset:-1024
	global_load_dword v88, v34, s[10:11]
	global_load_dword v90, v35, s[12:13]
	global_load_dword v91, v35, s[12:13] offset:4
	s_add_u32 s10, s10, 0x18000
	s_addc_u32 s11, s11, 0
	s_add_u32 s12, s12, 0x4000
	s_addc_u32 s13, s13, 0
	s_waitcnt vmcnt(0)
	v_lshlrev_b32_e32 v108, 16, v84
	v_lshlrev_b32_e32 v109, 16, v85
	v_and_b32_e32 v110, s17, v84
	v_and_b32_e32 v111, s17, v85
	v_lshlrev_b32_e32 v112, 16, v86
	v_lshlrev_b32_e32 v113, 16, v87
	v_and_b32_e32 v114, s17, v86
	v_and_b32_e32 v115, s17, v87
	v_lshlrev_b32_e32 v116, 16, v88
	v_and_b32_e32 v117, s17, v88
	v_rcp_f32_e32 v25, v24
	v_mul_f32_e32 v113, v24, v113
	v_mul_f32_e32 v115, v24, v115
	v_mul_f32_e32 v109, 0x3db504f3, v109
	v_mul_f32_e32 v111, 0x3db504f3, v111
	v_cndmask_b32_e64 v27, 1.0, v25, s[20:21]
	v_mul_f32_e32 v24, v24, v26
	v_mul_f32_e32 v116, v27, v116
	v_mul_f32_e32 v117, v27, v117
	ds_write_b128 v29, v[108:111] offset:24832
	ds_write_b128 v29, v[112:115] offset:33024
	ds_write_b64 v30, v[90:91] offset:24832
	ds_write_b64 v31, v[116:117] offset:24832
	v_add_u32_e32 v22, 0x8000, v2
	v_add_u32_e32 v23, 0x8000, v3
	v_mov_b32_e32 v6, 0
	v_mov_b32_e32 v7, 0
	v_mov_b32_e32 v8, 0
	v_mov_b32_e32 v9, 0
	v_mov_b32_e32 v10, 0
	v_mov_b32_e32 v11, 0
	v_mov_b32_e32 v12, 0
	v_mov_b32_e32 v13, 0
	v_mov_b32_e32 v14, 0
	v_mov_b32_e32 v15, 0
	v_mov_b32_e32 v16, 0
	v_mov_b32_e32 v17, 0
	v_mov_b32_e32 v18, 0
	v_mov_b32_e32 v19, 0
	v_mov_b32_e32 v20, 0
	v_mov_b32_e32 v21, 0
	s_mov_b32 s16, 0
	s_mov_b32 s2, 0x01010101
	s_mov_b32 s3, 0x01010101
	v_and_b32_e32 v28, 8, v198
	v_lshrrev_b32_e32 v28, 2, v28
	v_add_u32_e32 v28, v46, v28
	s_waitcnt vmcnt(0) lgkmcnt(0)
	s_barrier
	ds_read_b64 v[64:65], v3 offset:20736
	ds_read_b128 v[48:51], v2 offset:8448
	ds_read_b128 v[52:55], v2 offset:8704
	ds_read_b128 v[56:59], v2 offset:8960
	ds_read_b128 v[60:63], v2 offset:9216
.Lret2_loop:
	global_load_dword v84, v32, s[10:11]
	global_load_dword v85, v32, s[10:11] offset:-1024
	global_load_dword v86, v33, s[10:11]
	global_load_dword v87, v33, s[10:11] offset:-1024
	global_load_dword v88, v34, s[10:11]
	global_load_dword v90, v35, s[12:13]
	global_load_dword v91, v35, s[12:13] offset:4
	s_add_u32 s10, s10, 0x18000
	s_addc_u32 s11, s11, 0
	s_add_u32 s12, s12, 0x4000
	s_addc_u32 s13, s13, 0
	s_waitcnt lgkmcnt(3)
	v_pk_fma_f32 v[6:7], v[64:65], v[48:49], v[6:7] op_sel_hi:[1,0,1]
	v_pk_mul_f32 v[38:39], v[6:7], v[48:49] op_sel:[0,1] op_sel_hi:[1,1]
	v_pk_fma_f32 v[8:9], v[64:65], v[50:51], v[8:9] op_sel_hi:[1,0,1]
	v_pk_fma_f32 v[38:39], v[8:9], v[50:51], v[38:39] op_sel:[0,1,0] op_sel_hi:[1,1,1]
	s_waitcnt lgkmcnt(2)
	v_pk_fma_f32 v[10:11], v[64:65], v[52:53], v[10:11] op_sel_hi:[1,0,1]
	v_pk_fma_f32 v[38:39], v[10:11], v[52:53], v[38:39] op_sel:[0,1,0] op_sel_hi:[1,1,1]
	v_pk_fma_f32 v[12:13], v[64:65], v[54:55], v[12:13] op_sel_hi:[1,0,1]
	v_pk_fma_f32 v[38:39], v[12:13], v[54:55], v[38:39] op_sel:[0,1,0] op_sel_hi:[1,1,1]
	s_waitcnt lgkmcnt(1)
	v_pk_fma_f32 v[14:15], v[64:65], v[56:57], v[14:15] op_sel_hi:[1,0,1]
	v_pk_fma_f32 v[38:39], v[14:15], v[56:57], v[38:39] op_sel:[0,1,0] op_sel_hi:[1,1,1]
	v_pk_fma_f32 v[16:17], v[64:65], v[58:59], v[16:17] op_sel_hi:[1,0,1]
	v_pk_fma_f32 v[38:39], v[16:17], v[58:59], v[38:39] op_sel:[0,1,0] op_sel_hi:[1,1,1]
	s_waitcnt lgkmcnt(0)
	v_pk_fma_f32 v[18:19], v[64:65], v[60:61], v[18:19] op_sel_hi:[1,0,1]
	v_pk_fma_f32 v[38:39], v[18:19], v[60:61], v[38:39] op_sel:[0,1,0] op_sel_hi:[1,1,1]
	v_pk_fma_f32 v[20:21], v[64:65], v[62:63], v[20:21] op_sel_hi:[1,0,1]
	v_pk_fma_f32 v[38:39], v[20:21], v[62:63], v[38:39] op_sel:[0,1,0] op_sel_hi:[1,1,1]
	s_add_u32 s14, s14, 0x1000
	s_addc_u32 s15, s15, 0
	v_add_f32_dpp v38, v38, v38 row_ror:8 row_mask:0xf bank_mask:0x3 bound_ctrl:1
	v_add_f32_dpp v38, v39, v39 row_ror:8 row_mask:0xf bank_mask:0xc bound_ctrl:1
	ds_read_b64 v[82:83], v3 offset:20992
	ds_read_b128 v[66:69], v2 offset:9472
	v_add_f32_dpp v38, v38, v38 row_half_mirror row_mask:0xf bank_mask:0xf bound_ctrl:1
	ds_read_b128 v[70:73], v2 offset:9728
	ds_read_b128 v[74:77], v2 offset:9984
	v_add_f32_dpp v38, v38, v38 quad_perm:[1,0,3,2] row_mask:0xf bank_mask:0xf bound_ctrl:1
	ds_read_b128 v[78:81], v2 offset:10240
	s_nop 0
	v_add_f32_dpp v38, v38, v38 quad_perm:[2,3,0,1] row_mask:0xf bank_mask:0xf bound_ctrl:1
	v_cvt_pk_bf16_f32 v47, v38, v38
	s_mov_b64 exec, s[2:3]
	global_store_short v28, v47, s[14:15] offset:-4096
	s_mov_b64 exec, -1
	s_waitcnt lgkmcnt(3)
	v_pk_fma_f32 v[6:7], v[82:83], v[66:67], v[6:7] op_sel_hi:[1,0,1]
	v_pk_mul_f32 v[38:39], v[6:7], v[66:67] op_sel:[0,1] op_sel_hi:[1,1]
	v_pk_fma_f32 v[8:9], v[82:83], v[68:69], v[8:9] op_sel_hi:[1,0,1]
	v_pk_fma_f32 v[38:39], v[8:9], v[68:69], v[38:39] op_sel:[0,1,0] op_sel_hi:[1,1,1]
	s_waitcnt lgkmcnt(2)
	v_pk_fma_f32 v[10:11], v[82:83], v[70:71], v[10:11] op_sel_hi:[1,0,1]
	v_pk_fma_f32 v[38:39], v[10:11], v[70:71], v[38:39] op_sel:[0,1,0] op_sel_hi:[1,1,1]
	v_pk_fma_f32 v[12:13], v[82:83], v[72:73], v[12:13] op_sel_hi:[1,0,1]
	v_pk_fma_f32 v[38:39], v[12:13], v[72:73], v[38:39] op_sel:[0,1,0] op_sel_hi:[1,1,1]
	s_waitcnt lgkmcnt(1)
	v_pk_fma_f32 v[14:15], v[82:83], v[74:75], v[14:15] op_sel_hi:[1,0,1]
	v_pk_fma_f32 v[38:39], v[14:15], v[74:75], v[38:39] op_sel:[0,1,0] op_sel_hi:[1,1,1]
	v_pk_fma_f32 v[16:17], v[82:83], v[76:77], v[16:17] op_sel_hi:[1,0,1]
	v_pk_fma_f32 v[38:39], v[16:17], v[76:77], v[38:39] op_sel:[0,1,0] op_sel_hi:[1,1,1]
	s_waitcnt lgkmcnt(0)
	v_pk_fma_f32 v[18:19], v[82:83], v[78:79], v[18:19] op_sel_hi:[1,0,1]
	v_pk_fma_f32 v[38:39], v[18:19], v[78:79], v[38:39] op_sel:[0,1,0] op_sel_hi:[1,1,1]
	v_pk_fma_f32 v[20:21], v[82:83], v[80:81], v[20:21] op_sel_hi:[1,0,1]
	v_pk_fma_f32 v[38:39], v[20:21], v[80:81], v[38:39] op_sel:[0,1,0] op_sel_hi:[1,1,1]
	s_add_u32 s14, s14, 0x1000
	s_addc_u32 s15, s15, 0
	v_add_f32_dpp v38, v38, v38 row_ror:8 row_mask:0xf bank_mask:0x3 bound_ctrl:1
	v_add_f32_dpp v38, v39, v39 row_ror:8 row_mask:0xf bank_mask:0xc bound_ctrl:1
	ds_read_b64 v[64:65], v3 offset:21248
	ds_read_b128 v[48:51], v2 offset:10496
	v_add_f32_dpp v38, v38, v38 row_half_mirror row_mask:0xf bank_mask:0xf bound_ctrl:1
	ds_read_b128 v[52:55], v2 offset:10752
	ds_read_b128 v[56:59], v2 offset:11008
	v_add_f32_dpp v38, v38, v38 quad_perm:[1,0,3,2] row_mask:0xf bank_mask:0xf bound_ctrl:1
	ds_read_b128 v[60:63], v2 offset:11264
	s_nop 0
	v_add_f32_dpp v38, v38, v38 quad_perm:[2,3,0,1] row_mask:0xf bank_mask:0xf bound_ctrl:1
	v_cvt_pk_bf16_f32 v47, v38, v38
	s_mov_b64 exec, s[2:3]
	global_store_short v28, v47, s[14:15] offset:-4096
	s_mov_b64 exec, -1
	s_waitcnt lgkmcnt(3)
	v_pk_fma_f32 v[6:7], v[64:65], v[48:49], v[6:7] op_sel_hi:[1,0,1]
	v_pk_mul_f32 v[38:39], v[6:7], v[48:49] op_sel:[0,1] op_sel_hi:[1,1]
	v_pk_fma_f32 v[8:9], v[64:65], v[50:51], v[8:9] op_sel_hi:[1,0,1]
	v_pk_fma_f32 v[38:39], v[8:9], v[50:51], v[38:39] op_sel:[0,1,0] op_sel_hi:[1,1,1]
	s_waitcnt lgkmcnt(2)
	v_pk_fma_f32 v[10:11], v[64:65], v[52:53], v[10:11] op_sel_hi:[1,0,1]
	v_pk_fma_f32 v[38:39], v[10:11], v[52:53], v[38:39] op_sel:[0,1,0] op_sel_hi:[1,1,1]
	v_pk_fma_f32 v[12:13], v[64:65], v[54:55], v[12:13] op_sel_hi:[1,0,1]
	v_pk_fma_f32 v[38:39], v[12:13], v[54:55], v[38:39] op_sel:[0,1,0] op_sel_hi:[1,1,1]
	s_waitcnt lgkmcnt(1)
	v_pk_fma_f32 v[14:15], v[64:65], v[56:57], v[14:15] op_sel_hi:[1,0,1]
	v_pk_fma_f32 v[38:39], v[14:15], v[56:57], v[38:39] op_sel:[0,1,0] op_sel_hi:[1,1,1]
	v_pk_fma_f32 v[16:17], v[64:65], v[58:59], v[16:17] op_sel_hi:[1,0,1]
	v_pk_fma_f32 v[38:39], v[16:17], v[58:59], v[38:39] op_sel:[0,1,0] op_sel_hi:[1,1,1]
	s_waitcnt lgkmcnt(0)
	v_pk_fma_f32 v[18:19], v[64:65], v[60:61], v[18:19] op_sel_hi:[1,0,1]
	v_pk_fma_f32 v[38:39], v[18:19], v[60:61], v[38:39] op_sel:[0,1,0] op_sel_hi:[1,1,1]
	v_pk_fma_f32 v[20:21], v[64:65], v[62:63], v[20:21] op_sel_hi:[1,0,1]
	v_pk_fma_f32 v[38:39], v[20:21], v[62:63], v[38:39] op_sel:[0,1,0] op_sel_hi:[1,1,1]
	s_add_u32 s14, s14, 0x1000
	s_addc_u32 s15, s15, 0
	v_add_f32_dpp v38, v38, v38 row_ror:8 row_mask:0xf bank_mask:0x3 bound_ctrl:1
	v_add_f32_dpp v38, v39, v39 row_ror:8 row_mask:0xf bank_mask:0xc bound_ctrl:1
	ds_read_b64 v[82:83], v3 offset:21504
	ds_read_b128 v[66:69], v2 offset:11520
	v_add_f32_dpp v38, v38, v38 row_half_mirror row_mask:0xf bank_mask:0xf bound_ctrl:1
	ds_read_b128 v[70:73], v2 offset:11776
	ds_read_b128 v[74:77], v2 offset:12032
	v_add_f32_dpp v38, v38, v38 quad_perm:[1,0,3,2] row_mask:0xf bank_mask:0xf bound_ctrl:1
	ds_read_b128 v[78:81], v2 offset:12288
	s_nop 0
	v_add_f32_dpp v38, v38, v38 quad_perm:[2,3,0,1] row_mask:0xf bank_mask:0xf bound_ctrl:1
	v_cvt_pk_bf16_f32 v47, v38, v38
	s_mov_b64 exec, s[2:3]
	global_store_short v28, v47, s[14:15] offset:-4096
	s_mov_b64 exec, -1
	s_waitcnt lgkmcnt(3)
	v_pk_fma_f32 v[6:7], v[82:83], v[66:67], v[6:7] op_sel_hi:[1,0,1]
	v_pk_mul_f32 v[38:39], v[6:7], v[66:67] op_sel:[0,1] op_sel_hi:[1,1]
	v_pk_fma_f32 v[8:9], v[82:83], v[68:69], v[8:9] op_sel_hi:[1,0,1]
	v_pk_fma_f32 v[38:39], v[8:9], v[68:69], v[38:39] op_sel:[0,1,0] op_sel_hi:[1,1,1]
	s_waitcnt lgkmcnt(2)
	v_pk_fma_f32 v[10:11], v[82:83], v[70:71], v[10:11] op_sel_hi:[1,0,1]
	v_pk_fma_f32 v[38:39], v[10:11], v[70:71], v[38:39] op_sel:[0,1,0] op_sel_hi:[1,1,1]
	v_pk_fma_f32 v[12:13], v[82:83], v[72:73], v[12:13] op_sel_hi:[1,0,1]
	v_pk_fma_f32 v[38:39], v[12:13], v[72:73], v[38:39] op_sel:[0,1,0] op_sel_hi:[1,1,1]
	s_waitcnt lgkmcnt(1)
	v_pk_fma_f32 v[14:15], v[82:83], v[74:75], v[14:15] op_sel_hi:[1,0,1]
	v_pk_fma_f32 v[38:39], v[14:15], v[74:75], v[38:39] op_sel:[0,1,0] op_sel_hi:[1,1,1]
	v_pk_fma_f32 v[16:17], v[82:83], v[76:77], v[16:17] op_sel_hi:[1,0,1]
	v_pk_fma_f32 v[38:39], v[16:17], v[76:77], v[38:39] op_sel:[0,1,0] op_sel_hi:[1,1,1]
	s_waitcnt lgkmcnt(0)
	v_pk_fma_f32 v[18:19], v[82:83], v[78:79], v[18:19] op_sel_hi:[1,0,1]
	v_pk_fma_f32 v[38:39], v[18:19], v[78:79], v[38:39] op_sel:[0,1,0] op_sel_hi:[1,1,1]
	v_pk_fma_f32 v[20:21], v[82:83], v[80:81], v[20:21] op_sel_hi:[1,0,1]
	v_pk_fma_f32 v[38:39], v[20:21], v[80:81], v[38:39] op_sel:[0,1,0] op_sel_hi:[1,1,1]
	s_add_u32 s14, s14, 0x1000
	s_addc_u32 s15, s15, 0
	v_add_f32_dpp v38, v38, v38 row_ror:8 row_mask:0xf bank_mask:0x3 bound_ctrl:1
	v_add_f32_dpp v38, v39, v39 row_ror:8 row_mask:0xf bank_mask:0xc bound_ctrl:1
	ds_read_b64 v[64:65], v3 offset:21760
	ds_read_b128 v[48:51], v2 offset:12544
	v_add_f32_dpp v38, v38, v38 row_half_mirror row_mask:0xf bank_mask:0xf bound_ctrl:1
	ds_read_b128 v[52:55], v2 offset:12800
	ds_read_b128 v[56:59], v2 offset:13056
	v_add_f32_dpp v38, v38, v38 quad_perm:[1,0,3,2] row_mask:0xf bank_mask:0xf bound_ctrl:1
	ds_read_b128 v[60:63], v2 offset:13312
	s_nop 0
	v_add_f32_dpp v38, v38, v38 quad_perm:[2,3,0,1] row_mask:0xf bank_mask:0xf bound_ctrl:1
	v_cvt_pk_bf16_f32 v47, v38, v38
	s_mov_b64 exec, s[2:3]
	global_store_short v28, v47, s[14:15] offset:-4096
	s_mov_b64 exec, -1
	s_waitcnt lgkmcnt(3)
	v_pk_fma_f32 v[6:7], v[64:65], v[48:49], v[6:7] op_sel_hi:[1,0,1]
	v_pk_mul_f32 v[38:39], v[6:7], v[48:49] op_sel:[0,1] op_sel_hi:[1,1]
	v_pk_fma_f32 v[8:9], v[64:65], v[50:51], v[8:9] op_sel_hi:[1,0,1]
	v_pk_fma_f32 v[38:39], v[8:9], v[50:51], v[38:39] op_sel:[0,1,0] op_sel_hi:[1,1,1]
	s_waitcnt lgkmcnt(2)
	v_pk_fma_f32 v[10:11], v[64:65], v[52:53], v[10:11] op_sel_hi:[1,0,1]
	v_pk_fma_f32 v[38:39], v[10:11], v[52:53], v[38:39] op_sel:[0,1,0] op_sel_hi:[1,1,1]
	v_pk_fma_f32 v[12:13], v[64:65], v[54:55], v[12:13] op_sel_hi:[1,0,1]
	v_pk_fma_f32 v[38:39], v[12:13], v[54:55], v[38:39] op_sel:[0,1,0] op_sel_hi:[1,1,1]
	s_waitcnt lgkmcnt(1)
	v_pk_fma_f32 v[14:15], v[64:65], v[56:57], v[14:15] op_sel_hi:[1,0,1]
	v_pk_fma_f32 v[38:39], v[14:15], v[56:57], v[38:39] op_sel:[0,1,0] op_sel_hi:[1,1,1]
	v_pk_fma_f32 v[16:17], v[64:65], v[58:59], v[16:17] op_sel_hi:[1,0,1]
	v_pk_fma_f32 v[38:39], v[16:17], v[58:59], v[38:39] op_sel:[0,1,0] op_sel_hi:[1,1,1]
	s_waitcnt lgkmcnt(0)
	v_pk_fma_f32 v[18:19], v[64:65], v[60:61], v[18:19] op_sel_hi:[1,0,1]
	v_pk_fma_f32 v[38:39], v[18:19], v[60:61], v[38:39] op_sel:[0,1,0] op_sel_hi:[1,1,1]
	v_pk_fma_f32 v[20:21], v[64:65], v[62:63], v[20:21] op_sel_hi:[1,0,1]
	v_pk_fma_f32 v[38:39], v[20:21], v[62:63], v[38:39] op_sel:[0,1,0] op_sel_hi:[1,1,1]
	s_add_u32 s14, s14, 0x1000
	s_addc_u32 s15, s15, 0
	v_add_f32_dpp v38, v38, v38 row_ror:8 row_mask:0xf bank_mask:0x3 bound_ctrl:1
	v_add_f32_dpp v38, v39, v39 row_ror:8 row_mask:0xf bank_mask:0xc bound_ctrl:1
	ds_read_b64 v[82:83], v3 offset:22016
	ds_read_b128 v[66:69], v2 offset:13568
	v_add_f32_dpp v38, v38, v38 row_half_mirror row_mask:0xf bank_mask:0xf bound_ctrl:1
	ds_read_b128 v[70:73], v2 offset:13824
	ds_read_b128 v[74:77], v2 offset:14080
	v_add_f32_dpp v38, v38, v38 quad_perm:[1,0,3,2] row_mask:0xf bank_mask:0xf bound_ctrl:1
	ds_read_b128 v[78:81], v2 offset:14336
	s_nop 0
	v_add_f32_dpp v38, v38, v38 quad_perm:[2,3,0,1] row_mask:0xf bank_mask:0xf bound_ctrl:1
	v_cvt_pk_bf16_f32 v47, v38, v38
	s_mov_b64 exec, s[2:3]
	global_store_short v28, v47, s[14:15] offset:-4096
	s_mov_b64 exec, -1
	s_waitcnt lgkmcnt(3)
	v_pk_fma_f32 v[6:7], v[82:83], v[66:67], v[6:7] op_sel_hi:[1,0,1]
	v_pk_mul_f32 v[38:39], v[6:7], v[66:67] op_sel:[0,1] op_sel_hi:[1,1]
	v_pk_fma_f32 v[8:9], v[82:83], v[68:69], v[8:9] op_sel_hi:[1,0,1]
	v_pk_fma_f32 v[38:39], v[8:9], v[68:69], v[38:39] op_sel:[0,1,0] op_sel_hi:[1,1,1]
	s_waitcnt lgkmcnt(2)
	v_pk_fma_f32 v[10:11], v[82:83], v[70:71], v[10:11] op_sel_hi:[1,0,1]
	v_pk_fma_f32 v[38:39], v[10:11], v[70:71], v[38:39] op_sel:[0,1,0] op_sel_hi:[1,1,1]
	v_pk_fma_f32 v[12:13], v[82:83], v[72:73], v[12:13] op_sel_hi:[1,0,1]
	v_pk_fma_f32 v[38:39], v[12:13], v[72:73], v[38:39] op_sel:[0,1,0] op_sel_hi:[1,1,1]
	s_waitcnt lgkmcnt(1)
	v_pk_fma_f32 v[14:15], v[82:83], v[74:75], v[14:15] op_sel_hi:[1,0,1]
	v_pk_fma_f32 v[38:39], v[14:15], v[74:75], v[38:39] op_sel:[0,1,0] op_sel_hi:[1,1,1]
	v_pk_fma_f32 v[16:17], v[82:83], v[76:77], v[16:17] op_sel_hi:[1,0,1]
	v_pk_fma_f32 v[38:39], v[16:17], v[76:77], v[38:39] op_sel:[0,1,0] op_sel_hi:[1,1,1]
	s_waitcnt lgkmcnt(0)
	v_pk_fma_f32 v[18:19], v[82:83], v[78:79], v[18:19] op_sel_hi:[1,0,1]
	v_pk_fma_f32 v[38:39], v[18:19], v[78:79], v[38:39] op_sel:[0,1,0] op_sel_hi:[1,1,1]
	v_pk_fma_f32 v[20:21], v[82:83], v[80:81], v[20:21] op_sel_hi:[1,0,1]
	v_pk_fma_f32 v[38:39], v[20:21], v[80:81], v[38:39] op_sel:[0,1,0] op_sel_hi:[1,1,1]
	s_add_u32 s14, s14, 0x1000
	s_addc_u32 s15, s15, 0
	v_add_f32_dpp v38, v38, v38 row_ror:8 row_mask:0xf bank_mask:0x3 bound_ctrl:1
	v_add_f32_dpp v38, v39, v39 row_ror:8 row_mask:0xf bank_mask:0xc bound_ctrl:1
	ds_read_b64 v[64:65], v3 offset:22272
	ds_read_b128 v[48:51], v2 offset:14592
	v_add_f32_dpp v38, v38, v38 row_half_mirror row_mask:0xf bank_mask:0xf bound_ctrl:1
	ds_read_b128 v[52:55], v2 offset:14848
	ds_read_b128 v[56:59], v2 offset:15104
	v_add_f32_dpp v38, v38, v38 quad_perm:[1,0,3,2] row_mask:0xf bank_mask:0xf bound_ctrl:1
	ds_read_b128 v[60:63], v2 offset:15360
	s_nop 0
	v_add_f32_dpp v38, v38, v38 quad_perm:[2,3,0,1] row_mask:0xf bank_mask:0xf bound_ctrl:1
	v_cvt_pk_bf16_f32 v47, v38, v38
	s_mov_b64 exec, s[2:3]
	global_store_short v28, v47, s[14:15] offset:-4096
	s_mov_b64 exec, -1
	s_waitcnt lgkmcnt(3)
	v_pk_fma_f32 v[6:7], v[64:65], v[48:49], v[6:7] op_sel_hi:[1,0,1]
	v_pk_mul_f32 v[38:39], v[6:7], v[48:49] op_sel:[0,1] op_sel_hi:[1,1]
	v_pk_fma_f32 v[8:9], v[64:65], v[50:51], v[8:9] op_sel_hi:[1,0,1]
	v_pk_fma_f32 v[38:39], v[8:9], v[50:51], v[38:39] op_sel:[0,1,0] op_sel_hi:[1,1,1]
	s_waitcnt lgkmcnt(2)
	v_pk_fma_f32 v[10:11], v[64:65], v[52:53], v[10:11] op_sel_hi:[1,0,1]
	v_pk_fma_f32 v[38:39], v[10:11], v[52:53], v[38:39] op_sel:[0,1,0] op_sel_hi:[1,1,1]
	v_pk_fma_f32 v[12:13], v[64:65], v[54:55], v[12:13] op_sel_hi:[1,0,1]
	v_pk_fma_f32 v[38:39], v[12:13], v[54:55], v[38:39] op_sel:[0,1,0] op_sel_hi:[1,1,1]
	s_waitcnt lgkmcnt(1)
	v_pk_fma_f32 v[14:15], v[64:65], v[56:57], v[14:15] op_sel_hi:[1,0,1]
	v_pk_fma_f32 v[38:39], v[14:15], v[56:57], v[38:39] op_sel:[0,1,0] op_sel_hi:[1,1,1]
	v_pk_fma_f32 v[16:17], v[64:65], v[58:59], v[16:17] op_sel_hi:[1,0,1]
	v_pk_fma_f32 v[38:39], v[16:17], v[58:59], v[38:39] op_sel:[0,1,0] op_sel_hi:[1,1,1]
	s_waitcnt lgkmcnt(0)
	v_pk_fma_f32 v[18:19], v[64:65], v[60:61], v[18:19] op_sel_hi:[1,0,1]
	v_pk_fma_f32 v[38:39], v[18:19], v[60:61], v[38:39] op_sel:[0,1,0] op_sel_hi:[1,1,1]
	v_pk_fma_f32 v[20:21], v[64:65], v[62:63], v[20:21] op_sel_hi:[1,0,1]
	v_pk_fma_f32 v[38:39], v[20:21], v[62:63], v[38:39] op_sel:[0,1,0] op_sel_hi:[1,1,1]
	s_add_u32 s14, s14, 0x1000
	s_addc_u32 s15, s15, 0
	v_add_f32_dpp v38, v38, v38 row_ror:8 row_mask:0xf bank_mask:0x3 bound_ctrl:1
	v_add_f32_dpp v38, v39, v39 row_ror:8 row_mask:0xf bank_mask:0xc bound_ctrl:1
	ds_read_b64 v[82:83], v3 offset:22528
	ds_read_b128 v[66:69], v2 offset:15616
	v_add_f32_dpp v38, v38, v38 row_half_mirror row_mask:0xf bank_mask:0xf bound_ctrl:1
	ds_read_b128 v[70:73], v2 offset:15872
	ds_read_b128 v[74:77], v2 offset:16128
	v_add_f32_dpp v38, v38, v38 quad_perm:[1,0,3,2] row_mask:0xf bank_mask:0xf bound_ctrl:1
	ds_read_b128 v[78:81], v2 offset:16384
	s_nop 0
	v_add_f32_dpp v38, v38, v38 quad_perm:[2,3,0,1] row_mask:0xf bank_mask:0xf bound_ctrl:1
	v_cvt_pk_bf16_f32 v47, v38, v38
	s_mov_b64 exec, s[2:3]
	global_store_short v28, v47, s[14:15] offset:-4096
	s_mov_b64 exec, -1
	s_waitcnt lgkmcnt(3)
	v_pk_fma_f32 v[6:7], v[82:83], v[66:67], v[6:7] op_sel_hi:[1,0,1]
	v_pk_mul_f32 v[38:39], v[6:7], v[66:67] op_sel:[0,1] op_sel_hi:[1,1]
	v_pk_fma_f32 v[8:9], v[82:83], v[68:69], v[8:9] op_sel_hi:[1,0,1]
	v_pk_fma_f32 v[38:39], v[8:9], v[68:69], v[38:39] op_sel:[0,1,0] op_sel_hi:[1,1,1]
	s_waitcnt lgkmcnt(2)
	v_pk_fma_f32 v[10:11], v[82:83], v[70:71], v[10:11] op_sel_hi:[1,0,1]
	v_pk_fma_f32 v[38:39], v[10:11], v[70:71], v[38:39] op_sel:[0,1,0] op_sel_hi:[1,1,1]
	v_pk_fma_f32 v[12:13], v[82:83], v[72:73], v[12:13] op_sel_hi:[1,0,1]
	v_pk_fma_f32 v[38:39], v[12:13], v[72:73], v[38:39] op_sel:[0,1,0] op_sel_hi:[1,1,1]
	s_waitcnt lgkmcnt(1)
	v_pk_fma_f32 v[14:15], v[82:83], v[74:75], v[14:15] op_sel_hi:[1,0,1]
	v_pk_fma_f32 v[38:39], v[14:15], v[74:75], v[38:39] op_sel:[0,1,0] op_sel_hi:[1,1,1]
	v_pk_fma_f32 v[16:17], v[82:83], v[76:77], v[16:17] op_sel_hi:[1,0,1]
	v_pk_fma_f32 v[38:39], v[16:17], v[76:77], v[38:39] op_sel:[0,1,0] op_sel_hi:[1,1,1]
	s_waitcnt lgkmcnt(0)
	v_pk_fma_f32 v[18:19], v[82:83], v[78:79], v[18:19] op_sel_hi:[1,0,1]
	v_pk_fma_f32 v[38:39], v[18:19], v[78:79], v[38:39] op_sel:[0,1,0] op_sel_hi:[1,1,1]
	v_pk_fma_f32 v[20:21], v[82:83], v[80:81], v[20:21] op_sel_hi:[1,0,1]
	v_pk_fma_f32 v[38:39], v[20:21], v[80:81], v[38:39] op_sel:[0,1,0] op_sel_hi:[1,1,1]
	s_add_u32 s14, s14, 0x1000
	s_addc_u32 s15, s15, 0
	v_add_f32_dpp v38, v38, v38 row_ror:8 row_mask:0xf bank_mask:0x3 bound_ctrl:1
	v_add_f32_dpp v38, v39, v39 row_ror:8 row_mask:0xf bank_mask:0xc bound_ctrl:1
	ds_read_b64 v[64:65], v3 offset:45312
	ds_read_b128 v[48:51], v2 offset:33024
	v_add_f32_dpp v38, v38, v38 row_half_mirror row_mask:0xf bank_mask:0xf bound_ctrl:1
	ds_read_b128 v[52:55], v2 offset:33280
	ds_read_b128 v[56:59], v2 offset:33536
	v_add_f32_dpp v38, v38, v38 quad_perm:[1,0,3,2] row_mask:0xf bank_mask:0xf bound_ctrl:1
	ds_read_b128 v[60:63], v2 offset:33792
	s_nop 0
	v_add_f32_dpp v38, v38, v38 quad_perm:[2,3,0,1] row_mask:0xf bank_mask:0xf bound_ctrl:1
	v_cvt_pk_bf16_f32 v47, v38, v38
	s_mov_b64 exec, s[2:3]
	global_store_short v28, v47, s[14:15] offset:-4096
	s_mov_b64 exec, -1
	s_waitcnt vmcnt(8)
	v_lshlrev_b32_e32 v108, 16, v84
	v_lshlrev_b32_e32 v109, 16, v85
	v_and_b32_e32 v110, s17, v84
	v_and_b32_e32 v111, s17, v85
	v_lshlrev_b32_e32 v112, 16, v86
	v_lshlrev_b32_e32 v113, 16, v87
	v_and_b32_e32 v114, s17, v86
	v_and_b32_e32 v115, s17, v87
	v_lshlrev_b32_e32 v116, 16, v88
	v_and_b32_e32 v117, s17, v88
	v_rcp_f32_e32 v25, v24
	v_mul_f32_e32 v113, v24, v113
	v_mul_f32_e32 v115, v24, v115
	v_mul_f32_e32 v109, 0x3db504f3, v109
	v_mul_f32_e32 v111, 0x3db504f3, v111
	v_cndmask_b32_e64 v27, 1.0, v25, s[20:21]
	v_mul_f32_e32 v24, v24, v26
	v_mul_f32_e32 v116, v27, v116
	v_mul_f32_e32 v117, v27, v117
	ds_write_b128 v29, v[108:111] offset:49408
	ds_write_b128 v29, v[112:115] offset:57600
	ds_write_b64 v30, v[90:91] offset:49408
	ds_write_b64 v31, v[116:117] offset:49408
	s_add_i32 s16, s16, 8
	s_waitcnt lgkmcnt(0)
	s_barrier
	s_cmpk_lt_u32 s16, 0x800
	s_cbranch_scc0 .Lret2_done
	global_load_dword v84, v32, s[10:11]
	global_load_dword v85, v32, s[10:11] offset:-1024
	global_load_dword v86, v33, s[10:11]
	global_load_dword v87, v33, s[10:11] offset:-1024
	global_load_dword v88, v34, s[10:11]
	global_load_dword v90, v35, s[12:13]
	global_load_dword v91, v35, s[12:13] offset:4
	s_add_u32 s10, s10, 0x18000
	s_addc_u32 s11, s11, 0
	s_add_u32 s12, s12, 0x4000
	s_addc_u32 s13, s13, 0
	s_waitcnt lgkmcnt(3)
	v_pk_fma_f32 v[6:7], v[64:65], v[48:49], v[6:7] op_sel_hi:[1,0,1]
	v_pk_mul_f32 v[38:39], v[6:7], v[48:49] op_sel:[0,1] op_sel_hi:[1,1]
	v_pk_fma_f32 v[8:9], v[64:65], v[50:51], v[8:9] op_sel_hi:[1,0,1]
	v_pk_fma_f32 v[38:39], v[8:9], v[50:51], v[38:39] op_sel:[0,1,0] op_sel_hi:[1,1,1]
	s_waitcnt lgkmcnt(2)
	v_pk_fma_f32 v[10:11], v[64:65], v[52:53], v[10:11] op_sel_hi:[1,0,1]
	v_pk_fma_f32 v[38:39], v[10:11], v[52:53], v[38:39] op_sel:[0,1,0] op_sel_hi:[1,1,1]
	v_pk_fma_f32 v[12:13], v[64:65], v[54:55], v[12:13] op_sel_hi:[1,0,1]
	v_pk_fma_f32 v[38:39], v[12:13], v[54:55], v[38:39] op_sel:[0,1,0] op_sel_hi:[1,1,1]
	s_waitcnt lgkmcnt(1)
	v_pk_fma_f32 v[14:15], v[64:65], v[56:57], v[14:15] op_sel_hi:[1,0,1]
	v_pk_fma_f32 v[38:39], v[14:15], v[56:57], v[38:39] op_sel:[0,1,0] op_sel_hi:[1,1,1]
	v_pk_fma_f32 v[16:17], v[64:65], v[58:59], v[16:17] op_sel_hi:[1,0,1]
	v_pk_fma_f32 v[38:39], v[16:17], v[58:59], v[38:39] op_sel:[0,1,0] op_sel_hi:[1,1,1]
	s_waitcnt lgkmcnt(0)
	v_pk_fma_f32 v[18:19], v[64:65], v[60:61], v[18:19] op_sel_hi:[1,0,1]
	v_pk_fma_f32 v[38:39], v[18:19], v[60:61], v[38:39] op_sel:[0,1,0] op_sel_hi:[1,1,1]
	v_pk_fma_f32 v[20:21], v[64:65], v[62:63], v[20:21] op_sel_hi:[1,0,1]
	v_pk_fma_f32 v[38:39], v[20:21], v[62:63], v[38:39] op_sel:[0,1,0] op_sel_hi:[1,1,1]
	s_add_u32 s14, s14, 0x1000
	s_addc_u32 s15, s15, 0
	v_add_f32_dpp v38, v38, v38 row_ror:8 row_mask:0xf bank_mask:0x3 bound_ctrl:1
	v_add_f32_dpp v38, v39, v39 row_ror:8 row_mask:0xf bank_mask:0xc bound_ctrl:1
	ds_read_b64 v[82:83], v3 offset:45568
	ds_read_b128 v[66:69], v2 offset:34048
	v_add_f32_dpp v38, v38, v38 row_half_mirror row_mask:0xf bank_mask:0xf bound_ctrl:1
	ds_read_b128 v[70:73], v2 offset:34304
	ds_read_b128 v[74:77], v2 offset:34560
	v_add_f32_dpp v38, v38, v38 quad_perm:[1,0,3,2] row_mask:0xf bank_mask:0xf bound_ctrl:1
	ds_read_b128 v[78:81], v2 offset:34816
	s_nop 0
	v_add_f32_dpp v38, v38, v38 quad_perm:[2,3,0,1] row_mask:0xf bank_mask:0xf bound_ctrl:1
	v_cvt_pk_bf16_f32 v47, v38, v38
	s_mov_b64 exec, s[2:3]
	global_store_short v28, v47, s[14:15] offset:-4096
	s_mov_b64 exec, -1
	s_waitcnt lgkmcnt(3)
	v_pk_fma_f32 v[6:7], v[82:83], v[66:67], v[6:7] op_sel_hi:[1,0,1]
	v_pk_mul_f32 v[38:39], v[6:7], v[66:67] op_sel:[0,1] op_sel_hi:[1,1]
	v_pk_fma_f32 v[8:9], v[82:83], v[68:69], v[8:9] op_sel_hi:[1,0,1]
	v_pk_fma_f32 v[38:39], v[8:9], v[68:69], v[38:39] op_sel:[0,1,0] op_sel_hi:[1,1,1]
	s_waitcnt lgkmcnt(2)
	v_pk_fma_f32 v[10:11], v[82:83], v[70:71], v[10:11] op_sel_hi:[1,0,1]
	v_pk_fma_f32 v[38:39], v[10:11], v[70:71], v[38:39] op_sel:[0,1,0] op_sel_hi:[1,1,1]
	v_pk_fma_f32 v[12:13], v[82:83], v[72:73], v[12:13] op_sel_hi:[1,0,1]
	v_pk_fma_f32 v[38:39], v[12:13], v[72:73], v[38:39] op_sel:[0,1,0] op_sel_hi:[1,1,1]
	s_waitcnt lgkmcnt(1)
	v_pk_fma_f32 v[14:15], v[82:83], v[74:75], v[14:15] op_sel_hi:[1,0,1]
	v_pk_fma_f32 v[38:39], v[14:15], v[74:75], v[38:39] op_sel:[0,1,0] op_sel_hi:[1,1,1]
	v_pk_fma_f32 v[16:17], v[82:83], v[76:77], v[16:17] op_sel_hi:[1,0,1]
	v_pk_fma_f32 v[38:39], v[16:17], v[76:77], v[38:39] op_sel:[0,1,0] op_sel_hi:[1,1,1]
	s_waitcnt lgkmcnt(0)
	v_pk_fma_f32 v[18:19], v[82:83], v[78:79], v[18:19] op_sel_hi:[1,0,1]
	v_pk_fma_f32 v[38:39], v[18:19], v[78:79], v[38:39] op_sel:[0,1,0] op_sel_hi:[1,1,1]
	v_pk_fma_f32 v[20:21], v[82:83], v[80:81], v[20:21] op_sel_hi:[1,0,1]
	v_pk_fma_f32 v[38:39], v[20:21], v[80:81], v[38:39] op_sel:[0,1,0] op_sel_hi:[1,1,1]
	s_add_u32 s14, s14, 0x1000
	s_addc_u32 s15, s15, 0
	v_add_f32_dpp v38, v38, v38 row_ror:8 row_mask:0xf bank_mask:0x3 bound_ctrl:1
	v_add_f32_dpp v38, v39, v39 row_ror:8 row_mask:0xf bank_mask:0xc bound_ctrl:1
	ds_read_b64 v[64:65], v3 offset:45824
	ds_read_b128 v[48:51], v2 offset:35072
	v_add_f32_dpp v38, v38, v38 row_half_mirror row_mask:0xf bank_mask:0xf bound_ctrl:1
	ds_read_b128 v[52:55], v2 offset:35328
	ds_read_b128 v[56:59], v2 offset:35584
	v_add_f32_dpp v38, v38, v38 quad_perm:[1,0,3,2] row_mask:0xf bank_mask:0xf bound_ctrl:1
	ds_read_b128 v[60:63], v2 offset:35840
	s_nop 0
	v_add_f32_dpp v38, v38, v38 quad_perm:[2,3,0,1] row_mask:0xf bank_mask:0xf bound_ctrl:1
	v_cvt_pk_bf16_f32 v47, v38, v38
	s_mov_b64 exec, s[2:3]
	global_store_short v28, v47, s[14:15] offset:-4096
	s_mov_b64 exec, -1
	s_waitcnt lgkmcnt(3)
	v_pk_fma_f32 v[6:7], v[64:65], v[48:49], v[6:7] op_sel_hi:[1,0,1]
	v_pk_mul_f32 v[38:39], v[6:7], v[48:49] op_sel:[0,1] op_sel_hi:[1,1]
	v_pk_fma_f32 v[8:9], v[64:65], v[50:51], v[8:9] op_sel_hi:[1,0,1]
	v_pk_fma_f32 v[38:39], v[8:9], v[50:51], v[38:39] op_sel:[0,1,0] op_sel_hi:[1,1,1]
	s_waitcnt lgkmcnt(2)
	v_pk_fma_f32 v[10:11], v[64:65], v[52:53], v[10:11] op_sel_hi:[1,0,1]
	v_pk_fma_f32 v[38:39], v[10:11], v[52:53], v[38:39] op_sel:[0,1,0] op_sel_hi:[1,1,1]
	v_pk_fma_f32 v[12:13], v[64:65], v[54:55], v[12:13] op_sel_hi:[1,0,1]
	v_pk_fma_f32 v[38:39], v[12:13], v[54:55], v[38:39] op_sel:[0,1,0] op_sel_hi:[1,1,1]
	s_waitcnt lgkmcnt(1)
	v_pk_fma_f32 v[14:15], v[64:65], v[56:57], v[14:15] op_sel_hi:[1,0,1]
	v_pk_fma_f32 v[38:39], v[14:15], v[56:57], v[38:39] op_sel:[0,1,0] op_sel_hi:[1,1,1]
	v_pk_fma_f32 v[16:17], v[64:65], v[58:59], v[16:17] op_sel_hi:[1,0,1]
	v_pk_fma_f32 v[38:39], v[16:17], v[58:59], v[38:39] op_sel:[0,1,0] op_sel_hi:[1,1,1]
	s_waitcnt lgkmcnt(0)
	v_pk_fma_f32 v[18:19], v[64:65], v[60:61], v[18:19] op_sel_hi:[1,0,1]
	v_pk_fma_f32 v[38:39], v[18:19], v[60:61], v[38:39] op_sel:[0,1,0] op_sel_hi:[1,1,1]
	v_pk_fma_f32 v[20:21], v[64:65], v[62:63], v[20:21] op_sel_hi:[1,0,1]
	v_pk_fma_f32 v[38:39], v[20:21], v[62:63], v[38:39] op_sel:[0,1,0] op_sel_hi:[1,1,1]
	s_add_u32 s14, s14, 0x1000
	s_addc_u32 s15, s15, 0
	v_add_f32_dpp v38, v38, v38 row_ror:8 row_mask:0xf bank_mask:0x3 bound_ctrl:1
	v_add_f32_dpp v38, v39, v39 row_ror:8 row_mask:0xf bank_mask:0xc bound_ctrl:1
	ds_read_b64 v[82:83], v3 offset:46080
	ds_read_b128 v[66:69], v2 offset:36096
	v_add_f32_dpp v38, v38, v38 row_half_mirror row_mask:0xf bank_mask:0xf bound_ctrl:1
	ds_read_b128 v[70:73], v2 offset:36352
	ds_read_b128 v[74:77], v2 offset:36608
	v_add_f32_dpp v38, v38, v38 quad_perm:[1,0,3,2] row_mask:0xf bank_mask:0xf bound_ctrl:1
	ds_read_b128 v[78:81], v2 offset:36864
	s_nop 0
	v_add_f32_dpp v38, v38, v38 quad_perm:[2,3,0,1] row_mask:0xf bank_mask:0xf bound_ctrl:1
	v_cvt_pk_bf16_f32 v47, v38, v38
	s_mov_b64 exec, s[2:3]
	global_store_short v28, v47, s[14:15] offset:-4096
	s_mov_b64 exec, -1
	s_waitcnt lgkmcnt(3)
	v_pk_fma_f32 v[6:7], v[82:83], v[66:67], v[6:7] op_sel_hi:[1,0,1]
	v_pk_mul_f32 v[38:39], v[6:7], v[66:67] op_sel:[0,1] op_sel_hi:[1,1]
	v_pk_fma_f32 v[8:9], v[82:83], v[68:69], v[8:9] op_sel_hi:[1,0,1]
	v_pk_fma_f32 v[38:39], v[8:9], v[68:69], v[38:39] op_sel:[0,1,0] op_sel_hi:[1,1,1]
	s_waitcnt lgkmcnt(2)
	v_pk_fma_f32 v[10:11], v[82:83], v[70:71], v[10:11] op_sel_hi:[1,0,1]
	v_pk_fma_f32 v[38:39], v[10:11], v[70:71], v[38:39] op_sel:[0,1,0] op_sel_hi:[1,1,1]
	v_pk_fma_f32 v[12:13], v[82:83], v[72:73], v[12:13] op_sel_hi:[1,0,1]
	v_pk_fma_f32 v[38:39], v[12:13], v[72:73], v[38:39] op_sel:[0,1,0] op_sel_hi:[1,1,1]
	s_waitcnt lgkmcnt(1)
	v_pk_fma_f32 v[14:15], v[82:83], v[74:75], v[14:15] op_sel_hi:[1,0,1]
	v_pk_fma_f32 v[38:39], v[14:15], v[74:75], v[38:39] op_sel:[0,1,0] op_sel_hi:[1,1,1]
	v_pk_fma_f32 v[16:17], v[82:83], v[76:77], v[16:17] op_sel_hi:[1,0,1]
	v_pk_fma_f32 v[38:39], v[16:17], v[76:77], v[38:39] op_sel:[0,1,0] op_sel_hi:[1,1,1]
	s_waitcnt lgkmcnt(0)
	v_pk_fma_f32 v[18:19], v[82:83], v[78:79], v[18:19] op_sel_hi:[1,0,1]
	v_pk_fma_f32 v[38:39], v[18:19], v[78:79], v[38:39] op_sel:[0,1,0] op_sel_hi:[1,1,1]
	v_pk_fma_f32 v[20:21], v[82:83], v[80:81], v[20:21] op_sel_hi:[1,0,1]
	v_pk_fma_f32 v[38:39], v[20:21], v[80:81], v[38:39] op_sel:[0,1,0] op_sel_hi:[1,1,1]
	s_add_u32 s14, s14, 0x1000
	s_addc_u32 s15, s15, 0
	v_add_f32_dpp v38, v38, v38 row_ror:8 row_mask:0xf bank_mask:0x3 bound_ctrl:1
	v_add_f32_dpp v38, v39, v39 row_ror:8 row_mask:0xf bank_mask:0xc bound_ctrl:1
	ds_read_b64 v[64:65], v3 offset:46336
	ds_read_b128 v[48:51], v2 offset:37120
	v_add_f32_dpp v38, v38, v38 row_half_mirror row_mask:0xf bank_mask:0xf bound_ctrl:1
	ds_read_b128 v[52:55], v2 offset:37376
	ds_read_b128 v[56:59], v2 offset:37632
	v_add_f32_dpp v38, v38, v38 quad_perm:[1,0,3,2] row_mask:0xf bank_mask:0xf bound_ctrl:1
	ds_read_b128 v[60:63], v2 offset:37888
	s_nop 0
	v_add_f32_dpp v38, v38, v38 quad_perm:[2,3,0,1] row_mask:0xf bank_mask:0xf bound_ctrl:1
	v_cvt_pk_bf16_f32 v47, v38, v38
	s_mov_b64 exec, s[2:3]
	global_store_short v28, v47, s[14:15] offset:-4096
	s_mov_b64 exec, -1
	s_waitcnt lgkmcnt(3)
	v_pk_fma_f32 v[6:7], v[64:65], v[48:49], v[6:7] op_sel_hi:[1,0,1]
	v_pk_mul_f32 v[38:39], v[6:7], v[48:49] op_sel:[0,1] op_sel_hi:[1,1]
	v_pk_fma_f32 v[8:9], v[64:65], v[50:51], v[8:9] op_sel_hi:[1,0,1]
	v_pk_fma_f32 v[38:39], v[8:9], v[50:51], v[38:39] op_sel:[0,1,0] op_sel_hi:[1,1,1]
	s_waitcnt lgkmcnt(2)
	v_pk_fma_f32 v[10:11], v[64:65], v[52:53], v[10:11] op_sel_hi:[1,0,1]
	v_pk_fma_f32 v[38:39], v[10:11], v[52:53], v[38:39] op_sel:[0,1,0] op_sel_hi:[1,1,1]
	v_pk_fma_f32 v[12:13], v[64:65], v[54:55], v[12:13] op_sel_hi:[1,0,1]
	v_pk_fma_f32 v[38:39], v[12:13], v[54:55], v[38:39] op_sel:[0,1,0] op_sel_hi:[1,1,1]
	s_waitcnt lgkmcnt(1)
	v_pk_fma_f32 v[14:15], v[64:65], v[56:57], v[14:15] op_sel_hi:[1,0,1]
	v_pk_fma_f32 v[38:39], v[14:15], v[56:57], v[38:39] op_sel:[0,1,0] op_sel_hi:[1,1,1]
	v_pk_fma_f32 v[16:17], v[64:65], v[58:59], v[16:17] op_sel_hi:[1,0,1]
	v_pk_fma_f32 v[38:39], v[16:17], v[58:59], v[38:39] op_sel:[0,1,0] op_sel_hi:[1,1,1]
	s_waitcnt lgkmcnt(0)
	v_pk_fma_f32 v[18:19], v[64:65], v[60:61], v[18:19] op_sel_hi:[1,0,1]
	v_pk_fma_f32 v[38:39], v[18:19], v[60:61], v[38:39] op_sel:[0,1,0] op_sel_hi:[1,1,1]
	v_pk_fma_f32 v[20:21], v[64:65], v[62:63], v[20:21] op_sel_hi:[1,0,1]
	v_pk_fma_f32 v[38:39], v[20:21], v[62:63], v[38:39] op_sel:[0,1,0] op_sel_hi:[1,1,1]
	s_add_u32 s14, s14, 0x1000
	s_addc_u32 s15, s15, 0
	v_add_f32_dpp v38, v38, v38 row_ror:8 row_mask:0xf bank_mask:0x3 bound_ctrl:1
	v_add_f32_dpp v38, v39, v39 row_ror:8 row_mask:0xf bank_mask:0xc bound_ctrl:1
	ds_read_b64 v[82:83], v3 offset:46592
	ds_read_b128 v[66:69], v2 offset:38144
	v_add_f32_dpp v38, v38, v38 row_half_mirror row_mask:0xf bank_mask:0xf bound_ctrl:1
	ds_read_b128 v[70:73], v2 offset:38400
	ds_read_b128 v[74:77], v2 offset:38656
	v_add_f32_dpp v38, v38, v38 quad_perm:[1,0,3,2] row_mask:0xf bank_mask:0xf bound_ctrl:1
	ds_read_b128 v[78:81], v2 offset:38912
	s_nop 0
	v_add_f32_dpp v38, v38, v38 quad_perm:[2,3,0,1] row_mask:0xf bank_mask:0xf bound_ctrl:1
	v_cvt_pk_bf16_f32 v47, v38, v38
	s_mov_b64 exec, s[2:3]
	global_store_short v28, v47, s[14:15] offset:-4096
	s_mov_b64 exec, -1
	s_waitcnt lgkmcnt(3)
	v_pk_fma_f32 v[6:7], v[82:83], v[66:67], v[6:7] op_sel_hi:[1,0,1]
	v_pk_mul_f32 v[38:39], v[6:7], v[66:67] op_sel:[0,1] op_sel_hi:[1,1]
	v_pk_fma_f32 v[8:9], v[82:83], v[68:69], v[8:9] op_sel_hi:[1,0,1]
	v_pk_fma_f32 v[38:39], v[8:9], v[68:69], v[38:39] op_sel:[0,1,0] op_sel_hi:[1,1,1]
	s_waitcnt lgkmcnt(2)
	v_pk_fma_f32 v[10:11], v[82:83], v[70:71], v[10:11] op_sel_hi:[1,0,1]
	v_pk_fma_f32 v[38:39], v[10:11], v[70:71], v[38:39] op_sel:[0,1,0] op_sel_hi:[1,1,1]
	v_pk_fma_f32 v[12:13], v[82:83], v[72:73], v[12:13] op_sel_hi:[1,0,1]
	v_pk_fma_f32 v[38:39], v[12:13], v[72:73], v[38:39] op_sel:[0,1,0] op_sel_hi:[1,1,1]
	s_waitcnt lgkmcnt(1)
	v_pk_fma_f32 v[14:15], v[82:83], v[74:75], v[14:15] op_sel_hi:[1,0,1]
	v_pk_fma_f32 v[38:39], v[14:15], v[74:75], v[38:39] op_sel:[0,1,0] op_sel_hi:[1,1,1]
	v_pk_fma_f32 v[16:17], v[82:83], v[76:77], v[16:17] op_sel_hi:[1,0,1]
	v_pk_fma_f32 v[38:39], v[16:17], v[76:77], v[38:39] op_sel:[0,1,0] op_sel_hi:[1,1,1]
	s_waitcnt lgkmcnt(0)
	v_pk_fma_f32 v[18:19], v[82:83], v[78:79], v[18:19] op_sel_hi:[1,0,1]
	v_pk_fma_f32 v[38:39], v[18:19], v[78:79], v[38:39] op_sel:[0,1,0] op_sel_hi:[1,1,1]
	v_pk_fma_f32 v[20:21], v[82:83], v[80:81], v[20:21] op_sel_hi:[1,0,1]
	v_pk_fma_f32 v[38:39], v[20:21], v[80:81], v[38:39] op_sel:[0,1,0] op_sel_hi:[1,1,1]
	s_add_u32 s14, s14, 0x1000
	s_addc_u32 s15, s15, 0
	v_add_f32_dpp v38, v38, v38 row_ror:8 row_mask:0xf bank_mask:0x3 bound_ctrl:1
	v_add_f32_dpp v38, v39, v39 row_ror:8 row_mask:0xf bank_mask:0xc bound_ctrl:1
	ds_read_b64 v[64:65], v3 offset:46848
	ds_read_b128 v[48:51], v2 offset:39168
	v_add_f32_dpp v38, v38, v38 row_half_mirror row_mask:0xf bank_mask:0xf bound_ctrl:1
	ds_read_b128 v[52:55], v2 offset:39424
	ds_read_b128 v[56:59], v2 offset:39680
	v_add_f32_dpp v38, v38, v38 quad_perm:[1,0,3,2] row_mask:0xf bank_mask:0xf bound_ctrl:1
	ds_read_b128 v[60:63], v2 offset:39936
	s_nop 0
	v_add_f32_dpp v38, v38, v38 quad_perm:[2,3,0,1] row_mask:0xf bank_mask:0xf bound_ctrl:1
	v_cvt_pk_bf16_f32 v47, v38, v38
	s_mov_b64 exec, s[2:3]
	global_store_short v28, v47, s[14:15] offset:-4096
	s_mov_b64 exec, -1
	s_waitcnt lgkmcnt(3)
	v_pk_fma_f32 v[6:7], v[64:65], v[48:49], v[6:7] op_sel_hi:[1,0,1]
	v_pk_mul_f32 v[38:39], v[6:7], v[48:49] op_sel:[0,1] op_sel_hi:[1,1]
	v_pk_fma_f32 v[8:9], v[64:65], v[50:51], v[8:9] op_sel_hi:[1,0,1]
	v_pk_fma_f32 v[38:39], v[8:9], v[50:51], v[38:39] op_sel:[0,1,0] op_sel_hi:[1,1,1]
	s_waitcnt lgkmcnt(2)
	v_pk_fma_f32 v[10:11], v[64:65], v[52:53], v[10:11] op_sel_hi:[1,0,1]
	v_pk_fma_f32 v[38:39], v[10:11], v[52:53], v[38:39] op_sel:[0,1,0] op_sel_hi:[1,1,1]
	v_pk_fma_f32 v[12:13], v[64:65], v[54:55], v[12:13] op_sel_hi:[1,0,1]
	v_pk_fma_f32 v[38:39], v[12:13], v[54:55], v[38:39] op_sel:[0,1,0] op_sel_hi:[1,1,1]
	s_waitcnt lgkmcnt(1)
	v_pk_fma_f32 v[14:15], v[64:65], v[56:57], v[14:15] op_sel_hi:[1,0,1]
	v_pk_fma_f32 v[38:39], v[14:15], v[56:57], v[38:39] op_sel:[0,1,0] op_sel_hi:[1,1,1]
	v_pk_fma_f32 v[16:17], v[64:65], v[58:59], v[16:17] op_sel_hi:[1,0,1]
	v_pk_fma_f32 v[38:39], v[16:17], v[58:59], v[38:39] op_sel:[0,1,0] op_sel_hi:[1,1,1]
	s_waitcnt lgkmcnt(0)
	v_pk_fma_f32 v[18:19], v[64:65], v[60:61], v[18:19] op_sel_hi:[1,0,1]
	v_pk_fma_f32 v[38:39], v[18:19], v[60:61], v[38:39] op_sel:[0,1,0] op_sel_hi:[1,1,1]
	v_pk_fma_f32 v[20:21], v[64:65], v[62:63], v[20:21] op_sel_hi:[1,0,1]
	v_pk_fma_f32 v[38:39], v[20:21], v[62:63], v[38:39] op_sel:[0,1,0] op_sel_hi:[1,1,1]
	s_add_u32 s14, s14, 0x1000
	s_addc_u32 s15, s15, 0
	v_add_f32_dpp v38, v38, v38 row_ror:8 row_mask:0xf bank_mask:0x3 bound_ctrl:1
	v_add_f32_dpp v38, v39, v39 row_ror:8 row_mask:0xf bank_mask:0xc bound_ctrl:1
	ds_read_b64 v[82:83], v3 offset:47104
	ds_read_b128 v[66:69], v2 offset:40192
	v_add_f32_dpp v38, v38, v38 row_half_mirror row_mask:0xf bank_mask:0xf bound_ctrl:1
	ds_read_b128 v[70:73], v2 offset:40448
	ds_read_b128 v[74:77], v2 offset:40704
	v_add_f32_dpp v38, v38, v38 quad_perm:[1,0,3,2] row_mask:0xf bank_mask:0xf bound_ctrl:1
	ds_read_b128 v[78:81], v2 offset:40960
	s_nop 0
	v_add_f32_dpp v38, v38, v38 quad_perm:[2,3,0,1] row_mask:0xf bank_mask:0xf bound_ctrl:1
	v_cvt_pk_bf16_f32 v47, v38, v38
	s_mov_b64 exec, s[2:3]
	global_store_short v28, v47, s[14:15] offset:-4096
	s_mov_b64 exec, -1
	s_waitcnt lgkmcnt(3)
	v_pk_fma_f32 v[6:7], v[82:83], v[66:67], v[6:7] op_sel_hi:[1,0,1]
	v_pk_mul_f32 v[38:39], v[6:7], v[66:67] op_sel:[0,1] op_sel_hi:[1,1]
	v_pk_fma_f32 v[8:9], v[82:83], v[68:69], v[8:9] op_sel_hi:[1,0,1]
	v_pk_fma_f32 v[38:39], v[8:9], v[68:69], v[38:39] op_sel:[0,1,0] op_sel_hi:[1,1,1]
	s_waitcnt lgkmcnt(2)
	v_pk_fma_f32 v[10:11], v[82:83], v[70:71], v[10:11] op_sel_hi:[1,0,1]
	v_pk_fma_f32 v[38:39], v[10:11], v[70:71], v[38:39] op_sel:[0,1,0] op_sel_hi:[1,1,1]
	v_pk_fma_f32 v[12:13], v[82:83], v[72:73], v[12:13] op_sel_hi:[1,0,1]
	v_pk_fma_f32 v[38:39], v[12:13], v[72:73], v[38:39] op_sel:[0,1,0] op_sel_hi:[1,1,1]
	s_waitcnt lgkmcnt(1)
	v_pk_fma_f32 v[14:15], v[82:83], v[74:75], v[14:15] op_sel_hi:[1,0,1]
	v_pk_fma_f32 v[38:39], v[14:15], v[74:75], v[38:39] op_sel:[0,1,0] op_sel_hi:[1,1,1]
	v_pk_fma_f32 v[16:17], v[82:83], v[76:77], v[16:17] op_sel_hi:[1,0,1]
	v_pk_fma_f32 v[38:39], v[16:17], v[76:77], v[38:39] op_sel:[0,1,0] op_sel_hi:[1,1,1]
	s_waitcnt lgkmcnt(0)
	v_pk_fma_f32 v[18:19], v[82:83], v[78:79], v[18:19] op_sel_hi:[1,0,1]
	v_pk_fma_f32 v[38:39], v[18:19], v[78:79], v[38:39] op_sel:[0,1,0] op_sel_hi:[1,1,1]
	v_pk_fma_f32 v[20:21], v[82:83], v[80:81], v[20:21] op_sel_hi:[1,0,1]
	v_pk_fma_f32 v[38:39], v[20:21], v[80:81], v[38:39] op_sel:[0,1,0] op_sel_hi:[1,1,1]
	s_add_u32 s14, s14, 0x1000
	s_addc_u32 s15, s15, 0
	v_add_f32_dpp v38, v38, v38 row_ror:8 row_mask:0xf bank_mask:0x3 bound_ctrl:1
	v_add_f32_dpp v38, v39, v39 row_ror:8 row_mask:0xf bank_mask:0xc bound_ctrl:1
	ds_read_b64 v[64:65], v23 offset:37120
	ds_read_b128 v[48:51], v2 offset:57600
	v_add_f32_dpp v38, v38, v38 row_half_mirror row_mask:0xf bank_mask:0xf bound_ctrl:1
	ds_read_b128 v[52:55], v2 offset:57856
	ds_read_b128 v[56:59], v2 offset:58112
	v_add_f32_dpp v38, v38, v38 quad_perm:[1,0,3,2] row_mask:0xf bank_mask:0xf bound_ctrl:1
	ds_read_b128 v[60:63], v2 offset:58368
	s_nop 0
	v_add_f32_dpp v38, v38, v38 quad_perm:[2,3,0,1] row_mask:0xf bank_mask:0xf bound_ctrl:1
	v_cvt_pk_bf16_f32 v47, v38, v38
	s_mov_b64 exec, s[2:3]
	global_store_short v28, v47, s[14:15] offset:-4096
	s_mov_b64 exec, -1
	s_waitcnt vmcnt(8)
	v_lshlrev_b32_e32 v108, 16, v84
	v_lshlrev_b32_e32 v109, 16, v85
	v_and_b32_e32 v110, s17, v84
	v_and_b32_e32 v111, s17, v85
	v_lshlrev_b32_e32 v112, 16, v86
	v_lshlrev_b32_e32 v113, 16, v87
	v_and_b32_e32 v114, s17, v86
	v_and_b32_e32 v115, s17, v87
	v_lshlrev_b32_e32 v116, 16, v88
	v_and_b32_e32 v117, s17, v88
	v_rcp_f32_e32 v25, v24
	v_mul_f32_e32 v113, v24, v113
	v_mul_f32_e32 v115, v24, v115
	v_mul_f32_e32 v109, 0x3db504f3, v109
	v_mul_f32_e32 v111, 0x3db504f3, v111
	v_cndmask_b32_e64 v27, 1.0, v25, s[20:21]
	v_mul_f32_e32 v24, v24, v26
	v_mul_f32_e32 v116, v27, v116
	v_mul_f32_e32 v117, v27, v117
	ds_write_b128 v29, v[108:111] offset:256
	ds_write_b128 v29, v[112:115] offset:8448
	ds_write_b64 v30, v[90:91] offset:256
	ds_write_b64 v31, v[116:117] offset:256
	s_add_i32 s16, s16, 8
	s_waitcnt lgkmcnt(0)
	s_barrier
	s_cmpk_lt_u32 s16, 0x800
	s_cbranch_scc0 .Lret2_done
	global_load_dword v84, v32, s[10:11]
	global_load_dword v85, v32, s[10:11] offset:-1024
	global_load_dword v86, v33, s[10:11]
	global_load_dword v87, v33, s[10:11] offset:-1024
	global_load_dword v88, v34, s[10:11]
	global_load_dword v90, v35, s[12:13]
	global_load_dword v91, v35, s[12:13] offset:4
	s_add_u32 s10, s10, 0x18000
	s_addc_u32 s11, s11, 0
	s_add_u32 s12, s12, 0x4000
	s_addc_u32 s13, s13, 0
	s_waitcnt lgkmcnt(3)
	v_pk_fma_f32 v[6:7], v[64:65], v[48:49], v[6:7] op_sel_hi:[1,0,1]
	v_pk_mul_f32 v[38:39], v[6:7], v[48:49] op_sel:[0,1] op_sel_hi:[1,1]
	v_pk_fma_f32 v[8:9], v[64:65], v[50:51], v[8:9] op_sel_hi:[1,0,1]
	v_pk_fma_f32 v[38:39], v[8:9], v[50:51], v[38:39] op_sel:[0,1,0] op_sel_hi:[1,1,1]
	s_waitcnt lgkmcnt(2)
	v_pk_fma_f32 v[10:11], v[64:65], v[52:53], v[10:11] op_sel_hi:[1,0,1]
	v_pk_fma_f32 v[38:39], v[10:11], v[52:53], v[38:39] op_sel:[0,1,0] op_sel_hi:[1,1,1]
	v_pk_fma_f32 v[12:13], v[64:65], v[54:55], v[12:13] op_sel_hi:[1,0,1]
	v_pk_fma_f32 v[38:39], v[12:13], v[54:55], v[38:39] op_sel:[0,1,0] op_sel_hi:[1,1,1]
	s_waitcnt lgkmcnt(1)
	v_pk_fma_f32 v[14:15], v[64:65], v[56:57], v[14:15] op_sel_hi:[1,0,1]
	v_pk_fma_f32 v[38:39], v[14:15], v[56:57], v[38:39] op_sel:[0,1,0] op_sel_hi:[1,1,1]
	v_pk_fma_f32 v[16:17], v[64:65], v[58:59], v[16:17] op_sel_hi:[1,0,1]
	v_pk_fma_f32 v[38:39], v[16:17], v[58:59], v[38:39] op_sel:[0,1,0] op_sel_hi:[1,1,1]
	s_waitcnt lgkmcnt(0)
	v_pk_fma_f32 v[18:19], v[64:65], v[60:61], v[18:19] op_sel_hi:[1,0,1]
	v_pk_fma_f32 v[38:39], v[18:19], v[60:61], v[38:39] op_sel:[0,1,0] op_sel_hi:[1,1,1]
	v_pk_fma_f32 v[20:21], v[64:65], v[62:63], v[20:21] op_sel_hi:[1,0,1]
	v_pk_fma_f32 v[38:39], v[20:21], v[62:63], v[38:39] op_sel:[0,1,0] op_sel_hi:[1,1,1]
	s_add_u32 s14, s14, 0x1000
	s_addc_u32 s15, s15, 0
	v_add_f32_dpp v38, v38, v38 row_ror:8 row_mask:0xf bank_mask:0x3 bound_ctrl:1
	v_add_f32_dpp v38, v39, v39 row_ror:8 row_mask:0xf bank_mask:0xc bound_ctrl:1
	ds_read_b64 v[82:83], v23 offset:37376
	ds_read_b128 v[66:69], v2 offset:58624
	v_add_f32_dpp v38, v38, v38 row_half_mirror row_mask:0xf bank_mask:0xf bound_ctrl:1
	ds_read_b128 v[70:73], v2 offset:58880
	ds_read_b128 v[74:77], v2 offset:59136
	v_add_f32_dpp v38, v38, v38 quad_perm:[1,0,3,2] row_mask:0xf bank_mask:0xf bound_ctrl:1
	ds_read_b128 v[78:81], v2 offset:59392
	s_nop 0
	v_add_f32_dpp v38, v38, v38 quad_perm:[2,3,0,1] row_mask:0xf bank_mask:0xf bound_ctrl:1
	v_cvt_pk_bf16_f32 v47, v38, v38
	s_mov_b64 exec, s[2:3]
	global_store_short v28, v47, s[14:15] offset:-4096
	s_mov_b64 exec, -1
	s_waitcnt lgkmcnt(3)
	v_pk_fma_f32 v[6:7], v[82:83], v[66:67], v[6:7] op_sel_hi:[1,0,1]
	v_pk_mul_f32 v[38:39], v[6:7], v[66:67] op_sel:[0,1] op_sel_hi:[1,1]
	v_pk_fma_f32 v[8:9], v[82:83], v[68:69], v[8:9] op_sel_hi:[1,0,1]
	v_pk_fma_f32 v[38:39], v[8:9], v[68:69], v[38:39] op_sel:[0,1,0] op_sel_hi:[1,1,1]
	s_waitcnt lgkmcnt(2)
	v_pk_fma_f32 v[10:11], v[82:83], v[70:71], v[10:11] op_sel_hi:[1,0,1]
	v_pk_fma_f32 v[38:39], v[10:11], v[70:71], v[38:39] op_sel:[0,1,0] op_sel_hi:[1,1,1]
	v_pk_fma_f32 v[12:13], v[82:83], v[72:73], v[12:13] op_sel_hi:[1,0,1]
	v_pk_fma_f32 v[38:39], v[12:13], v[72:73], v[38:39] op_sel:[0,1,0] op_sel_hi:[1,1,1]
	s_waitcnt lgkmcnt(1)
	v_pk_fma_f32 v[14:15], v[82:83], v[74:75], v[14:15] op_sel_hi:[1,0,1]
	v_pk_fma_f32 v[38:39], v[14:15], v[74:75], v[38:39] op_sel:[0,1,0] op_sel_hi:[1,1,1]
	v_pk_fma_f32 v[16:17], v[82:83], v[76:77], v[16:17] op_sel_hi:[1,0,1]
	v_pk_fma_f32 v[38:39], v[16:17], v[76:77], v[38:39] op_sel:[0,1,0] op_sel_hi:[1,1,1]
	s_waitcnt lgkmcnt(0)
	v_pk_fma_f32 v[18:19], v[82:83], v[78:79], v[18:19] op_sel_hi:[1,0,1]
	v_pk_fma_f32 v[38:39], v[18:19], v[78:79], v[38:39] op_sel:[0,1,0] op_sel_hi:[1,1,1]
	v_pk_fma_f32 v[20:21], v[82:83], v[80:81], v[20:21] op_sel_hi:[1,0,1]
	v_pk_fma_f32 v[38:39], v[20:21], v[80:81], v[38:39] op_sel:[0,1,0] op_sel_hi:[1,1,1]
	s_add_u32 s14, s14, 0x1000
	s_addc_u32 s15, s15, 0
	v_add_f32_dpp v38, v38, v38 row_ror:8 row_mask:0xf bank_mask:0x3 bound_ctrl:1
	v_add_f32_dpp v38, v39, v39 row_ror:8 row_mask:0xf bank_mask:0xc bound_ctrl:1
	ds_read_b64 v[64:65], v23 offset:37632
	ds_read_b128 v[48:51], v2 offset:59648
	v_add_f32_dpp v38, v38, v38 row_half_mirror row_mask:0xf bank_mask:0xf bound_ctrl:1
	ds_read_b128 v[52:55], v2 offset:59904
	ds_read_b128 v[56:59], v2 offset:60160
	v_add_f32_dpp v38, v38, v38 quad_perm:[1,0,3,2] row_mask:0xf bank_mask:0xf bound_ctrl:1
	ds_read_b128 v[60:63], v2 offset:60416
	s_nop 0
	v_add_f32_dpp v38, v38, v38 quad_perm:[2,3,0,1] row_mask:0xf bank_mask:0xf bound_ctrl:1
	v_cvt_pk_bf16_f32 v47, v38, v38
	s_mov_b64 exec, s[2:3]
	global_store_short v28, v47, s[14:15] offset:-4096
	s_mov_b64 exec, -1
	s_waitcnt lgkmcnt(3)
	v_pk_fma_f32 v[6:7], v[64:65], v[48:49], v[6:7] op_sel_hi:[1,0,1]
	v_pk_mul_f32 v[38:39], v[6:7], v[48:49] op_sel:[0,1] op_sel_hi:[1,1]
	v_pk_fma_f32 v[8:9], v[64:65], v[50:51], v[8:9] op_sel_hi:[1,0,1]
	v_pk_fma_f32 v[38:39], v[8:9], v[50:51], v[38:39] op_sel:[0,1,0] op_sel_hi:[1,1,1]
	s_waitcnt lgkmcnt(2)
	v_pk_fma_f32 v[10:11], v[64:65], v[52:53], v[10:11] op_sel_hi:[1,0,1]
	v_pk_fma_f32 v[38:39], v[10:11], v[52:53], v[38:39] op_sel:[0,1,0] op_sel_hi:[1,1,1]
	v_pk_fma_f32 v[12:13], v[64:65], v[54:55], v[12:13] op_sel_hi:[1,0,1]
	v_pk_fma_f32 v[38:39], v[12:13], v[54:55], v[38:39] op_sel:[0,1,0] op_sel_hi:[1,1,1]
	s_waitcnt lgkmcnt(1)
	v_pk_fma_f32 v[14:15], v[64:65], v[56:57], v[14:15] op_sel_hi:[1,0,1]
	v_pk_fma_f32 v[38:39], v[14:15], v[56:57], v[38:39] op_sel:[0,1,0] op_sel_hi:[1,1,1]
	v_pk_fma_f32 v[16:17], v[64:65], v[58:59], v[16:17] op_sel_hi:[1,0,1]
	v_pk_fma_f32 v[38:39], v[16:17], v[58:59], v[38:39] op_sel:[0,1,0] op_sel_hi:[1,1,1]
	s_waitcnt lgkmcnt(0)
	v_pk_fma_f32 v[18:19], v[64:65], v[60:61], v[18:19] op_sel_hi:[1,0,1]
	v_pk_fma_f32 v[38:39], v[18:19], v[60:61], v[38:39] op_sel:[0,1,0] op_sel_hi:[1,1,1]
	v_pk_fma_f32 v[20:21], v[64:65], v[62:63], v[20:21] op_sel_hi:[1,0,1]
	v_pk_fma_f32 v[38:39], v[20:21], v[62:63], v[38:39] op_sel:[0,1,0] op_sel_hi:[1,1,1]
	s_add_u32 s14, s14, 0x1000
	s_addc_u32 s15, s15, 0
	v_add_f32_dpp v38, v38, v38 row_ror:8 row_mask:0xf bank_mask:0x3 bound_ctrl:1
	v_add_f32_dpp v38, v39, v39 row_ror:8 row_mask:0xf bank_mask:0xc bound_ctrl:1
	ds_read_b64 v[82:83], v23 offset:37888
	ds_read_b128 v[66:69], v2 offset:60672
	v_add_f32_dpp v38, v38, v38 row_half_mirror row_mask:0xf bank_mask:0xf bound_ctrl:1
	ds_read_b128 v[70:73], v2 offset:60928
	ds_read_b128 v[74:77], v2 offset:61184
	v_add_f32_dpp v38, v38, v38 quad_perm:[1,0,3,2] row_mask:0xf bank_mask:0xf bound_ctrl:1
	ds_read_b128 v[78:81], v2 offset:61440
	s_nop 0
	v_add_f32_dpp v38, v38, v38 quad_perm:[2,3,0,1] row_mask:0xf bank_mask:0xf bound_ctrl:1
	v_cvt_pk_bf16_f32 v47, v38, v38
	s_mov_b64 exec, s[2:3]
	global_store_short v28, v47, s[14:15] offset:-4096
	s_mov_b64 exec, -1
	s_waitcnt lgkmcnt(3)
	v_pk_fma_f32 v[6:7], v[82:83], v[66:67], v[6:7] op_sel_hi:[1,0,1]
	v_pk_mul_f32 v[38:39], v[6:7], v[66:67] op_sel:[0,1] op_sel_hi:[1,1]
	v_pk_fma_f32 v[8:9], v[82:83], v[68:69], v[8:9] op_sel_hi:[1,0,1]
	v_pk_fma_f32 v[38:39], v[8:9], v[68:69], v[38:39] op_sel:[0,1,0] op_sel_hi:[1,1,1]
	s_waitcnt lgkmcnt(2)
	v_pk_fma_f32 v[10:11], v[82:83], v[70:71], v[10:11] op_sel_hi:[1,0,1]
	v_pk_fma_f32 v[38:39], v[10:11], v[70:71], v[38:39] op_sel:[0,1,0] op_sel_hi:[1,1,1]
	v_pk_fma_f32 v[12:13], v[82:83], v[72:73], v[12:13] op_sel_hi:[1,0,1]
	v_pk_fma_f32 v[38:39], v[12:13], v[72:73], v[38:39] op_sel:[0,1,0] op_sel_hi:[1,1,1]
	s_waitcnt lgkmcnt(1)
	v_pk_fma_f32 v[14:15], v[82:83], v[74:75], v[14:15] op_sel_hi:[1,0,1]
	v_pk_fma_f32 v[38:39], v[14:15], v[74:75], v[38:39] op_sel:[0,1,0] op_sel_hi:[1,1,1]
	v_pk_fma_f32 v[16:17], v[82:83], v[76:77], v[16:17] op_sel_hi:[1,0,1]
	v_pk_fma_f32 v[38:39], v[16:17], v[76:77], v[38:39] op_sel:[0,1,0] op_sel_hi:[1,1,1]
	s_waitcnt lgkmcnt(0)
	v_pk_fma_f32 v[18:19], v[82:83], v[78:79], v[18:19] op_sel_hi:[1,0,1]
	v_pk_fma_f32 v[38:39], v[18:19], v[78:79], v[38:39] op_sel:[0,1,0] op_sel_hi:[1,1,1]
	v_pk_fma_f32 v[20:21], v[82:83], v[80:81], v[20:21] op_sel_hi:[1,0,1]
	v_pk_fma_f32 v[38:39], v[20:21], v[80:81], v[38:39] op_sel:[0,1,0] op_sel_hi:[1,1,1]
	s_add_u32 s14, s14, 0x1000
	s_addc_u32 s15, s15, 0
	v_add_f32_dpp v38, v38, v38 row_ror:8 row_mask:0xf bank_mask:0x3 bound_ctrl:1
	v_add_f32_dpp v38, v39, v39 row_ror:8 row_mask:0xf bank_mask:0xc bound_ctrl:1
	ds_read_b64 v[64:65], v23 offset:38144
	ds_read_b128 v[48:51], v2 offset:61696
	v_add_f32_dpp v38, v38, v38 row_half_mirror row_mask:0xf bank_mask:0xf bound_ctrl:1
	ds_read_b128 v[52:55], v2 offset:61952
	ds_read_b128 v[56:59], v2 offset:62208
	v_add_f32_dpp v38, v38, v38 quad_perm:[1,0,3,2] row_mask:0xf bank_mask:0xf bound_ctrl:1
	ds_read_b128 v[60:63], v2 offset:62464
	s_nop 0
	v_add_f32_dpp v38, v38, v38 quad_perm:[2,3,0,1] row_mask:0xf bank_mask:0xf bound_ctrl:1
	v_cvt_pk_bf16_f32 v47, v38, v38
	s_mov_b64 exec, s[2:3]
	global_store_short v28, v47, s[14:15] offset:-4096
	s_mov_b64 exec, -1
	s_waitcnt lgkmcnt(3)
	v_pk_fma_f32 v[6:7], v[64:65], v[48:49], v[6:7] op_sel_hi:[1,0,1]
	v_pk_mul_f32 v[38:39], v[6:7], v[48:49] op_sel:[0,1] op_sel_hi:[1,1]
	v_pk_fma_f32 v[8:9], v[64:65], v[50:51], v[8:9] op_sel_hi:[1,0,1]
	v_pk_fma_f32 v[38:39], v[8:9], v[50:51], v[38:39] op_sel:[0,1,0] op_sel_hi:[1,1,1]
	s_waitcnt lgkmcnt(2)
	v_pk_fma_f32 v[10:11], v[64:65], v[52:53], v[10:11] op_sel_hi:[1,0,1]
	v_pk_fma_f32 v[38:39], v[10:11], v[52:53], v[38:39] op_sel:[0,1,0] op_sel_hi:[1,1,1]
	v_pk_fma_f32 v[12:13], v[64:65], v[54:55], v[12:13] op_sel_hi:[1,0,1]
	v_pk_fma_f32 v[38:39], v[12:13], v[54:55], v[38:39] op_sel:[0,1,0] op_sel_hi:[1,1,1]
	s_waitcnt lgkmcnt(1)
	v_pk_fma_f32 v[14:15], v[64:65], v[56:57], v[14:15] op_sel_hi:[1,0,1]
	v_pk_fma_f32 v[38:39], v[14:15], v[56:57], v[38:39] op_sel:[0,1,0] op_sel_hi:[1,1,1]
	v_pk_fma_f32 v[16:17], v[64:65], v[58:59], v[16:17] op_sel_hi:[1,0,1]
	v_pk_fma_f32 v[38:39], v[16:17], v[58:59], v[38:39] op_sel:[0,1,0] op_sel_hi:[1,1,1]
	s_waitcnt lgkmcnt(0)
	v_pk_fma_f32 v[18:19], v[64:65], v[60:61], v[18:19] op_sel_hi:[1,0,1]
	v_pk_fma_f32 v[38:39], v[18:19], v[60:61], v[38:39] op_sel:[0,1,0] op_sel_hi:[1,1,1]
	v_pk_fma_f32 v[20:21], v[64:65], v[62:63], v[20:21] op_sel_hi:[1,0,1]
	v_pk_fma_f32 v[38:39], v[20:21], v[62:63], v[38:39] op_sel:[0,1,0] op_sel_hi:[1,1,1]
	s_add_u32 s14, s14, 0x1000
	s_addc_u32 s15, s15, 0
	v_add_f32_dpp v38, v38, v38 row_ror:8 row_mask:0xf bank_mask:0x3 bound_ctrl:1
	v_add_f32_dpp v38, v39, v39 row_ror:8 row_mask:0xf bank_mask:0xc bound_ctrl:1
	ds_read_b64 v[82:83], v23 offset:38400
	ds_read_b128 v[66:69], v2 offset:62720
	v_add_f32_dpp v38, v38, v38 row_half_mirror row_mask:0xf bank_mask:0xf bound_ctrl:1
	ds_read_b128 v[70:73], v2 offset:62976
	ds_read_b128 v[74:77], v2 offset:63232
	v_add_f32_dpp v38, v38, v38 quad_perm:[1,0,3,2] row_mask:0xf bank_mask:0xf bound_ctrl:1
	ds_read_b128 v[78:81], v2 offset:63488
	s_nop 0
	v_add_f32_dpp v38, v38, v38 quad_perm:[2,3,0,1] row_mask:0xf bank_mask:0xf bound_ctrl:1
	v_cvt_pk_bf16_f32 v47, v38, v38
	s_mov_b64 exec, s[2:3]
	global_store_short v28, v47, s[14:15] offset:-4096
	s_mov_b64 exec, -1
	s_waitcnt lgkmcnt(3)
	v_pk_fma_f32 v[6:7], v[82:83], v[66:67], v[6:7] op_sel_hi:[1,0,1]
	v_pk_mul_f32 v[38:39], v[6:7], v[66:67] op_sel:[0,1] op_sel_hi:[1,1]
	v_pk_fma_f32 v[8:9], v[82:83], v[68:69], v[8:9] op_sel_hi:[1,0,1]
	v_pk_fma_f32 v[38:39], v[8:9], v[68:69], v[38:39] op_sel:[0,1,0] op_sel_hi:[1,1,1]
	s_waitcnt lgkmcnt(2)
	v_pk_fma_f32 v[10:11], v[82:83], v[70:71], v[10:11] op_sel_hi:[1,0,1]
	v_pk_fma_f32 v[38:39], v[10:11], v[70:71], v[38:39] op_sel:[0,1,0] op_sel_hi:[1,1,1]
	v_pk_fma_f32 v[12:13], v[82:83], v[72:73], v[12:13] op_sel_hi:[1,0,1]
	v_pk_fma_f32 v[38:39], v[12:13], v[72:73], v[38:39] op_sel:[0,1,0] op_sel_hi:[1,1,1]
	s_waitcnt lgkmcnt(1)
	v_pk_fma_f32 v[14:15], v[82:83], v[74:75], v[14:15] op_sel_hi:[1,0,1]
	v_pk_fma_f32 v[38:39], v[14:15], v[74:75], v[38:39] op_sel:[0,1,0] op_sel_hi:[1,1,1]
	v_pk_fma_f32 v[16:17], v[82:83], v[76:77], v[16:17] op_sel_hi:[1,0,1]
	v_pk_fma_f32 v[38:39], v[16:17], v[76:77], v[38:39] op_sel:[0,1,0] op_sel_hi:[1,1,1]
	s_waitcnt lgkmcnt(0)
	v_pk_fma_f32 v[18:19], v[82:83], v[78:79], v[18:19] op_sel_hi:[1,0,1]
	v_pk_fma_f32 v[38:39], v[18:19], v[78:79], v[38:39] op_sel:[0,1,0] op_sel_hi:[1,1,1]
	v_pk_fma_f32 v[20:21], v[82:83], v[80:81], v[20:21] op_sel_hi:[1,0,1]
	v_pk_fma_f32 v[38:39], v[20:21], v[80:81], v[38:39] op_sel:[0,1,0] op_sel_hi:[1,1,1]
	s_add_u32 s14, s14, 0x1000
	s_addc_u32 s15, s15, 0
	v_add_f32_dpp v38, v38, v38 row_ror:8 row_mask:0xf bank_mask:0x3 bound_ctrl:1
	v_add_f32_dpp v38, v39, v39 row_ror:8 row_mask:0xf bank_mask:0xc bound_ctrl:1
	ds_read_b64 v[64:65], v23 offset:38656
	ds_read_b128 v[48:51], v2 offset:63744
	v_add_f32_dpp v38, v38, v38 row_half_mirror row_mask:0xf bank_mask:0xf bound_ctrl:1
	ds_read_b128 v[52:55], v2 offset:64000
	ds_read_b128 v[56:59], v2 offset:64256
	v_add_f32_dpp v38, v38, v38 quad_perm:[1,0,3,2] row_mask:0xf bank_mask:0xf bound_ctrl:1
	ds_read_b128 v[60:63], v2 offset:64512
	s_nop 0
	v_add_f32_dpp v38, v38, v38 quad_perm:[2,3,0,1] row_mask:0xf bank_mask:0xf bound_ctrl:1
	v_cvt_pk_bf16_f32 v47, v38, v38
	s_mov_b64 exec, s[2:3]
	global_store_short v28, v47, s[14:15] offset:-4096
	s_mov_b64 exec, -1
	s_waitcnt lgkmcnt(3)
	v_pk_fma_f32 v[6:7], v[64:65], v[48:49], v[6:7] op_sel_hi:[1,0,1]
	v_pk_mul_f32 v[38:39], v[6:7], v[48:49] op_sel:[0,1] op_sel_hi:[1,1]
	v_pk_fma_f32 v[8:9], v[64:65], v[50:51], v[8:9] op_sel_hi:[1,0,1]
	v_pk_fma_f32 v[38:39], v[8:9], v[50:51], v[38:39] op_sel:[0,1,0] op_sel_hi:[1,1,1]
	s_waitcnt lgkmcnt(2)
	v_pk_fma_f32 v[10:11], v[64:65], v[52:53], v[10:11] op_sel_hi:[1,0,1]
	v_pk_fma_f32 v[38:39], v[10:11], v[52:53], v[38:39] op_sel:[0,1,0] op_sel_hi:[1,1,1]
	v_pk_fma_f32 v[12:13], v[64:65], v[54:55], v[12:13] op_sel_hi:[1,0,1]
	v_pk_fma_f32 v[38:39], v[12:13], v[54:55], v[38:39] op_sel:[0,1,0] op_sel_hi:[1,1,1]
	s_waitcnt lgkmcnt(1)
	v_pk_fma_f32 v[14:15], v[64:65], v[56:57], v[14:15] op_sel_hi:[1,0,1]
	v_pk_fma_f32 v[38:39], v[14:15], v[56:57], v[38:39] op_sel:[0,1,0] op_sel_hi:[1,1,1]
	v_pk_fma_f32 v[16:17], v[64:65], v[58:59], v[16:17] op_sel_hi:[1,0,1]
	v_pk_fma_f32 v[38:39], v[16:17], v[58:59], v[38:39] op_sel:[0,1,0] op_sel_hi:[1,1,1]
	s_waitcnt lgkmcnt(0)
	v_pk_fma_f32 v[18:19], v[64:65], v[60:61], v[18:19] op_sel_hi:[1,0,1]
	v_pk_fma_f32 v[38:39], v[18:19], v[60:61], v[38:39] op_sel:[0,1,0] op_sel_hi:[1,1,1]
	v_pk_fma_f32 v[20:21], v[64:65], v[62:63], v[20:21] op_sel_hi:[1,0,1]
	v_pk_fma_f32 v[38:39], v[20:21], v[62:63], v[38:39] op_sel:[0,1,0] op_sel_hi:[1,1,1]
	s_add_u32 s14, s14, 0x1000
	s_addc_u32 s15, s15, 0
	v_add_f32_dpp v38, v38, v38 row_ror:8 row_mask:0xf bank_mask:0x3 bound_ctrl:1
	v_add_f32_dpp v38, v39, v39 row_ror:8 row_mask:0xf bank_mask:0xc bound_ctrl:1
	ds_read_b64 v[82:83], v23 offset:38912
	ds_read_b128 v[66:69], v2 offset:64768
	v_add_f32_dpp v38, v38, v38 row_half_mirror row_mask:0xf bank_mask:0xf bound_ctrl:1
	ds_read_b128 v[70:73], v2 offset:65024
	ds_read_b128 v[74:77], v2 offset:65280
	v_add_f32_dpp v38, v38, v38 quad_perm:[1,0,3,2] row_mask:0xf bank_mask:0xf bound_ctrl:1
	ds_read_b128 v[78:81], v22 offset:32768
	s_nop 0
	v_add_f32_dpp v38, v38, v38 quad_perm:[2,3,0,1] row_mask:0xf bank_mask:0xf bound_ctrl:1
	v_cvt_pk_bf16_f32 v47, v38, v38
	s_mov_b64 exec, s[2:3]
	global_store_short v28, v47, s[14:15] offset:-4096
	s_mov_b64 exec, -1
	s_waitcnt lgkmcnt(3)
	v_pk_fma_f32 v[6:7], v[82:83], v[66:67], v[6:7] op_sel_hi:[1,0,1]
	v_pk_mul_f32 v[38:39], v[6:7], v[66:67] op_sel:[0,1] op_sel_hi:[1,1]
	v_pk_fma_f32 v[8:9], v[82:83], v[68:69], v[8:9] op_sel_hi:[1,0,1]
	v_pk_fma_f32 v[38:39], v[8:9], v[68:69], v[38:39] op_sel:[0,1,0] op_sel_hi:[1,1,1]
	s_waitcnt lgkmcnt(2)
	v_pk_fma_f32 v[10:11], v[82:83], v[70:71], v[10:11] op_sel_hi:[1,0,1]
	v_pk_fma_f32 v[38:39], v[10:11], v[70:71], v[38:39] op_sel:[0,1,0] op_sel_hi:[1,1,1]
	v_pk_fma_f32 v[12:13], v[82:83], v[72:73], v[12:13] op_sel_hi:[1,0,1]
	v_pk_fma_f32 v[38:39], v[12:13], v[72:73], v[38:39] op_sel:[0,1,0] op_sel_hi:[1,1,1]
	s_waitcnt lgkmcnt(1)
	v_pk_fma_f32 v[14:15], v[82:83], v[74:75], v[14:15] op_sel_hi:[1,0,1]
	v_pk_fma_f32 v[38:39], v[14:15], v[74:75], v[38:39] op_sel:[0,1,0] op_sel_hi:[1,1,1]
	v_pk_fma_f32 v[16:17], v[82:83], v[76:77], v[16:17] op_sel_hi:[1,0,1]
	v_pk_fma_f32 v[38:39], v[16:17], v[76:77], v[38:39] op_sel:[0,1,0] op_sel_hi:[1,1,1]
	s_waitcnt lgkmcnt(0)
	v_pk_fma_f32 v[18:19], v[82:83], v[78:79], v[18:19] op_sel_hi:[1,0,1]
	v_pk_fma_f32 v[38:39], v[18:19], v[78:79], v[38:39] op_sel:[0,1,0] op_sel_hi:[1,1,1]
	v_pk_fma_f32 v[20:21], v[82:83], v[80:81], v[20:21] op_sel_hi:[1,0,1]
	v_pk_fma_f32 v[38:39], v[20:21], v[80:81], v[38:39] op_sel:[0,1,0] op_sel_hi:[1,1,1]
	s_add_u32 s14, s14, 0x1000
	s_addc_u32 s15, s15, 0
	v_add_f32_dpp v38, v38, v38 row_ror:8 row_mask:0xf bank_mask:0x3 bound_ctrl:1
	v_add_f32_dpp v38, v39, v39 row_ror:8 row_mask:0xf bank_mask:0xc bound_ctrl:1
	ds_read_b64 v[64:65], v3 offset:20736
	ds_read_b128 v[48:51], v2 offset:8448
	v_add_f32_dpp v38, v38, v38 row_half_mirror row_mask:0xf bank_mask:0xf bound_ctrl:1
	ds_read_b128 v[52:55], v2 offset:8704
	ds_read_b128 v[56:59], v2 offset:8960
	v_add_f32_dpp v38, v38, v38 quad_perm:[1,0,3,2] row_mask:0xf bank_mask:0xf bound_ctrl:1
	ds_read_b128 v[60:63], v2 offset:9216
	s_nop 0
	v_add_f32_dpp v38, v38, v38 quad_perm:[2,3,0,1] row_mask:0xf bank_mask:0xf bound_ctrl:1
	v_cvt_pk_bf16_f32 v47, v38, v38
	s_mov_b64 exec, s[2:3]
	global_store_short v28, v47, s[14:15] offset:-4096
	s_mov_b64 exec, -1
	s_waitcnt vmcnt(8)
	v_lshlrev_b32_e32 v108, 16, v84
	v_lshlrev_b32_e32 v109, 16, v85
	v_and_b32_e32 v110, s17, v84
	v_and_b32_e32 v111, s17, v85
	v_lshlrev_b32_e32 v112, 16, v86
	v_lshlrev_b32_e32 v113, 16, v87
	v_and_b32_e32 v114, s17, v86
	v_and_b32_e32 v115, s17, v87
	v_lshlrev_b32_e32 v116, 16, v88
	v_and_b32_e32 v117, s17, v88
	v_rcp_f32_e32 v25, v24
	v_mul_f32_e32 v113, v24, v113
	v_mul_f32_e32 v115, v24, v115
	v_mul_f32_e32 v109, 0x3db504f3, v109
	v_mul_f32_e32 v111, 0x3db504f3, v111
	v_cndmask_b32_e64 v27, 1.0, v25, s[20:21]
	v_mul_f32_e32 v24, v24, v26
	v_mul_f32_e32 v116, v27, v116
	v_mul_f32_e32 v117, v27, v117
	ds_write_b128 v29, v[108:111] offset:24832
	ds_write_b128 v29, v[112:115] offset:33024
	ds_write_b64 v30, v[90:91] offset:24832
	ds_write_b64 v31, v[116:117] offset:24832
	s_add_i32 s16, s16, 8
	s_waitcnt lgkmcnt(0)
	s_barrier
	s_cmpk_lt_u32 s16, 0x800
	s_cbranch_scc1 .Lret2_loop

.Lgla2_gw2:
	s_mov_b32 s20, 0xffff0000
	s_mov_b32 s21, -1
	global_load_dword v110, v32, s[10:11]
	global_load_dword v111, v32, s[10:11] offset:-1024
	global_load_dword v112, v33, s[10:11]
	global_load_dword v113, v33, s[10:11] offset:-1024
	global_load_dword v114, v34, s[10:11]
	global_load_dword v116, v35, s[12:13]
	global_load_dword v117, v35, s[12:13] offset:4
	s_add_u32 s10, s10, 0x18000
	s_addc_u32 s11, s11, 0
	s_add_u32 s12, s12, 0x4000
	s_addc_u32 s13, s13, 0
	s_waitcnt vmcnt(0)
	v_lshlrev_b32_e32 v144, 16, v110
	v_lshlrev_b32_e32 v145, 16, v111
	v_and_b32_e32 v146, s17, v110
	v_and_b32_e32 v147, s17, v111
	v_lshlrev_b32_e32 v148, 16, v112
	v_lshlrev_b32_e32 v149, 16, v113
	v_and_b32_e32 v150, s17, v112
	v_and_b32_e32 v151, s17, v113
	v_lshlrev_b32_e32 v152, 16, v114
	v_and_b32_e32 v153, s17, v114
	v_rcp_f32_e32 v25, v24
	v_mul_f32_e32 v149, v24, v149
	v_mul_f32_e32 v151, v24, v151
	v_mul_f32_e32 v145, 0x3db504f3, v145
	v_mul_f32_e32 v147, 0x3db504f3, v147
	v_cndmask_b32_e64 v27, 1.0, v25, s[20:21]
	v_mul_f32_e32 v24, v24, v26
	v_mul_f32_e32 v152, v27, v152
	v_mul_f32_e32 v153, v27, v153
	ds_write_b128 v29, v[144:147] offset:256
	ds_write_b128 v29, v[148:151] offset:8448
	ds_write_b64 v30, v[116:117] offset:256
	ds_write_b64 v31, v[152:153] offset:256
	global_load_dword v110, v32, s[10:11]
	global_load_dword v111, v32, s[10:11] offset:-1024
	global_load_dword v112, v33, s[10:11]
	global_load_dword v113, v33, s[10:11] offset:-1024
	global_load_dword v114, v34, s[10:11]
	global_load_dword v116, v35, s[12:13]
	global_load_dword v117, v35, s[12:13] offset:4
	s_add_u32 s10, s10, 0x18000
	s_addc_u32 s11, s11, 0
	s_add_u32 s12, s12, 0x4000
	s_addc_u32 s13, s13, 0
	s_waitcnt vmcnt(0)
	v_lshlrev_b32_e32 v144, 16, v110
	v_lshlrev_b32_e32 v145, 16, v111
	v_and_b32_e32 v146, s17, v110
	v_and_b32_e32 v147, s17, v111
	v_lshlrev_b32_e32 v148, 16, v112
	v_lshlrev_b32_e32 v149, 16, v113
	v_and_b32_e32 v150, s17, v112
	v_and_b32_e32 v151, s17, v113
	v_lshlrev_b32_e32 v152, 16, v114
	v_and_b32_e32 v153, s17, v114
	v_rcp_f32_e32 v25, v24
	v_mul_f32_e32 v149, v24, v149
	v_mul_f32_e32 v151, v24, v151
	v_mul_f32_e32 v145, 0x3db504f3, v145
	v_mul_f32_e32 v147, 0x3db504f3, v147
	v_cndmask_b32_e64 v27, 1.0, v25, s[20:21]
	v_mul_f32_e32 v24, v24, v26
	v_mul_f32_e32 v152, v27, v152
	v_mul_f32_e32 v153, v27, v153
	ds_write_b128 v29, v[144:147] offset:24832
	ds_write_b128 v29, v[148:151] offset:33024
	ds_write_b64 v30, v[116:117] offset:24832
	ds_write_b64 v31, v[152:153] offset:24832
	v_add_u32_e32 v22, 0x8000, v2
	v_add_u32_e32 v23, 0x8000, v3
	v_mov_b32_e32 v6, 0
	v_mov_b32_e32 v7, 0
	v_mov_b32_e32 v8, 0
	v_mov_b32_e32 v9, 0
	v_mov_b32_e32 v10, 0
	v_mov_b32_e32 v11, 0
	v_mov_b32_e32 v12, 0
	v_mov_b32_e32 v13, 0
	v_mov_b32_e32 v14, 0
	v_mov_b32_e32 v15, 0
	v_mov_b32_e32 v16, 0
	v_mov_b32_e32 v17, 0
	v_mov_b32_e32 v18, 0
	v_mov_b32_e32 v19, 0
	v_mov_b32_e32 v20, 0
	v_mov_b32_e32 v21, 0
	s_mov_b32 s16, 0
	s_mov_b32 s2, 0x01010101
	s_mov_b32 s3, 0x01010101
	v_and_b32_e32 v28, 8, v198
	v_lshrrev_b32_e32 v28, 2, v28
	v_add_u32_e32 v28, v46, v28
	s_waitcnt vmcnt(0) lgkmcnt(0)
	s_barrier
	ds_read_b64 v[72:73], v3 offset:20736
	ds_read_b128 v[48:51], v2 offset:256
	ds_read_b128 v[64:67], v2 offset:16640
	ds_read_b128 v[52:55], v2 offset:512
	ds_read_b128 v[56:59], v2 offset:768
	ds_read_b128 v[68:71], v2 offset:16896
	ds_read_b128 v[60:63], v2 offset:1024
.Lgla2_loop:
	global_load_dword v110, v32, s[10:11]
	global_load_dword v111, v32, s[10:11] offset:-1024
	global_load_dword v112, v33, s[10:11]
	global_load_dword v113, v33, s[10:11] offset:-1024
	global_load_dword v114, v34, s[10:11]
	global_load_dword v116, v35, s[12:13]
	global_load_dword v117, v35, s[12:13] offset:4
	s_add_u32 s10, s10, 0x18000
	s_addc_u32 s11, s11, 0
	s_add_u32 s12, s12, 0x4000
	s_addc_u32 s13, s13, 0
	s_waitcnt lgkmcnt(4)
	v_pk_mul_f32 v[42:43], v[72:73], v[48:49] op_sel_hi:[1,0]
	v_pk_fma_f32 v[6:7], v[6:7], v[64:65], v[42:43] op_sel:[0,0,0] op_sel_hi:[1,0,1]
	v_pk_mul_f32 v[38:39], v[6:7], v[48:49] op_sel:[0,1] op_sel_hi:[1,1]
	v_pk_mul_f32 v[44:45], v[72:73], v[50:51] op_sel_hi:[1,0]
	v_pk_fma_f32 v[8:9], v[8:9], v[64:65], v[44:45] op_sel:[0,1,0] op_sel_hi:[1,1,1]
	v_pk_fma_f32 v[38:39], v[8:9], v[50:51], v[38:39] op_sel:[0,1,0] op_sel_hi:[1,1,1]
	s_waitcnt lgkmcnt(3)
	v_pk_mul_f32 v[42:43], v[72:73], v[52:53] op_sel_hi:[1,0]
	v_pk_fma_f32 v[10:11], v[10:11], v[66:67], v[42:43] op_sel:[0,0,0] op_sel_hi:[1,0,1]
	v_pk_fma_f32 v[38:39], v[10:11], v[52:53], v[38:39] op_sel:[0,1,0] op_sel_hi:[1,1,1]
	v_pk_mul_f32 v[44:45], v[72:73], v[54:55] op_sel_hi:[1,0]
	v_pk_fma_f32 v[12:13], v[12:13], v[66:67], v[44:45] op_sel:[0,1,0] op_sel_hi:[1,1,1]
	v_pk_fma_f32 v[38:39], v[12:13], v[54:55], v[38:39] op_sel:[0,1,0] op_sel_hi:[1,1,1]
	s_waitcnt lgkmcnt(1)
	v_pk_mul_f32 v[42:43], v[72:73], v[56:57] op_sel_hi:[1,0]
	v_pk_fma_f32 v[14:15], v[14:15], v[68:69], v[42:43] op_sel:[0,0,0] op_sel_hi:[1,0,1]
	v_pk_fma_f32 v[38:39], v[14:15], v[56:57], v[38:39] op_sel:[0,1,0] op_sel_hi:[1,1,1]
	v_pk_mul_f32 v[44:45], v[72:73], v[58:59] op_sel_hi:[1,0]
	v_pk_fma_f32 v[16:17], v[16:17], v[68:69], v[44:45] op_sel:[0,1,0] op_sel_hi:[1,1,1]
	v_pk_fma_f32 v[38:39], v[16:17], v[58:59], v[38:39] op_sel:[0,1,0] op_sel_hi:[1,1,1]
	s_waitcnt lgkmcnt(0)
	v_pk_mul_f32 v[42:43], v[72:73], v[60:61] op_sel_hi:[1,0]
	v_pk_fma_f32 v[18:19], v[18:19], v[70:71], v[42:43] op_sel:[0,0,0] op_sel_hi:[1,0,1]
	v_pk_fma_f32 v[38:39], v[18:19], v[60:61], v[38:39] op_sel:[0,1,0] op_sel_hi:[1,1,1]
	v_pk_mul_f32 v[44:45], v[72:73], v[62:63] op_sel_hi:[1,0]
	v_pk_fma_f32 v[20:21], v[20:21], v[70:71], v[44:45] op_sel:[0,1,0] op_sel_hi:[1,1,1]
	v_pk_fma_f32 v[38:39], v[20:21], v[62:63], v[38:39] op_sel:[0,1,0] op_sel_hi:[1,1,1]
	s_add_u32 s14, s14, 0x1000
	s_addc_u32 s15, s15, 0
	v_add_f32_dpp v38, v38, v38 row_ror:8 row_mask:0xf bank_mask:0x3 bound_ctrl:1
	v_add_f32_dpp v38, v39, v39 row_ror:8 row_mask:0xf bank_mask:0xc bound_ctrl:1
	ds_read_b64 v[104:105], v3 offset:20992
	ds_read_b128 v[80:83], v2 offset:1280
	v_add_f32_dpp v38, v38, v38 row_half_mirror row_mask:0xf bank_mask:0xf bound_ctrl:1
	ds_read_b128 v[96:99], v2 offset:17152
	ds_read_b128 v[84:87], v2 offset:1536
	v_add_f32_dpp v38, v38, v38 quad_perm:[1,0,3,2] row_mask:0xf bank_mask:0xf bound_ctrl:1
	ds_read_b128 v[88:91], v2 offset:1792
	ds_read_b128 v[100:103], v2 offset:17408
	v_add_f32_dpp v38, v38, v38 quad_perm:[2,3,0,1] row_mask:0xf bank_mask:0xf bound_ctrl:1
	ds_read_b128 v[92:95], v2 offset:2048
	v_cvt_pk_bf16_f32 v47, v38, v38
	s_mov_b64 exec, s[2:3]
	global_store_short v28, v47, s[14:15] offset:-4096
	s_mov_b64 exec, -1
	s_waitcnt lgkmcnt(4)
	v_pk_mul_f32 v[42:43], v[104:105], v[80:81] op_sel_hi:[1,0]
	v_pk_fma_f32 v[6:7], v[6:7], v[96:97], v[42:43] op_sel:[0,0,0] op_sel_hi:[1,0,1]
	v_pk_mul_f32 v[38:39], v[6:7], v[80:81] op_sel:[0,1] op_sel_hi:[1,1]
	v_pk_mul_f32 v[44:45], v[104:105], v[82:83] op_sel_hi:[1,0]
	v_pk_fma_f32 v[8:9], v[8:9], v[96:97], v[44:45] op_sel:[0,1,0] op_sel_hi:[1,1,1]
	v_pk_fma_f32 v[38:39], v[8:9], v[82:83], v[38:39] op_sel:[0,1,0] op_sel_hi:[1,1,1]
	s_waitcnt lgkmcnt(3)
	v_pk_mul_f32 v[42:43], v[104:105], v[84:85] op_sel_hi:[1,0]
	v_pk_fma_f32 v[10:11], v[10:11], v[98:99], v[42:43] op_sel:[0,0,0] op_sel_hi:[1,0,1]
	v_pk_fma_f32 v[38:39], v[10:11], v[84:85], v[38:39] op_sel:[0,1,0] op_sel_hi:[1,1,1]
	v_pk_mul_f32 v[44:45], v[104:105], v[86:87] op_sel_hi:[1,0]
	v_pk_fma_f32 v[12:13], v[12:13], v[98:99], v[44:45] op_sel:[0,1,0] op_sel_hi:[1,1,1]
	v_pk_fma_f32 v[38:39], v[12:13], v[86:87], v[38:39] op_sel:[0,1,0] op_sel_hi:[1,1,1]
	s_waitcnt lgkmcnt(1)
	v_pk_mul_f32 v[42:43], v[104:105], v[88:89] op_sel_hi:[1,0]
	v_pk_fma_f32 v[14:15], v[14:15], v[100:101], v[42:43] op_sel:[0,0,0] op_sel_hi:[1,0,1]
	v_pk_fma_f32 v[38:39], v[14:15], v[88:89], v[38:39] op_sel:[0,1,0] op_sel_hi:[1,1,1]
	v_pk_mul_f32 v[44:45], v[104:105], v[90:91] op_sel_hi:[1,0]
	v_pk_fma_f32 v[16:17], v[16:17], v[100:101], v[44:45] op_sel:[0,1,0] op_sel_hi:[1,1,1]
	v_pk_fma_f32 v[38:39], v[16:17], v[90:91], v[38:39] op_sel:[0,1,0] op_sel_hi:[1,1,1]
	s_waitcnt lgkmcnt(0)
	v_pk_mul_f32 v[42:43], v[104:105], v[92:93] op_sel_hi:[1,0]
	v_pk_fma_f32 v[18:19], v[18:19], v[102:103], v[42:43] op_sel:[0,0,0] op_sel_hi:[1,0,1]
	v_pk_fma_f32 v[38:39], v[18:19], v[92:93], v[38:39] op_sel:[0,1,0] op_sel_hi:[1,1,1]
	v_pk_mul_f32 v[44:45], v[104:105], v[94:95] op_sel_hi:[1,0]
	v_pk_fma_f32 v[20:21], v[20:21], v[102:103], v[44:45] op_sel:[0,1,0] op_sel_hi:[1,1,1]
	v_pk_fma_f32 v[38:39], v[20:21], v[94:95], v[38:39] op_sel:[0,1,0] op_sel_hi:[1,1,1]
	s_add_u32 s14, s14, 0x1000
	s_addc_u32 s15, s15, 0
	v_add_f32_dpp v38, v38, v38 row_ror:8 row_mask:0xf bank_mask:0x3 bound_ctrl:1
	v_add_f32_dpp v38, v39, v39 row_ror:8 row_mask:0xf bank_mask:0xc bound_ctrl:1
	ds_read_b64 v[72:73], v3 offset:21248
	ds_read_b128 v[48:51], v2 offset:2304
	v_add_f32_dpp v38, v38, v38 row_half_mirror row_mask:0xf bank_mask:0xf bound_ctrl:1
	ds_read_b128 v[64:67], v2 offset:17664
	ds_read_b128 v[52:55], v2 offset:2560
	v_add_f32_dpp v38, v38, v38 quad_perm:[1,0,3,2] row_mask:0xf bank_mask:0xf bound_ctrl:1
	ds_read_b128 v[56:59], v2 offset:2816
	ds_read_b128 v[68:71], v2 offset:17920
	v_add_f32_dpp v38, v38, v38 quad_perm:[2,3,0,1] row_mask:0xf bank_mask:0xf bound_ctrl:1
	ds_read_b128 v[60:63], v2 offset:3072
	v_cvt_pk_bf16_f32 v47, v38, v38
	s_mov_b64 exec, s[2:3]
	global_store_short v28, v47, s[14:15] offset:-4096
	s_mov_b64 exec, -1
	s_waitcnt lgkmcnt(4)
	v_pk_mul_f32 v[42:43], v[72:73], v[48:49] op_sel_hi:[1,0]
	v_pk_fma_f32 v[6:7], v[6:7], v[64:65], v[42:43] op_sel:[0,0,0] op_sel_hi:[1,0,1]
	v_pk_mul_f32 v[38:39], v[6:7], v[48:49] op_sel:[0,1] op_sel_hi:[1,1]
	v_pk_mul_f32 v[44:45], v[72:73], v[50:51] op_sel_hi:[1,0]
	v_pk_fma_f32 v[8:9], v[8:9], v[64:65], v[44:45] op_sel:[0,1,0] op_sel_hi:[1,1,1]
	v_pk_fma_f32 v[38:39], v[8:9], v[50:51], v[38:39] op_sel:[0,1,0] op_sel_hi:[1,1,1]
	s_waitcnt lgkmcnt(3)
	v_pk_mul_f32 v[42:43], v[72:73], v[52:53] op_sel_hi:[1,0]
	v_pk_fma_f32 v[10:11], v[10:11], v[66:67], v[42:43] op_sel:[0,0,0] op_sel_hi:[1,0,1]
	v_pk_fma_f32 v[38:39], v[10:11], v[52:53], v[38:39] op_sel:[0,1,0] op_sel_hi:[1,1,1]
	v_pk_mul_f32 v[44:45], v[72:73], v[54:55] op_sel_hi:[1,0]
	v_pk_fma_f32 v[12:13], v[12:13], v[66:67], v[44:45] op_sel:[0,1,0] op_sel_hi:[1,1,1]
	v_pk_fma_f32 v[38:39], v[12:13], v[54:55], v[38:39] op_sel:[0,1,0] op_sel_hi:[1,1,1]
	s_waitcnt lgkmcnt(1)
	v_pk_mul_f32 v[42:43], v[72:73], v[56:57] op_sel_hi:[1,0]
	v_pk_fma_f32 v[14:15], v[14:15], v[68:69], v[42:43] op_sel:[0,0,0] op_sel_hi:[1,0,1]
	v_pk_fma_f32 v[38:39], v[14:15], v[56:57], v[38:39] op_sel:[0,1,0] op_sel_hi:[1,1,1]
	v_pk_mul_f32 v[44:45], v[72:73], v[58:59] op_sel_hi:[1,0]
	v_pk_fma_f32 v[16:17], v[16:17], v[68:69], v[44:45] op_sel:[0,1,0] op_sel_hi:[1,1,1]
	v_pk_fma_f32 v[38:39], v[16:17], v[58:59], v[38:39] op_sel:[0,1,0] op_sel_hi:[1,1,1]
	s_waitcnt lgkmcnt(0)
	v_pk_mul_f32 v[42:43], v[72:73], v[60:61] op_sel_hi:[1,0]
	v_pk_fma_f32 v[18:19], v[18:19], v[70:71], v[42:43] op_sel:[0,0,0] op_sel_hi:[1,0,1]
	v_pk_fma_f32 v[38:39], v[18:19], v[60:61], v[38:39] op_sel:[0,1,0] op_sel_hi:[1,1,1]
	v_pk_mul_f32 v[44:45], v[72:73], v[62:63] op_sel_hi:[1,0]
	v_pk_fma_f32 v[20:21], v[20:21], v[70:71], v[44:45] op_sel:[0,1,0] op_sel_hi:[1,1,1]
	v_pk_fma_f32 v[38:39], v[20:21], v[62:63], v[38:39] op_sel:[0,1,0] op_sel_hi:[1,1,1]
	s_add_u32 s14, s14, 0x1000
	s_addc_u32 s15, s15, 0
	v_add_f32_dpp v38, v38, v38 row_ror:8 row_mask:0xf bank_mask:0x3 bound_ctrl:1
	v_add_f32_dpp v38, v39, v39 row_ror:8 row_mask:0xf bank_mask:0xc bound_ctrl:1
	ds_read_b64 v[104:105], v3 offset:21504
	ds_read_b128 v[80:83], v2 offset:3328
	v_add_f32_dpp v38, v38, v38 row_half_mirror row_mask:0xf bank_mask:0xf bound_ctrl:1
	ds_read_b128 v[96:99], v2 offset:18176
	ds_read_b128 v[84:87], v2 offset:3584
	v_add_f32_dpp v38, v38, v38 quad_perm:[1,0,3,2] row_mask:0xf bank_mask:0xf bound_ctrl:1
	ds_read_b128 v[88:91], v2 offset:3840
	ds_read_b128 v[100:103], v2 offset:18432
	v_add_f32_dpp v38, v38, v38 quad_perm:[2,3,0,1] row_mask:0xf bank_mask:0xf bound_ctrl:1
	ds_read_b128 v[92:95], v2 offset:4096
	v_cvt_pk_bf16_f32 v47, v38, v38
	s_mov_b64 exec, s[2:3]
	global_store_short v28, v47, s[14:15] offset:-4096
	s_mov_b64 exec, -1
	s_waitcnt lgkmcnt(4)
	v_pk_mul_f32 v[42:43], v[104:105], v[80:81] op_sel_hi:[1,0]
	v_pk_fma_f32 v[6:7], v[6:7], v[96:97], v[42:43] op_sel:[0,0,0] op_sel_hi:[1,0,1]
	v_pk_mul_f32 v[38:39], v[6:7], v[80:81] op_sel:[0,1] op_sel_hi:[1,1]
	v_pk_mul_f32 v[44:45], v[104:105], v[82:83] op_sel_hi:[1,0]
	v_pk_fma_f32 v[8:9], v[8:9], v[96:97], v[44:45] op_sel:[0,1,0] op_sel_hi:[1,1,1]
	v_pk_fma_f32 v[38:39], v[8:9], v[82:83], v[38:39] op_sel:[0,1,0] op_sel_hi:[1,1,1]
	s_waitcnt lgkmcnt(3)
	v_pk_mul_f32 v[42:43], v[104:105], v[84:85] op_sel_hi:[1,0]
	v_pk_fma_f32 v[10:11], v[10:11], v[98:99], v[42:43] op_sel:[0,0,0] op_sel_hi:[1,0,1]
	v_pk_fma_f32 v[38:39], v[10:11], v[84:85], v[38:39] op_sel:[0,1,0] op_sel_hi:[1,1,1]
	v_pk_mul_f32 v[44:45], v[104:105], v[86:87] op_sel_hi:[1,0]
	v_pk_fma_f32 v[12:13], v[12:13], v[98:99], v[44:45] op_sel:[0,1,0] op_sel_hi:[1,1,1]
	v_pk_fma_f32 v[38:39], v[12:13], v[86:87], v[38:39] op_sel:[0,1,0] op_sel_hi:[1,1,1]
	s_waitcnt lgkmcnt(1)
	v_pk_mul_f32 v[42:43], v[104:105], v[88:89] op_sel_hi:[1,0]
	v_pk_fma_f32 v[14:15], v[14:15], v[100:101], v[42:43] op_sel:[0,0,0] op_sel_hi:[1,0,1]
	v_pk_fma_f32 v[38:39], v[14:15], v[88:89], v[38:39] op_sel:[0,1,0] op_sel_hi:[1,1,1]
	v_pk_mul_f32 v[44:45], v[104:105], v[90:91] op_sel_hi:[1,0]
	v_pk_fma_f32 v[16:17], v[16:17], v[100:101], v[44:45] op_sel:[0,1,0] op_sel_hi:[1,1,1]
	v_pk_fma_f32 v[38:39], v[16:17], v[90:91], v[38:39] op_sel:[0,1,0] op_sel_hi:[1,1,1]
	s_waitcnt lgkmcnt(0)
	v_pk_mul_f32 v[42:43], v[104:105], v[92:93] op_sel_hi:[1,0]
	v_pk_fma_f32 v[18:19], v[18:19], v[102:103], v[42:43] op_sel:[0,0,0] op_sel_hi:[1,0,1]
	v_pk_fma_f32 v[38:39], v[18:19], v[92:93], v[38:39] op_sel:[0,1,0] op_sel_hi:[1,1,1]
	v_pk_mul_f32 v[44:45], v[104:105], v[94:95] op_sel_hi:[1,0]
	v_pk_fma_f32 v[20:21], v[20:21], v[102:103], v[44:45] op_sel:[0,1,0] op_sel_hi:[1,1,1]
	v_pk_fma_f32 v[38:39], v[20:21], v[94:95], v[38:39] op_sel:[0,1,0] op_sel_hi:[1,1,1]
	s_add_u32 s14, s14, 0x1000
	s_addc_u32 s15, s15, 0
	v_add_f32_dpp v38, v38, v38 row_ror:8 row_mask:0xf bank_mask:0x3 bound_ctrl:1
	v_add_f32_dpp v38, v39, v39 row_ror:8 row_mask:0xf bank_mask:0xc bound_ctrl:1
	ds_read_b64 v[72:73], v3 offset:21760
	ds_read_b128 v[48:51], v2 offset:4352
	v_add_f32_dpp v38, v38, v38 row_half_mirror row_mask:0xf bank_mask:0xf bound_ctrl:1
	ds_read_b128 v[64:67], v2 offset:18688
	ds_read_b128 v[52:55], v2 offset:4608
	v_add_f32_dpp v38, v38, v38 quad_perm:[1,0,3,2] row_mask:0xf bank_mask:0xf bound_ctrl:1
	ds_read_b128 v[56:59], v2 offset:4864
	ds_read_b128 v[68:71], v2 offset:18944
	v_add_f32_dpp v38, v38, v38 quad_perm:[2,3,0,1] row_mask:0xf bank_mask:0xf bound_ctrl:1
	ds_read_b128 v[60:63], v2 offset:5120
	v_cvt_pk_bf16_f32 v47, v38, v38
	s_mov_b64 exec, s[2:3]
	global_store_short v28, v47, s[14:15] offset:-4096
	s_mov_b64 exec, -1
	s_waitcnt lgkmcnt(4)
	v_pk_mul_f32 v[42:43], v[72:73], v[48:49] op_sel_hi:[1,0]
	v_pk_fma_f32 v[6:7], v[6:7], v[64:65], v[42:43] op_sel:[0,0,0] op_sel_hi:[1,0,1]
	v_pk_mul_f32 v[38:39], v[6:7], v[48:49] op_sel:[0,1] op_sel_hi:[1,1]
	v_pk_mul_f32 v[44:45], v[72:73], v[50:51] op_sel_hi:[1,0]
	v_pk_fma_f32 v[8:9], v[8:9], v[64:65], v[44:45] op_sel:[0,1,0] op_sel_hi:[1,1,1]
	v_pk_fma_f32 v[38:39], v[8:9], v[50:51], v[38:39] op_sel:[0,1,0] op_sel_hi:[1,1,1]
	s_waitcnt lgkmcnt(3)
	v_pk_mul_f32 v[42:43], v[72:73], v[52:53] op_sel_hi:[1,0]
	v_pk_fma_f32 v[10:11], v[10:11], v[66:67], v[42:43] op_sel:[0,0,0] op_sel_hi:[1,0,1]
	v_pk_fma_f32 v[38:39], v[10:11], v[52:53], v[38:39] op_sel:[0,1,0] op_sel_hi:[1,1,1]
	v_pk_mul_f32 v[44:45], v[72:73], v[54:55] op_sel_hi:[1,0]
	v_pk_fma_f32 v[12:13], v[12:13], v[66:67], v[44:45] op_sel:[0,1,0] op_sel_hi:[1,1,1]
	v_pk_fma_f32 v[38:39], v[12:13], v[54:55], v[38:39] op_sel:[0,1,0] op_sel_hi:[1,1,1]
	s_waitcnt lgkmcnt(1)
	v_pk_mul_f32 v[42:43], v[72:73], v[56:57] op_sel_hi:[1,0]
	v_pk_fma_f32 v[14:15], v[14:15], v[68:69], v[42:43] op_sel:[0,0,0] op_sel_hi:[1,0,1]
	v_pk_fma_f32 v[38:39], v[14:15], v[56:57], v[38:39] op_sel:[0,1,0] op_sel_hi:[1,1,1]
	v_pk_mul_f32 v[44:45], v[72:73], v[58:59] op_sel_hi:[1,0]
	v_pk_fma_f32 v[16:17], v[16:17], v[68:69], v[44:45] op_sel:[0,1,0] op_sel_hi:[1,1,1]
	v_pk_fma_f32 v[38:39], v[16:17], v[58:59], v[38:39] op_sel:[0,1,0] op_sel_hi:[1,1,1]
	s_waitcnt lgkmcnt(0)
	v_pk_mul_f32 v[42:43], v[72:73], v[60:61] op_sel_hi:[1,0]
	v_pk_fma_f32 v[18:19], v[18:19], v[70:71], v[42:43] op_sel:[0,0,0] op_sel_hi:[1,0,1]
	v_pk_fma_f32 v[38:39], v[18:19], v[60:61], v[38:39] op_sel:[0,1,0] op_sel_hi:[1,1,1]
	v_pk_mul_f32 v[44:45], v[72:73], v[62:63] op_sel_hi:[1,0]
	v_pk_fma_f32 v[20:21], v[20:21], v[70:71], v[44:45] op_sel:[0,1,0] op_sel_hi:[1,1,1]
	v_pk_fma_f32 v[38:39], v[20:21], v[62:63], v[38:39] op_sel:[0,1,0] op_sel_hi:[1,1,1]
	s_add_u32 s14, s14, 0x1000
	s_addc_u32 s15, s15, 0
	v_add_f32_dpp v38, v38, v38 row_ror:8 row_mask:0xf bank_mask:0x3 bound_ctrl:1
	v_add_f32_dpp v38, v39, v39 row_ror:8 row_mask:0xf bank_mask:0xc bound_ctrl:1
	ds_read_b64 v[104:105], v3 offset:22016
	ds_read_b128 v[80:83], v2 offset:5376
	v_add_f32_dpp v38, v38, v38 row_half_mirror row_mask:0xf bank_mask:0xf bound_ctrl:1
	ds_read_b128 v[96:99], v2 offset:19200
	ds_read_b128 v[84:87], v2 offset:5632
	v_add_f32_dpp v38, v38, v38 quad_perm:[1,0,3,2] row_mask:0xf bank_mask:0xf bound_ctrl:1
	ds_read_b128 v[88:91], v2 offset:5888
	ds_read_b128 v[100:103], v2 offset:19456
	v_add_f32_dpp v38, v38, v38 quad_perm:[2,3,0,1] row_mask:0xf bank_mask:0xf bound_ctrl:1
	ds_read_b128 v[92:95], v2 offset:6144
	v_cvt_pk_bf16_f32 v47, v38, v38
	s_mov_b64 exec, s[2:3]
	global_store_short v28, v47, s[14:15] offset:-4096
	s_mov_b64 exec, -1
	s_waitcnt lgkmcnt(4)
	v_pk_mul_f32 v[42:43], v[104:105], v[80:81] op_sel_hi:[1,0]
	v_pk_fma_f32 v[6:7], v[6:7], v[96:97], v[42:43] op_sel:[0,0,0] op_sel_hi:[1,0,1]
	v_pk_mul_f32 v[38:39], v[6:7], v[80:81] op_sel:[0,1] op_sel_hi:[1,1]
	v_pk_mul_f32 v[44:45], v[104:105], v[82:83] op_sel_hi:[1,0]
	v_pk_fma_f32 v[8:9], v[8:9], v[96:97], v[44:45] op_sel:[0,1,0] op_sel_hi:[1,1,1]
	v_pk_fma_f32 v[38:39], v[8:9], v[82:83], v[38:39] op_sel:[0,1,0] op_sel_hi:[1,1,1]
	s_waitcnt lgkmcnt(3)
	v_pk_mul_f32 v[42:43], v[104:105], v[84:85] op_sel_hi:[1,0]
	v_pk_fma_f32 v[10:11], v[10:11], v[98:99], v[42:43] op_sel:[0,0,0] op_sel_hi:[1,0,1]
	v_pk_fma_f32 v[38:39], v[10:11], v[84:85], v[38:39] op_sel:[0,1,0] op_sel_hi:[1,1,1]
	v_pk_mul_f32 v[44:45], v[104:105], v[86:87] op_sel_hi:[1,0]
	v_pk_fma_f32 v[12:13], v[12:13], v[98:99], v[44:45] op_sel:[0,1,0] op_sel_hi:[1,1,1]
	v_pk_fma_f32 v[38:39], v[12:13], v[86:87], v[38:39] op_sel:[0,1,0] op_sel_hi:[1,1,1]
	s_waitcnt lgkmcnt(1)
	v_pk_mul_f32 v[42:43], v[104:105], v[88:89] op_sel_hi:[1,0]
	v_pk_fma_f32 v[14:15], v[14:15], v[100:101], v[42:43] op_sel:[0,0,0] op_sel_hi:[1,0,1]
	v_pk_fma_f32 v[38:39], v[14:15], v[88:89], v[38:39] op_sel:[0,1,0] op_sel_hi:[1,1,1]
	v_pk_mul_f32 v[44:45], v[104:105], v[90:91] op_sel_hi:[1,0]
	v_pk_fma_f32 v[16:17], v[16:17], v[100:101], v[44:45] op_sel:[0,1,0] op_sel_hi:[1,1,1]
	v_pk_fma_f32 v[38:39], v[16:17], v[90:91], v[38:39] op_sel:[0,1,0] op_sel_hi:[1,1,1]
	s_waitcnt lgkmcnt(0)
	v_pk_mul_f32 v[42:43], v[104:105], v[92:93] op_sel_hi:[1,0]
	v_pk_fma_f32 v[18:19], v[18:19], v[102:103], v[42:43] op_sel:[0,0,0] op_sel_hi:[1,0,1]
	v_pk_fma_f32 v[38:39], v[18:19], v[92:93], v[38:39] op_sel:[0,1,0] op_sel_hi:[1,1,1]
	v_pk_mul_f32 v[44:45], v[104:105], v[94:95] op_sel_hi:[1,0]
	v_pk_fma_f32 v[20:21], v[20:21], v[102:103], v[44:45] op_sel:[0,1,0] op_sel_hi:[1,1,1]
	v_pk_fma_f32 v[38:39], v[20:21], v[94:95], v[38:39] op_sel:[0,1,0] op_sel_hi:[1,1,1]
	s_add_u32 s14, s14, 0x1000
	s_addc_u32 s15, s15, 0
	v_add_f32_dpp v38, v38, v38 row_ror:8 row_mask:0xf bank_mask:0x3 bound_ctrl:1
	v_add_f32_dpp v38, v39, v39 row_ror:8 row_mask:0xf bank_mask:0xc bound_ctrl:1
	ds_read_b64 v[72:73], v3 offset:22272
	ds_read_b128 v[48:51], v2 offset:6400
	v_add_f32_dpp v38, v38, v38 row_half_mirror row_mask:0xf bank_mask:0xf bound_ctrl:1
	ds_read_b128 v[64:67], v2 offset:19712
	ds_read_b128 v[52:55], v2 offset:6656
	v_add_f32_dpp v38, v38, v38 quad_perm:[1,0,3,2] row_mask:0xf bank_mask:0xf bound_ctrl:1
	ds_read_b128 v[56:59], v2 offset:6912
	ds_read_b128 v[68:71], v2 offset:19968
	v_add_f32_dpp v38, v38, v38 quad_perm:[2,3,0,1] row_mask:0xf bank_mask:0xf bound_ctrl:1
	ds_read_b128 v[60:63], v2 offset:7168
	v_cvt_pk_bf16_f32 v47, v38, v38
	s_mov_b64 exec, s[2:3]
	global_store_short v28, v47, s[14:15] offset:-4096
	s_mov_b64 exec, -1
	s_waitcnt lgkmcnt(4)
	v_pk_mul_f32 v[42:43], v[72:73], v[48:49] op_sel_hi:[1,0]
	v_pk_fma_f32 v[6:7], v[6:7], v[64:65], v[42:43] op_sel:[0,0,0] op_sel_hi:[1,0,1]
	v_pk_mul_f32 v[38:39], v[6:7], v[48:49] op_sel:[0,1] op_sel_hi:[1,1]
	v_pk_mul_f32 v[44:45], v[72:73], v[50:51] op_sel_hi:[1,0]
	v_pk_fma_f32 v[8:9], v[8:9], v[64:65], v[44:45] op_sel:[0,1,0] op_sel_hi:[1,1,1]
	v_pk_fma_f32 v[38:39], v[8:9], v[50:51], v[38:39] op_sel:[0,1,0] op_sel_hi:[1,1,1]
	s_waitcnt lgkmcnt(3)
	v_pk_mul_f32 v[42:43], v[72:73], v[52:53] op_sel_hi:[1,0]
	v_pk_fma_f32 v[10:11], v[10:11], v[66:67], v[42:43] op_sel:[0,0,0] op_sel_hi:[1,0,1]
	v_pk_fma_f32 v[38:39], v[10:11], v[52:53], v[38:39] op_sel:[0,1,0] op_sel_hi:[1,1,1]
	v_pk_mul_f32 v[44:45], v[72:73], v[54:55] op_sel_hi:[1,0]
	v_pk_fma_f32 v[12:13], v[12:13], v[66:67], v[44:45] op_sel:[0,1,0] op_sel_hi:[1,1,1]
	v_pk_fma_f32 v[38:39], v[12:13], v[54:55], v[38:39] op_sel:[0,1,0] op_sel_hi:[1,1,1]
	s_waitcnt lgkmcnt(1)
	v_pk_mul_f32 v[42:43], v[72:73], v[56:57] op_sel_hi:[1,0]
	v_pk_fma_f32 v[14:15], v[14:15], v[68:69], v[42:43] op_sel:[0,0,0] op_sel_hi:[1,0,1]
	v_pk_fma_f32 v[38:39], v[14:15], v[56:57], v[38:39] op_sel:[0,1,0] op_sel_hi:[1,1,1]
	v_pk_mul_f32 v[44:45], v[72:73], v[58:59] op_sel_hi:[1,0]
	v_pk_fma_f32 v[16:17], v[16:17], v[68:69], v[44:45] op_sel:[0,1,0] op_sel_hi:[1,1,1]
	v_pk_fma_f32 v[38:39], v[16:17], v[58:59], v[38:39] op_sel:[0,1,0] op_sel_hi:[1,1,1]
	s_waitcnt lgkmcnt(0)
	v_pk_mul_f32 v[42:43], v[72:73], v[60:61] op_sel_hi:[1,0]
	v_pk_fma_f32 v[18:19], v[18:19], v[70:71], v[42:43] op_sel:[0,0,0] op_sel_hi:[1,0,1]
	v_pk_fma_f32 v[38:39], v[18:19], v[60:61], v[38:39] op_sel:[0,1,0] op_sel_hi:[1,1,1]
	v_pk_mul_f32 v[44:45], v[72:73], v[62:63] op_sel_hi:[1,0]
	v_pk_fma_f32 v[20:21], v[20:21], v[70:71], v[44:45] op_sel:[0,1,0] op_sel_hi:[1,1,1]
	v_pk_fma_f32 v[38:39], v[20:21], v[62:63], v[38:39] op_sel:[0,1,0] op_sel_hi:[1,1,1]
	s_add_u32 s14, s14, 0x1000
	s_addc_u32 s15, s15, 0
	v_add_f32_dpp v38, v38, v38 row_ror:8 row_mask:0xf bank_mask:0x3 bound_ctrl:1
	v_add_f32_dpp v38, v39, v39 row_ror:8 row_mask:0xf bank_mask:0xc bound_ctrl:1
	ds_read_b64 v[104:105], v3 offset:22528
	ds_read_b128 v[80:83], v2 offset:7424
	v_add_f32_dpp v38, v38, v38 row_half_mirror row_mask:0xf bank_mask:0xf bound_ctrl:1
	ds_read_b128 v[96:99], v2 offset:20224
	ds_read_b128 v[84:87], v2 offset:7680
	v_add_f32_dpp v38, v38, v38 quad_perm:[1,0,3,2] row_mask:0xf bank_mask:0xf bound_ctrl:1
	ds_read_b128 v[88:91], v2 offset:7936
	ds_read_b128 v[100:103], v2 offset:20480
	v_add_f32_dpp v38, v38, v38 quad_perm:[2,3,0,1] row_mask:0xf bank_mask:0xf bound_ctrl:1
	ds_read_b128 v[92:95], v2 offset:8192
	v_cvt_pk_bf16_f32 v47, v38, v38
	s_mov_b64 exec, s[2:3]
	global_store_short v28, v47, s[14:15] offset:-4096
	s_mov_b64 exec, -1
	s_waitcnt lgkmcnt(4)
	v_pk_mul_f32 v[42:43], v[104:105], v[80:81] op_sel_hi:[1,0]
	v_pk_fma_f32 v[6:7], v[6:7], v[96:97], v[42:43] op_sel:[0,0,0] op_sel_hi:[1,0,1]
	v_pk_mul_f32 v[38:39], v[6:7], v[80:81] op_sel:[0,1] op_sel_hi:[1,1]
	v_pk_mul_f32 v[44:45], v[104:105], v[82:83] op_sel_hi:[1,0]
	v_pk_fma_f32 v[8:9], v[8:9], v[96:97], v[44:45] op_sel:[0,1,0] op_sel_hi:[1,1,1]
	v_pk_fma_f32 v[38:39], v[8:9], v[82:83], v[38:39] op_sel:[0,1,0] op_sel_hi:[1,1,1]
	s_waitcnt lgkmcnt(3)
	v_pk_mul_f32 v[42:43], v[104:105], v[84:85] op_sel_hi:[1,0]
	v_pk_fma_f32 v[10:11], v[10:11], v[98:99], v[42:43] op_sel:[0,0,0] op_sel_hi:[1,0,1]
	v_pk_fma_f32 v[38:39], v[10:11], v[84:85], v[38:39] op_sel:[0,1,0] op_sel_hi:[1,1,1]
	v_pk_mul_f32 v[44:45], v[104:105], v[86:87] op_sel_hi:[1,0]
	v_pk_fma_f32 v[12:13], v[12:13], v[98:99], v[44:45] op_sel:[0,1,0] op_sel_hi:[1,1,1]
	v_pk_fma_f32 v[38:39], v[12:13], v[86:87], v[38:39] op_sel:[0,1,0] op_sel_hi:[1,1,1]
	s_waitcnt lgkmcnt(1)
	v_pk_mul_f32 v[42:43], v[104:105], v[88:89] op_sel_hi:[1,0]
	v_pk_fma_f32 v[14:15], v[14:15], v[100:101], v[42:43] op_sel:[0,0,0] op_sel_hi:[1,0,1]
	v_pk_fma_f32 v[38:39], v[14:15], v[88:89], v[38:39] op_sel:[0,1,0] op_sel_hi:[1,1,1]
	v_pk_mul_f32 v[44:45], v[104:105], v[90:91] op_sel_hi:[1,0]
	v_pk_fma_f32 v[16:17], v[16:17], v[100:101], v[44:45] op_sel:[0,1,0] op_sel_hi:[1,1,1]
	v_pk_fma_f32 v[38:39], v[16:17], v[90:91], v[38:39] op_sel:[0,1,0] op_sel_hi:[1,1,1]
	s_waitcnt lgkmcnt(0)
	v_pk_mul_f32 v[42:43], v[104:105], v[92:93] op_sel_hi:[1,0]
	v_pk_fma_f32 v[18:19], v[18:19], v[102:103], v[42:43] op_sel:[0,0,0] op_sel_hi:[1,0,1]
	v_pk_fma_f32 v[38:39], v[18:19], v[92:93], v[38:39] op_sel:[0,1,0] op_sel_hi:[1,1,1]
	v_pk_mul_f32 v[44:45], v[104:105], v[94:95] op_sel_hi:[1,0]
	v_pk_fma_f32 v[20:21], v[20:21], v[102:103], v[44:45] op_sel:[0,1,0] op_sel_hi:[1,1,1]
	v_pk_fma_f32 v[38:39], v[20:21], v[94:95], v[38:39] op_sel:[0,1,0] op_sel_hi:[1,1,1]
	s_add_u32 s14, s14, 0x1000
	s_addc_u32 s15, s15, 0
	v_add_f32_dpp v38, v38, v38 row_ror:8 row_mask:0xf bank_mask:0x3 bound_ctrl:1
	v_add_f32_dpp v38, v39, v39 row_ror:8 row_mask:0xf bank_mask:0xc bound_ctrl:1
	ds_read_b64 v[72:73], v3 offset:45312
	ds_read_b128 v[48:51], v2 offset:24832
	v_add_f32_dpp v38, v38, v38 row_half_mirror row_mask:0xf bank_mask:0xf bound_ctrl:1
	ds_read_b128 v[64:67], v2 offset:41216
	ds_read_b128 v[52:55], v2 offset:25088
	v_add_f32_dpp v38, v38, v38 quad_perm:[1,0,3,2] row_mask:0xf bank_mask:0xf bound_ctrl:1
	ds_read_b128 v[56:59], v2 offset:25344
	ds_read_b128 v[68:71], v2 offset:41472
	v_add_f32_dpp v38, v38, v38 quad_perm:[2,3,0,1] row_mask:0xf bank_mask:0xf bound_ctrl:1
	ds_read_b128 v[60:63], v2 offset:25600
	v_cvt_pk_bf16_f32 v47, v38, v38
	s_mov_b64 exec, s[2:3]
	global_store_short v28, v47, s[14:15] offset:-4096
	s_mov_b64 exec, -1
	s_waitcnt vmcnt(8)
	v_lshlrev_b32_e32 v144, 16, v110
	v_lshlrev_b32_e32 v145, 16, v111
	v_and_b32_e32 v146, s17, v110
	v_and_b32_e32 v147, s17, v111
	v_lshlrev_b32_e32 v148, 16, v112
	v_lshlrev_b32_e32 v149, 16, v113
	v_and_b32_e32 v150, s17, v112
	v_and_b32_e32 v151, s17, v113
	v_lshlrev_b32_e32 v152, 16, v114
	v_and_b32_e32 v153, s17, v114
	v_rcp_f32_e32 v25, v24
	v_mul_f32_e32 v149, v24, v149
	v_mul_f32_e32 v151, v24, v151
	v_mul_f32_e32 v145, 0x3db504f3, v145
	v_mul_f32_e32 v147, 0x3db504f3, v147
	v_cndmask_b32_e64 v27, 1.0, v25, s[20:21]
	v_mul_f32_e32 v24, v24, v26
	v_mul_f32_e32 v152, v27, v152
	v_mul_f32_e32 v153, v27, v153
	ds_write_b128 v29, v[144:147] offset:49408
	ds_write_b128 v29, v[148:151] offset:57600
	ds_write_b64 v30, v[116:117] offset:49408
	ds_write_b64 v31, v[152:153] offset:49408
	s_add_i32 s16, s16, 8
	s_waitcnt lgkmcnt(0)
	s_barrier
	s_cmpk_lt_u32 s16, 0x800
	s_cbranch_scc0 .Lgla2_done
	global_load_dword v110, v32, s[10:11]
	global_load_dword v111, v32, s[10:11] offset:-1024
	global_load_dword v112, v33, s[10:11]
	global_load_dword v113, v33, s[10:11] offset:-1024
	global_load_dword v114, v34, s[10:11]
	global_load_dword v116, v35, s[12:13]
	global_load_dword v117, v35, s[12:13] offset:4
	s_add_u32 s10, s10, 0x18000
	s_addc_u32 s11, s11, 0
	s_add_u32 s12, s12, 0x4000
	s_addc_u32 s13, s13, 0
	s_waitcnt lgkmcnt(4)
	v_pk_mul_f32 v[42:43], v[72:73], v[48:49] op_sel_hi:[1,0]
	v_pk_fma_f32 v[6:7], v[6:7], v[64:65], v[42:43] op_sel:[0,0,0] op_sel_hi:[1,0,1]
	v_pk_mul_f32 v[38:39], v[6:7], v[48:49] op_sel:[0,1] op_sel_hi:[1,1]
	v_pk_mul_f32 v[44:45], v[72:73], v[50:51] op_sel_hi:[1,0]
	v_pk_fma_f32 v[8:9], v[8:9], v[64:65], v[44:45] op_sel:[0,1,0] op_sel_hi:[1,1,1]
	v_pk_fma_f32 v[38:39], v[8:9], v[50:51], v[38:39] op_sel:[0,1,0] op_sel_hi:[1,1,1]
	s_waitcnt lgkmcnt(3)
	v_pk_mul_f32 v[42:43], v[72:73], v[52:53] op_sel_hi:[1,0]
	v_pk_fma_f32 v[10:11], v[10:11], v[66:67], v[42:43] op_sel:[0,0,0] op_sel_hi:[1,0,1]
	v_pk_fma_f32 v[38:39], v[10:11], v[52:53], v[38:39] op_sel:[0,1,0] op_sel_hi:[1,1,1]
	v_pk_mul_f32 v[44:45], v[72:73], v[54:55] op_sel_hi:[1,0]
	v_pk_fma_f32 v[12:13], v[12:13], v[66:67], v[44:45] op_sel:[0,1,0] op_sel_hi:[1,1,1]
	v_pk_fma_f32 v[38:39], v[12:13], v[54:55], v[38:39] op_sel:[0,1,0] op_sel_hi:[1,1,1]
	s_waitcnt lgkmcnt(1)
	v_pk_mul_f32 v[42:43], v[72:73], v[56:57] op_sel_hi:[1,0]
	v_pk_fma_f32 v[14:15], v[14:15], v[68:69], v[42:43] op_sel:[0,0,0] op_sel_hi:[1,0,1]
	v_pk_fma_f32 v[38:39], v[14:15], v[56:57], v[38:39] op_sel:[0,1,0] op_sel_hi:[1,1,1]
	v_pk_mul_f32 v[44:45], v[72:73], v[58:59] op_sel_hi:[1,0]
	v_pk_fma_f32 v[16:17], v[16:17], v[68:69], v[44:45] op_sel:[0,1,0] op_sel_hi:[1,1,1]
	v_pk_fma_f32 v[38:39], v[16:17], v[58:59], v[38:39] op_sel:[0,1,0] op_sel_hi:[1,1,1]
	s_waitcnt lgkmcnt(0)
	v_pk_mul_f32 v[42:43], v[72:73], v[60:61] op_sel_hi:[1,0]
	v_pk_fma_f32 v[18:19], v[18:19], v[70:71], v[42:43] op_sel:[0,0,0] op_sel_hi:[1,0,1]
	v_pk_fma_f32 v[38:39], v[18:19], v[60:61], v[38:39] op_sel:[0,1,0] op_sel_hi:[1,1,1]
	v_pk_mul_f32 v[44:45], v[72:73], v[62:63] op_sel_hi:[1,0]
	v_pk_fma_f32 v[20:21], v[20:21], v[70:71], v[44:45] op_sel:[0,1,0] op_sel_hi:[1,1,1]
	v_pk_fma_f32 v[38:39], v[20:21], v[62:63], v[38:39] op_sel:[0,1,0] op_sel_hi:[1,1,1]
	s_add_u32 s14, s14, 0x1000
	s_addc_u32 s15, s15, 0
	v_add_f32_dpp v38, v38, v38 row_ror:8 row_mask:0xf bank_mask:0x3 bound_ctrl:1
	v_add_f32_dpp v38, v39, v39 row_ror:8 row_mask:0xf bank_mask:0xc bound_ctrl:1
	ds_read_b64 v[104:105], v3 offset:45568
	ds_read_b128 v[80:83], v2 offset:25856
	v_add_f32_dpp v38, v38, v38 row_half_mirror row_mask:0xf bank_mask:0xf bound_ctrl:1
	ds_read_b128 v[96:99], v2 offset:41728
	ds_read_b128 v[84:87], v2 offset:26112
	v_add_f32_dpp v38, v38, v38 quad_perm:[1,0,3,2] row_mask:0xf bank_mask:0xf bound_ctrl:1
	ds_read_b128 v[88:91], v2 offset:26368
	ds_read_b128 v[100:103], v2 offset:41984
	v_add_f32_dpp v38, v38, v38 quad_perm:[2,3,0,1] row_mask:0xf bank_mask:0xf bound_ctrl:1
	ds_read_b128 v[92:95], v2 offset:26624
	v_cvt_pk_bf16_f32 v47, v38, v38
	s_mov_b64 exec, s[2:3]
	global_store_short v28, v47, s[14:15] offset:-4096
	s_mov_b64 exec, -1
	s_waitcnt lgkmcnt(4)
	v_pk_mul_f32 v[42:43], v[104:105], v[80:81] op_sel_hi:[1,0]
	v_pk_fma_f32 v[6:7], v[6:7], v[96:97], v[42:43] op_sel:[0,0,0] op_sel_hi:[1,0,1]
	v_pk_mul_f32 v[38:39], v[6:7], v[80:81] op_sel:[0,1] op_sel_hi:[1,1]
	v_pk_mul_f32 v[44:45], v[104:105], v[82:83] op_sel_hi:[1,0]
	v_pk_fma_f32 v[8:9], v[8:9], v[96:97], v[44:45] op_sel:[0,1,0] op_sel_hi:[1,1,1]
	v_pk_fma_f32 v[38:39], v[8:9], v[82:83], v[38:39] op_sel:[0,1,0] op_sel_hi:[1,1,1]
	s_waitcnt lgkmcnt(3)
	v_pk_mul_f32 v[42:43], v[104:105], v[84:85] op_sel_hi:[1,0]
	v_pk_fma_f32 v[10:11], v[10:11], v[98:99], v[42:43] op_sel:[0,0,0] op_sel_hi:[1,0,1]
	v_pk_fma_f32 v[38:39], v[10:11], v[84:85], v[38:39] op_sel:[0,1,0] op_sel_hi:[1,1,1]
	v_pk_mul_f32 v[44:45], v[104:105], v[86:87] op_sel_hi:[1,0]
	v_pk_fma_f32 v[12:13], v[12:13], v[98:99], v[44:45] op_sel:[0,1,0] op_sel_hi:[1,1,1]
	v_pk_fma_f32 v[38:39], v[12:13], v[86:87], v[38:39] op_sel:[0,1,0] op_sel_hi:[1,1,1]
	s_waitcnt lgkmcnt(1)
	v_pk_mul_f32 v[42:43], v[104:105], v[88:89] op_sel_hi:[1,0]
	v_pk_fma_f32 v[14:15], v[14:15], v[100:101], v[42:43] op_sel:[0,0,0] op_sel_hi:[1,0,1]
	v_pk_fma_f32 v[38:39], v[14:15], v[88:89], v[38:39] op_sel:[0,1,0] op_sel_hi:[1,1,1]
	v_pk_mul_f32 v[44:45], v[104:105], v[90:91] op_sel_hi:[1,0]
	v_pk_fma_f32 v[16:17], v[16:17], v[100:101], v[44:45] op_sel:[0,1,0] op_sel_hi:[1,1,1]
	v_pk_fma_f32 v[38:39], v[16:17], v[90:91], v[38:39] op_sel:[0,1,0] op_sel_hi:[1,1,1]
	s_waitcnt lgkmcnt(0)
	v_pk_mul_f32 v[42:43], v[104:105], v[92:93] op_sel_hi:[1,0]
	v_pk_fma_f32 v[18:19], v[18:19], v[102:103], v[42:43] op_sel:[0,0,0] op_sel_hi:[1,0,1]
	v_pk_fma_f32 v[38:39], v[18:19], v[92:93], v[38:39] op_sel:[0,1,0] op_sel_hi:[1,1,1]
	v_pk_mul_f32 v[44:45], v[104:105], v[94:95] op_sel_hi:[1,0]
	v_pk_fma_f32 v[20:21], v[20:21], v[102:103], v[44:45] op_sel:[0,1,0] op_sel_hi:[1,1,1]
	v_pk_fma_f32 v[38:39], v[20:21], v[94:95], v[38:39] op_sel:[0,1,0] op_sel_hi:[1,1,1]
	s_add_u32 s14, s14, 0x1000
	s_addc_u32 s15, s15, 0
	v_add_f32_dpp v38, v38, v38 row_ror:8 row_mask:0xf bank_mask:0x3 bound_ctrl:1
	v_add_f32_dpp v38, v39, v39 row_ror:8 row_mask:0xf bank_mask:0xc bound_ctrl:1
	ds_read_b64 v[72:73], v3 offset:45824
	ds_read_b128 v[48:51], v2 offset:26880
	v_add_f32_dpp v38, v38, v38 row_half_mirror row_mask:0xf bank_mask:0xf bound_ctrl:1
	ds_read_b128 v[64:67], v2 offset:42240
	ds_read_b128 v[52:55], v2 offset:27136
	v_add_f32_dpp v38, v38, v38 quad_perm:[1,0,3,2] row_mask:0xf bank_mask:0xf bound_ctrl:1
	ds_read_b128 v[56:59], v2 offset:27392
	ds_read_b128 v[68:71], v2 offset:42496
	v_add_f32_dpp v38, v38, v38 quad_perm:[2,3,0,1] row_mask:0xf bank_mask:0xf bound_ctrl:1
	ds_read_b128 v[60:63], v2 offset:27648
	v_cvt_pk_bf16_f32 v47, v38, v38
	s_mov_b64 exec, s[2:3]
	global_store_short v28, v47, s[14:15] offset:-4096
	s_mov_b64 exec, -1
	s_waitcnt lgkmcnt(4)
	v_pk_mul_f32 v[42:43], v[72:73], v[48:49] op_sel_hi:[1,0]
	v_pk_fma_f32 v[6:7], v[6:7], v[64:65], v[42:43] op_sel:[0,0,0] op_sel_hi:[1,0,1]
	v_pk_mul_f32 v[38:39], v[6:7], v[48:49] op_sel:[0,1] op_sel_hi:[1,1]
	v_pk_mul_f32 v[44:45], v[72:73], v[50:51] op_sel_hi:[1,0]
	v_pk_fma_f32 v[8:9], v[8:9], v[64:65], v[44:45] op_sel:[0,1,0] op_sel_hi:[1,1,1]
	v_pk_fma_f32 v[38:39], v[8:9], v[50:51], v[38:39] op_sel:[0,1,0] op_sel_hi:[1,1,1]
	s_waitcnt lgkmcnt(3)
	v_pk_mul_f32 v[42:43], v[72:73], v[52:53] op_sel_hi:[1,0]
	v_pk_fma_f32 v[10:11], v[10:11], v[66:67], v[42:43] op_sel:[0,0,0] op_sel_hi:[1,0,1]
	v_pk_fma_f32 v[38:39], v[10:11], v[52:53], v[38:39] op_sel:[0,1,0] op_sel_hi:[1,1,1]
	v_pk_mul_f32 v[44:45], v[72:73], v[54:55] op_sel_hi:[1,0]
	v_pk_fma_f32 v[12:13], v[12:13], v[66:67], v[44:45] op_sel:[0,1,0] op_sel_hi:[1,1,1]
	v_pk_fma_f32 v[38:39], v[12:13], v[54:55], v[38:39] op_sel:[0,1,0] op_sel_hi:[1,1,1]
	s_waitcnt lgkmcnt(1)
	v_pk_mul_f32 v[42:43], v[72:73], v[56:57] op_sel_hi:[1,0]
	v_pk_fma_f32 v[14:15], v[14:15], v[68:69], v[42:43] op_sel:[0,0,0] op_sel_hi:[1,0,1]
	v_pk_fma_f32 v[38:39], v[14:15], v[56:57], v[38:39] op_sel:[0,1,0] op_sel_hi:[1,1,1]
	v_pk_mul_f32 v[44:45], v[72:73], v[58:59] op_sel_hi:[1,0]
	v_pk_fma_f32 v[16:17], v[16:17], v[68:69], v[44:45] op_sel:[0,1,0] op_sel_hi:[1,1,1]
	v_pk_fma_f32 v[38:39], v[16:17], v[58:59], v[38:39] op_sel:[0,1,0] op_sel_hi:[1,1,1]
	s_waitcnt lgkmcnt(0)
	v_pk_mul_f32 v[42:43], v[72:73], v[60:61] op_sel_hi:[1,0]
	v_pk_fma_f32 v[18:19], v[18:19], v[70:71], v[42:43] op_sel:[0,0,0] op_sel_hi:[1,0,1]
	v_pk_fma_f32 v[38:39], v[18:19], v[60:61], v[38:39] op_sel:[0,1,0] op_sel_hi:[1,1,1]
	v_pk_mul_f32 v[44:45], v[72:73], v[62:63] op_sel_hi:[1,0]
	v_pk_fma_f32 v[20:21], v[20:21], v[70:71], v[44:45] op_sel:[0,1,0] op_sel_hi:[1,1,1]
	v_pk_fma_f32 v[38:39], v[20:21], v[62:63], v[38:39] op_sel:[0,1,0] op_sel_hi:[1,1,1]
	s_add_u32 s14, s14, 0x1000
	s_addc_u32 s15, s15, 0
	v_add_f32_dpp v38, v38, v38 row_ror:8 row_mask:0xf bank_mask:0x3 bound_ctrl:1
	v_add_f32_dpp v38, v39, v39 row_ror:8 row_mask:0xf bank_mask:0xc bound_ctrl:1
	ds_read_b64 v[104:105], v3 offset:46080
	ds_read_b128 v[80:83], v2 offset:27904
	v_add_f32_dpp v38, v38, v38 row_half_mirror row_mask:0xf bank_mask:0xf bound_ctrl:1
	ds_read_b128 v[96:99], v2 offset:42752
	ds_read_b128 v[84:87], v2 offset:28160
	v_add_f32_dpp v38, v38, v38 quad_perm:[1,0,3,2] row_mask:0xf bank_mask:0xf bound_ctrl:1
	ds_read_b128 v[88:91], v2 offset:28416
	ds_read_b128 v[100:103], v2 offset:43008
	v_add_f32_dpp v38, v38, v38 quad_perm:[2,3,0,1] row_mask:0xf bank_mask:0xf bound_ctrl:1
	ds_read_b128 v[92:95], v2 offset:28672
	v_cvt_pk_bf16_f32 v47, v38, v38
	s_mov_b64 exec, s[2:3]
	global_store_short v28, v47, s[14:15] offset:-4096
	s_mov_b64 exec, -1
	s_waitcnt lgkmcnt(4)
	v_pk_mul_f32 v[42:43], v[104:105], v[80:81] op_sel_hi:[1,0]
	v_pk_fma_f32 v[6:7], v[6:7], v[96:97], v[42:43] op_sel:[0,0,0] op_sel_hi:[1,0,1]
	v_pk_mul_f32 v[38:39], v[6:7], v[80:81] op_sel:[0,1] op_sel_hi:[1,1]
	v_pk_mul_f32 v[44:45], v[104:105], v[82:83] op_sel_hi:[1,0]
	v_pk_fma_f32 v[8:9], v[8:9], v[96:97], v[44:45] op_sel:[0,1,0] op_sel_hi:[1,1,1]
	v_pk_fma_f32 v[38:39], v[8:9], v[82:83], v[38:39] op_sel:[0,1,0] op_sel_hi:[1,1,1]
	s_waitcnt lgkmcnt(3)
	v_pk_mul_f32 v[42:43], v[104:105], v[84:85] op_sel_hi:[1,0]
	v_pk_fma_f32 v[10:11], v[10:11], v[98:99], v[42:43] op_sel:[0,0,0] op_sel_hi:[1,0,1]
	v_pk_fma_f32 v[38:39], v[10:11], v[84:85], v[38:39] op_sel:[0,1,0] op_sel_hi:[1,1,1]
	v_pk_mul_f32 v[44:45], v[104:105], v[86:87] op_sel_hi:[1,0]
	v_pk_fma_f32 v[12:13], v[12:13], v[98:99], v[44:45] op_sel:[0,1,0] op_sel_hi:[1,1,1]
	v_pk_fma_f32 v[38:39], v[12:13], v[86:87], v[38:39] op_sel:[0,1,0] op_sel_hi:[1,1,1]
	s_waitcnt lgkmcnt(1)
	v_pk_mul_f32 v[42:43], v[104:105], v[88:89] op_sel_hi:[1,0]
	v_pk_fma_f32 v[14:15], v[14:15], v[100:101], v[42:43] op_sel:[0,0,0] op_sel_hi:[1,0,1]
	v_pk_fma_f32 v[38:39], v[14:15], v[88:89], v[38:39] op_sel:[0,1,0] op_sel_hi:[1,1,1]
	v_pk_mul_f32 v[44:45], v[104:105], v[90:91] op_sel_hi:[1,0]
	v_pk_fma_f32 v[16:17], v[16:17], v[100:101], v[44:45] op_sel:[0,1,0] op_sel_hi:[1,1,1]
	v_pk_fma_f32 v[38:39], v[16:17], v[90:91], v[38:39] op_sel:[0,1,0] op_sel_hi:[1,1,1]
	s_waitcnt lgkmcnt(0)
	v_pk_mul_f32 v[42:43], v[104:105], v[92:93] op_sel_hi:[1,0]
	v_pk_fma_f32 v[18:19], v[18:19], v[102:103], v[42:43] op_sel:[0,0,0] op_sel_hi:[1,0,1]
	v_pk_fma_f32 v[38:39], v[18:19], v[92:93], v[38:39] op_sel:[0,1,0] op_sel_hi:[1,1,1]
	v_pk_mul_f32 v[44:45], v[104:105], v[94:95] op_sel_hi:[1,0]
	v_pk_fma_f32 v[20:21], v[20:21], v[102:103], v[44:45] op_sel:[0,1,0] op_sel_hi:[1,1,1]
	v_pk_fma_f32 v[38:39], v[20:21], v[94:95], v[38:39] op_sel:[0,1,0] op_sel_hi:[1,1,1]
	s_add_u32 s14, s14, 0x1000
	s_addc_u32 s15, s15, 0
	v_add_f32_dpp v38, v38, v38 row_ror:8 row_mask:0xf bank_mask:0x3 bound_ctrl:1
	v_add_f32_dpp v38, v39, v39 row_ror:8 row_mask:0xf bank_mask:0xc bound_ctrl:1
	ds_read_b64 v[72:73], v3 offset:46336
	ds_read_b128 v[48:51], v2 offset:28928
	v_add_f32_dpp v38, v38, v38 row_half_mirror row_mask:0xf bank_mask:0xf bound_ctrl:1
	ds_read_b128 v[64:67], v2 offset:43264
	ds_read_b128 v[52:55], v2 offset:29184
	v_add_f32_dpp v38, v38, v38 quad_perm:[1,0,3,2] row_mask:0xf bank_mask:0xf bound_ctrl:1
	ds_read_b128 v[56:59], v2 offset:29440
	ds_read_b128 v[68:71], v2 offset:43520
	v_add_f32_dpp v38, v38, v38 quad_perm:[2,3,0,1] row_mask:0xf bank_mask:0xf bound_ctrl:1
	ds_read_b128 v[60:63], v2 offset:29696
	v_cvt_pk_bf16_f32 v47, v38, v38
	s_mov_b64 exec, s[2:3]
	global_store_short v28, v47, s[14:15] offset:-4096
	s_mov_b64 exec, -1
	s_waitcnt lgkmcnt(4)
	v_pk_mul_f32 v[42:43], v[72:73], v[48:49] op_sel_hi:[1,0]
	v_pk_fma_f32 v[6:7], v[6:7], v[64:65], v[42:43] op_sel:[0,0,0] op_sel_hi:[1,0,1]
	v_pk_mul_f32 v[38:39], v[6:7], v[48:49] op_sel:[0,1] op_sel_hi:[1,1]
	v_pk_mul_f32 v[44:45], v[72:73], v[50:51] op_sel_hi:[1,0]
	v_pk_fma_f32 v[8:9], v[8:9], v[64:65], v[44:45] op_sel:[0,1,0] op_sel_hi:[1,1,1]
	v_pk_fma_f32 v[38:39], v[8:9], v[50:51], v[38:39] op_sel:[0,1,0] op_sel_hi:[1,1,1]
	s_waitcnt lgkmcnt(3)
	v_pk_mul_f32 v[42:43], v[72:73], v[52:53] op_sel_hi:[1,0]
	v_pk_fma_f32 v[10:11], v[10:11], v[66:67], v[42:43] op_sel:[0,0,0] op_sel_hi:[1,0,1]
	v_pk_fma_f32 v[38:39], v[10:11], v[52:53], v[38:39] op_sel:[0,1,0] op_sel_hi:[1,1,1]
	v_pk_mul_f32 v[44:45], v[72:73], v[54:55] op_sel_hi:[1,0]
	v_pk_fma_f32 v[12:13], v[12:13], v[66:67], v[44:45] op_sel:[0,1,0] op_sel_hi:[1,1,1]
	v_pk_fma_f32 v[38:39], v[12:13], v[54:55], v[38:39] op_sel:[0,1,0] op_sel_hi:[1,1,1]
	s_waitcnt lgkmcnt(1)
	v_pk_mul_f32 v[42:43], v[72:73], v[56:57] op_sel_hi:[1,0]
	v_pk_fma_f32 v[14:15], v[14:15], v[68:69], v[42:43] op_sel:[0,0,0] op_sel_hi:[1,0,1]
	v_pk_fma_f32 v[38:39], v[14:15], v[56:57], v[38:39] op_sel:[0,1,0] op_sel_hi:[1,1,1]
	v_pk_mul_f32 v[44:45], v[72:73], v[58:59] op_sel_hi:[1,0]
	v_pk_fma_f32 v[16:17], v[16:17], v[68:69], v[44:45] op_sel:[0,1,0] op_sel_hi:[1,1,1]
	v_pk_fma_f32 v[38:39], v[16:17], v[58:59], v[38:39] op_sel:[0,1,0] op_sel_hi:[1,1,1]
	s_waitcnt lgkmcnt(0)
	v_pk_mul_f32 v[42:43], v[72:73], v[60:61] op_sel_hi:[1,0]
	v_pk_fma_f32 v[18:19], v[18:19], v[70:71], v[42:43] op_sel:[0,0,0] op_sel_hi:[1,0,1]
	v_pk_fma_f32 v[38:39], v[18:19], v[60:61], v[38:39] op_sel:[0,1,0] op_sel_hi:[1,1,1]
	v_pk_mul_f32 v[44:45], v[72:73], v[62:63] op_sel_hi:[1,0]
	v_pk_fma_f32 v[20:21], v[20:21], v[70:71], v[44:45] op_sel:[0,1,0] op_sel_hi:[1,1,1]
	v_pk_fma_f32 v[38:39], v[20:21], v[62:63], v[38:39] op_sel:[0,1,0] op_sel_hi:[1,1,1]
	s_add_u32 s14, s14, 0x1000
	s_addc_u32 s15, s15, 0
	v_add_f32_dpp v38, v38, v38 row_ror:8 row_mask:0xf bank_mask:0x3 bound_ctrl:1
	v_add_f32_dpp v38, v39, v39 row_ror:8 row_mask:0xf bank_mask:0xc bound_ctrl:1
	ds_read_b64 v[104:105], v3 offset:46592
	ds_read_b128 v[80:83], v2 offset:29952
	v_add_f32_dpp v38, v38, v38 row_half_mirror row_mask:0xf bank_mask:0xf bound_ctrl:1
	ds_read_b128 v[96:99], v2 offset:43776
	ds_read_b128 v[84:87], v2 offset:30208
	v_add_f32_dpp v38, v38, v38 quad_perm:[1,0,3,2] row_mask:0xf bank_mask:0xf bound_ctrl:1
	ds_read_b128 v[88:91], v2 offset:30464
	ds_read_b128 v[100:103], v2 offset:44032
	v_add_f32_dpp v38, v38, v38 quad_perm:[2,3,0,1] row_mask:0xf bank_mask:0xf bound_ctrl:1
	ds_read_b128 v[92:95], v2 offset:30720
	v_cvt_pk_bf16_f32 v47, v38, v38
	s_mov_b64 exec, s[2:3]
	global_store_short v28, v47, s[14:15] offset:-4096
	s_mov_b64 exec, -1
	s_waitcnt lgkmcnt(4)
	v_pk_mul_f32 v[42:43], v[104:105], v[80:81] op_sel_hi:[1,0]
	v_pk_fma_f32 v[6:7], v[6:7], v[96:97], v[42:43] op_sel:[0,0,0] op_sel_hi:[1,0,1]
	v_pk_mul_f32 v[38:39], v[6:7], v[80:81] op_sel:[0,1] op_sel_hi:[1,1]
	v_pk_mul_f32 v[44:45], v[104:105], v[82:83] op_sel_hi:[1,0]
	v_pk_fma_f32 v[8:9], v[8:9], v[96:97], v[44:45] op_sel:[0,1,0] op_sel_hi:[1,1,1]
	v_pk_fma_f32 v[38:39], v[8:9], v[82:83], v[38:39] op_sel:[0,1,0] op_sel_hi:[1,1,1]
	s_waitcnt lgkmcnt(3)
	v_pk_mul_f32 v[42:43], v[104:105], v[84:85] op_sel_hi:[1,0]
	v_pk_fma_f32 v[10:11], v[10:11], v[98:99], v[42:43] op_sel:[0,0,0] op_sel_hi:[1,0,1]
	v_pk_fma_f32 v[38:39], v[10:11], v[84:85], v[38:39] op_sel:[0,1,0] op_sel_hi:[1,1,1]
	v_pk_mul_f32 v[44:45], v[104:105], v[86:87] op_sel_hi:[1,0]
	v_pk_fma_f32 v[12:13], v[12:13], v[98:99], v[44:45] op_sel:[0,1,0] op_sel_hi:[1,1,1]
	v_pk_fma_f32 v[38:39], v[12:13], v[86:87], v[38:39] op_sel:[0,1,0] op_sel_hi:[1,1,1]
	s_waitcnt lgkmcnt(1)
	v_pk_mul_f32 v[42:43], v[104:105], v[88:89] op_sel_hi:[1,0]
	v_pk_fma_f32 v[14:15], v[14:15], v[100:101], v[42:43] op_sel:[0,0,0] op_sel_hi:[1,0,1]
	v_pk_fma_f32 v[38:39], v[14:15], v[88:89], v[38:39] op_sel:[0,1,0] op_sel_hi:[1,1,1]
	v_pk_mul_f32 v[44:45], v[104:105], v[90:91] op_sel_hi:[1,0]
	v_pk_fma_f32 v[16:17], v[16:17], v[100:101], v[44:45] op_sel:[0,1,0] op_sel_hi:[1,1,1]
	v_pk_fma_f32 v[38:39], v[16:17], v[90:91], v[38:39] op_sel:[0,1,0] op_sel_hi:[1,1,1]
	s_waitcnt lgkmcnt(0)
	v_pk_mul_f32 v[42:43], v[104:105], v[92:93] op_sel_hi:[1,0]
	v_pk_fma_f32 v[18:19], v[18:19], v[102:103], v[42:43] op_sel:[0,0,0] op_sel_hi:[1,0,1]
	v_pk_fma_f32 v[38:39], v[18:19], v[92:93], v[38:39] op_sel:[0,1,0] op_sel_hi:[1,1,1]
	v_pk_mul_f32 v[44:45], v[104:105], v[94:95] op_sel_hi:[1,0]
	v_pk_fma_f32 v[20:21], v[20:21], v[102:103], v[44:45] op_sel:[0,1,0] op_sel_hi:[1,1,1]
	v_pk_fma_f32 v[38:39], v[20:21], v[94:95], v[38:39] op_sel:[0,1,0] op_sel_hi:[1,1,1]
	s_add_u32 s14, s14, 0x1000
	s_addc_u32 s15, s15, 0
	v_add_f32_dpp v38, v38, v38 row_ror:8 row_mask:0xf bank_mask:0x3 bound_ctrl:1
	v_add_f32_dpp v38, v39, v39 row_ror:8 row_mask:0xf bank_mask:0xc bound_ctrl:1
	ds_read_b64 v[72:73], v3 offset:46848
	ds_read_b128 v[48:51], v2 offset:30976
	v_add_f32_dpp v38, v38, v38 row_half_mirror row_mask:0xf bank_mask:0xf bound_ctrl:1
	ds_read_b128 v[64:67], v2 offset:44288
	ds_read_b128 v[52:55], v2 offset:31232
	v_add_f32_dpp v38, v38, v38 quad_perm:[1,0,3,2] row_mask:0xf bank_mask:0xf bound_ctrl:1
	ds_read_b128 v[56:59], v2 offset:31488
	ds_read_b128 v[68:71], v2 offset:44544
	v_add_f32_dpp v38, v38, v38 quad_perm:[2,3,0,1] row_mask:0xf bank_mask:0xf bound_ctrl:1
	ds_read_b128 v[60:63], v2 offset:31744
	v_cvt_pk_bf16_f32 v47, v38, v38
	s_mov_b64 exec, s[2:3]
	global_store_short v28, v47, s[14:15] offset:-4096
	s_mov_b64 exec, -1
	s_waitcnt lgkmcnt(4)
	v_pk_mul_f32 v[42:43], v[72:73], v[48:49] op_sel_hi:[1,0]
	v_pk_fma_f32 v[6:7], v[6:7], v[64:65], v[42:43] op_sel:[0,0,0] op_sel_hi:[1,0,1]
	v_pk_mul_f32 v[38:39], v[6:7], v[48:49] op_sel:[0,1] op_sel_hi:[1,1]
	v_pk_mul_f32 v[44:45], v[72:73], v[50:51] op_sel_hi:[1,0]
	v_pk_fma_f32 v[8:9], v[8:9], v[64:65], v[44:45] op_sel:[0,1,0] op_sel_hi:[1,1,1]
	v_pk_fma_f32 v[38:39], v[8:9], v[50:51], v[38:39] op_sel:[0,1,0] op_sel_hi:[1,1,1]
	s_waitcnt lgkmcnt(3)
	v_pk_mul_f32 v[42:43], v[72:73], v[52:53] op_sel_hi:[1,0]
	v_pk_fma_f32 v[10:11], v[10:11], v[66:67], v[42:43] op_sel:[0,0,0] op_sel_hi:[1,0,1]
	v_pk_fma_f32 v[38:39], v[10:11], v[52:53], v[38:39] op_sel:[0,1,0] op_sel_hi:[1,1,1]
	v_pk_mul_f32 v[44:45], v[72:73], v[54:55] op_sel_hi:[1,0]
	v_pk_fma_f32 v[12:13], v[12:13], v[66:67], v[44:45] op_sel:[0,1,0] op_sel_hi:[1,1,1]
	v_pk_fma_f32 v[38:39], v[12:13], v[54:55], v[38:39] op_sel:[0,1,0] op_sel_hi:[1,1,1]
	s_waitcnt lgkmcnt(1)
	v_pk_mul_f32 v[42:43], v[72:73], v[56:57] op_sel_hi:[1,0]
	v_pk_fma_f32 v[14:15], v[14:15], v[68:69], v[42:43] op_sel:[0,0,0] op_sel_hi:[1,0,1]
	v_pk_fma_f32 v[38:39], v[14:15], v[56:57], v[38:39] op_sel:[0,1,0] op_sel_hi:[1,1,1]
	v_pk_mul_f32 v[44:45], v[72:73], v[58:59] op_sel_hi:[1,0]
	v_pk_fma_f32 v[16:17], v[16:17], v[68:69], v[44:45] op_sel:[0,1,0] op_sel_hi:[1,1,1]
	v_pk_fma_f32 v[38:39], v[16:17], v[58:59], v[38:39] op_sel:[0,1,0] op_sel_hi:[1,1,1]
	s_waitcnt lgkmcnt(0)
	v_pk_mul_f32 v[42:43], v[72:73], v[60:61] op_sel_hi:[1,0]
	v_pk_fma_f32 v[18:19], v[18:19], v[70:71], v[42:43] op_sel:[0,0,0] op_sel_hi:[1,0,1]
	v_pk_fma_f32 v[38:39], v[18:19], v[60:61], v[38:39] op_sel:[0,1,0] op_sel_hi:[1,1,1]
	v_pk_mul_f32 v[44:45], v[72:73], v[62:63] op_sel_hi:[1,0]
	v_pk_fma_f32 v[20:21], v[20:21], v[70:71], v[44:45] op_sel:[0,1,0] op_sel_hi:[1,1,1]
	v_pk_fma_f32 v[38:39], v[20:21], v[62:63], v[38:39] op_sel:[0,1,0] op_sel_hi:[1,1,1]
	s_add_u32 s14, s14, 0x1000
	s_addc_u32 s15, s15, 0
	v_add_f32_dpp v38, v38, v38 row_ror:8 row_mask:0xf bank_mask:0x3 bound_ctrl:1
	v_add_f32_dpp v38, v39, v39 row_ror:8 row_mask:0xf bank_mask:0xc bound_ctrl:1
	ds_read_b64 v[104:105], v3 offset:47104
	ds_read_b128 v[80:83], v2 offset:32000
	v_add_f32_dpp v38, v38, v38 row_half_mirror row_mask:0xf bank_mask:0xf bound_ctrl:1
	ds_read_b128 v[96:99], v2 offset:44800
	ds_read_b128 v[84:87], v2 offset:32256
	v_add_f32_dpp v38, v38, v38 quad_perm:[1,0,3,2] row_mask:0xf bank_mask:0xf bound_ctrl:1
	ds_read_b128 v[88:91], v2 offset:32512
	ds_read_b128 v[100:103], v2 offset:45056
	v_add_f32_dpp v38, v38, v38 quad_perm:[2,3,0,1] row_mask:0xf bank_mask:0xf bound_ctrl:1
	ds_read_b128 v[92:95], v2 offset:32768
	v_cvt_pk_bf16_f32 v47, v38, v38
	s_mov_b64 exec, s[2:3]
	global_store_short v28, v47, s[14:15] offset:-4096
	s_mov_b64 exec, -1
	s_waitcnt lgkmcnt(4)
	v_pk_mul_f32 v[42:43], v[104:105], v[80:81] op_sel_hi:[1,0]
	v_pk_fma_f32 v[6:7], v[6:7], v[96:97], v[42:43] op_sel:[0,0,0] op_sel_hi:[1,0,1]
	v_pk_mul_f32 v[38:39], v[6:7], v[80:81] op_sel:[0,1] op_sel_hi:[1,1]
	v_pk_mul_f32 v[44:45], v[104:105], v[82:83] op_sel_hi:[1,0]
	v_pk_fma_f32 v[8:9], v[8:9], v[96:97], v[44:45] op_sel:[0,1,0] op_sel_hi:[1,1,1]
	v_pk_fma_f32 v[38:39], v[8:9], v[82:83], v[38:39] op_sel:[0,1,0] op_sel_hi:[1,1,1]
	s_waitcnt lgkmcnt(3)
	v_pk_mul_f32 v[42:43], v[104:105], v[84:85] op_sel_hi:[1,0]
	v_pk_fma_f32 v[10:11], v[10:11], v[98:99], v[42:43] op_sel:[0,0,0] op_sel_hi:[1,0,1]
	v_pk_fma_f32 v[38:39], v[10:11], v[84:85], v[38:39] op_sel:[0,1,0] op_sel_hi:[1,1,1]
	v_pk_mul_f32 v[44:45], v[104:105], v[86:87] op_sel_hi:[1,0]
	v_pk_fma_f32 v[12:13], v[12:13], v[98:99], v[44:45] op_sel:[0,1,0] op_sel_hi:[1,1,1]
	v_pk_fma_f32 v[38:39], v[12:13], v[86:87], v[38:39] op_sel:[0,1,0] op_sel_hi:[1,1,1]
	s_waitcnt lgkmcnt(1)
	v_pk_mul_f32 v[42:43], v[104:105], v[88:89] op_sel_hi:[1,0]
	v_pk_fma_f32 v[14:15], v[14:15], v[100:101], v[42:43] op_sel:[0,0,0] op_sel_hi:[1,0,1]
	v_pk_fma_f32 v[38:39], v[14:15], v[88:89], v[38:39] op_sel:[0,1,0] op_sel_hi:[1,1,1]
	v_pk_mul_f32 v[44:45], v[104:105], v[90:91] op_sel_hi:[1,0]
	v_pk_fma_f32 v[16:17], v[16:17], v[100:101], v[44:45] op_sel:[0,1,0] op_sel_hi:[1,1,1]
	v_pk_fma_f32 v[38:39], v[16:17], v[90:91], v[38:39] op_sel:[0,1,0] op_sel_hi:[1,1,1]
	s_waitcnt lgkmcnt(0)
	v_pk_mul_f32 v[42:43], v[104:105], v[92:93] op_sel_hi:[1,0]
	v_pk_fma_f32 v[18:19], v[18:19], v[102:103], v[42:43] op_sel:[0,0,0] op_sel_hi:[1,0,1]
	v_pk_fma_f32 v[38:39], v[18:19], v[92:93], v[38:39] op_sel:[0,1,0] op_sel_hi:[1,1,1]
	v_pk_mul_f32 v[44:45], v[104:105], v[94:95] op_sel_hi:[1,0]
	v_pk_fma_f32 v[20:21], v[20:21], v[102:103], v[44:45] op_sel:[0,1,0] op_sel_hi:[1,1,1]
	v_pk_fma_f32 v[38:39], v[20:21], v[94:95], v[38:39] op_sel:[0,1,0] op_sel_hi:[1,1,1]
	s_add_u32 s14, s14, 0x1000
	s_addc_u32 s15, s15, 0
	v_add_f32_dpp v38, v38, v38 row_ror:8 row_mask:0xf bank_mask:0x3 bound_ctrl:1
	v_add_f32_dpp v38, v39, v39 row_ror:8 row_mask:0xf bank_mask:0xc bound_ctrl:1
	ds_read_b64 v[72:73], v23 offset:37120
	ds_read_b128 v[48:51], v2 offset:49408
	v_add_f32_dpp v38, v38, v38 row_half_mirror row_mask:0xf bank_mask:0xf bound_ctrl:1
	ds_read_b128 v[64:67], v22 offset:33024
	ds_read_b128 v[52:55], v2 offset:49664
	v_add_f32_dpp v38, v38, v38 quad_perm:[1,0,3,2] row_mask:0xf bank_mask:0xf bound_ctrl:1
	ds_read_b128 v[56:59], v2 offset:49920
	ds_read_b128 v[68:71], v22 offset:33280
	v_add_f32_dpp v38, v38, v38 quad_perm:[2,3,0,1] row_mask:0xf bank_mask:0xf bound_ctrl:1
	ds_read_b128 v[60:63], v2 offset:50176
	v_cvt_pk_bf16_f32 v47, v38, v38
	s_mov_b64 exec, s[2:3]
	global_store_short v28, v47, s[14:15] offset:-4096
	s_mov_b64 exec, -1
	s_waitcnt vmcnt(8)
	v_lshlrev_b32_e32 v144, 16, v110
	v_lshlrev_b32_e32 v145, 16, v111
	v_and_b32_e32 v146, s17, v110
	v_and_b32_e32 v147, s17, v111
	v_lshlrev_b32_e32 v148, 16, v112
	v_lshlrev_b32_e32 v149, 16, v113
	v_and_b32_e32 v150, s17, v112
	v_and_b32_e32 v151, s17, v113
	v_lshlrev_b32_e32 v152, 16, v114
	v_and_b32_e32 v153, s17, v114
	v_rcp_f32_e32 v25, v24
	v_mul_f32_e32 v149, v24, v149
	v_mul_f32_e32 v151, v24, v151
	v_mul_f32_e32 v145, 0x3db504f3, v145
	v_mul_f32_e32 v147, 0x3db504f3, v147
	v_cndmask_b32_e64 v27, 1.0, v25, s[20:21]
	v_mul_f32_e32 v24, v24, v26
	v_mul_f32_e32 v152, v27, v152
	v_mul_f32_e32 v153, v27, v153
	ds_write_b128 v29, v[144:147] offset:256
	ds_write_b128 v29, v[148:151] offset:8448
	ds_write_b64 v30, v[116:117] offset:256
	ds_write_b64 v31, v[152:153] offset:256
	s_add_i32 s16, s16, 8
	s_waitcnt lgkmcnt(0)
	s_barrier
	s_cmpk_lt_u32 s16, 0x800
	s_cbranch_scc0 .Lgla2_done
	global_load_dword v110, v32, s[10:11]
	global_load_dword v111, v32, s[10:11] offset:-1024
	global_load_dword v112, v33, s[10:11]
	global_load_dword v113, v33, s[10:11] offset:-1024
	global_load_dword v114, v34, s[10:11]
	global_load_dword v116, v35, s[12:13]
	global_load_dword v117, v35, s[12:13] offset:4
	s_add_u32 s10, s10, 0x18000
	s_addc_u32 s11, s11, 0
	s_add_u32 s12, s12, 0x4000
	s_addc_u32 s13, s13, 0
	s_waitcnt lgkmcnt(4)
	v_pk_mul_f32 v[42:43], v[72:73], v[48:49] op_sel_hi:[1,0]
	v_pk_fma_f32 v[6:7], v[6:7], v[64:65], v[42:43] op_sel:[0,0,0] op_sel_hi:[1,0,1]
	v_pk_mul_f32 v[38:39], v[6:7], v[48:49] op_sel:[0,1] op_sel_hi:[1,1]
	v_pk_mul_f32 v[44:45], v[72:73], v[50:51] op_sel_hi:[1,0]
	v_pk_fma_f32 v[8:9], v[8:9], v[64:65], v[44:45] op_sel:[0,1,0] op_sel_hi:[1,1,1]
	v_pk_fma_f32 v[38:39], v[8:9], v[50:51], v[38:39] op_sel:[0,1,0] op_sel_hi:[1,1,1]
	s_waitcnt lgkmcnt(3)
	v_pk_mul_f32 v[42:43], v[72:73], v[52:53] op_sel_hi:[1,0]
	v_pk_fma_f32 v[10:11], v[10:11], v[66:67], v[42:43] op_sel:[0,0,0] op_sel_hi:[1,0,1]
	v_pk_fma_f32 v[38:39], v[10:11], v[52:53], v[38:39] op_sel:[0,1,0] op_sel_hi:[1,1,1]
	v_pk_mul_f32 v[44:45], v[72:73], v[54:55] op_sel_hi:[1,0]
	v_pk_fma_f32 v[12:13], v[12:13], v[66:67], v[44:45] op_sel:[0,1,0] op_sel_hi:[1,1,1]
	v_pk_fma_f32 v[38:39], v[12:13], v[54:55], v[38:39] op_sel:[0,1,0] op_sel_hi:[1,1,1]
	s_waitcnt lgkmcnt(1)
	v_pk_mul_f32 v[42:43], v[72:73], v[56:57] op_sel_hi:[1,0]
	v_pk_fma_f32 v[14:15], v[14:15], v[68:69], v[42:43] op_sel:[0,0,0] op_sel_hi:[1,0,1]
	v_pk_fma_f32 v[38:39], v[14:15], v[56:57], v[38:39] op_sel:[0,1,0] op_sel_hi:[1,1,1]
	v_pk_mul_f32 v[44:45], v[72:73], v[58:59] op_sel_hi:[1,0]
	v_pk_fma_f32 v[16:17], v[16:17], v[68:69], v[44:45] op_sel:[0,1,0] op_sel_hi:[1,1,1]
	v_pk_fma_f32 v[38:39], v[16:17], v[58:59], v[38:39] op_sel:[0,1,0] op_sel_hi:[1,1,1]
	s_waitcnt lgkmcnt(0)
	v_pk_mul_f32 v[42:43], v[72:73], v[60:61] op_sel_hi:[1,0]
	v_pk_fma_f32 v[18:19], v[18:19], v[70:71], v[42:43] op_sel:[0,0,0] op_sel_hi:[1,0,1]
	v_pk_fma_f32 v[38:39], v[18:19], v[60:61], v[38:39] op_sel:[0,1,0] op_sel_hi:[1,1,1]
	v_pk_mul_f32 v[44:45], v[72:73], v[62:63] op_sel_hi:[1,0]
	v_pk_fma_f32 v[20:21], v[20:21], v[70:71], v[44:45] op_sel:[0,1,0] op_sel_hi:[1,1,1]
	v_pk_fma_f32 v[38:39], v[20:21], v[62:63], v[38:39] op_sel:[0,1,0] op_sel_hi:[1,1,1]
	s_add_u32 s14, s14, 0x1000
	s_addc_u32 s15, s15, 0
	v_add_f32_dpp v38, v38, v38 row_ror:8 row_mask:0xf bank_mask:0x3 bound_ctrl:1
	v_add_f32_dpp v38, v39, v39 row_ror:8 row_mask:0xf bank_mask:0xc bound_ctrl:1
	ds_read_b64 v[104:105], v23 offset:37376
	ds_read_b128 v[80:83], v2 offset:50432
	v_add_f32_dpp v38, v38, v38 row_half_mirror row_mask:0xf bank_mask:0xf bound_ctrl:1
	ds_read_b128 v[96:99], v22 offset:33536
	ds_read_b128 v[84:87], v2 offset:50688
	v_add_f32_dpp v38, v38, v38 quad_perm:[1,0,3,2] row_mask:0xf bank_mask:0xf bound_ctrl:1
	ds_read_b128 v[88:91], v2 offset:50944
	ds_read_b128 v[100:103], v22 offset:33792
	v_add_f32_dpp v38, v38, v38 quad_perm:[2,3,0,1] row_mask:0xf bank_mask:0xf bound_ctrl:1
	ds_read_b128 v[92:95], v2 offset:51200
	v_cvt_pk_bf16_f32 v47, v38, v38
	s_mov_b64 exec, s[2:3]
	global_store_short v28, v47, s[14:15] offset:-4096
	s_mov_b64 exec, -1
	s_waitcnt lgkmcnt(4)
	v_pk_mul_f32 v[42:43], v[104:105], v[80:81] op_sel_hi:[1,0]
	v_pk_fma_f32 v[6:7], v[6:7], v[96:97], v[42:43] op_sel:[0,0,0] op_sel_hi:[1,0,1]
	v_pk_mul_f32 v[38:39], v[6:7], v[80:81] op_sel:[0,1] op_sel_hi:[1,1]
	v_pk_mul_f32 v[44:45], v[104:105], v[82:83] op_sel_hi:[1,0]
	v_pk_fma_f32 v[8:9], v[8:9], v[96:97], v[44:45] op_sel:[0,1,0] op_sel_hi:[1,1,1]
	v_pk_fma_f32 v[38:39], v[8:9], v[82:83], v[38:39] op_sel:[0,1,0] op_sel_hi:[1,1,1]
	s_waitcnt lgkmcnt(3)
	v_pk_mul_f32 v[42:43], v[104:105], v[84:85] op_sel_hi:[1,0]
	v_pk_fma_f32 v[10:11], v[10:11], v[98:99], v[42:43] op_sel:[0,0,0] op_sel_hi:[1,0,1]
	v_pk_fma_f32 v[38:39], v[10:11], v[84:85], v[38:39] op_sel:[0,1,0] op_sel_hi:[1,1,1]
	v_pk_mul_f32 v[44:45], v[104:105], v[86:87] op_sel_hi:[1,0]
	v_pk_fma_f32 v[12:13], v[12:13], v[98:99], v[44:45] op_sel:[0,1,0] op_sel_hi:[1,1,1]
	v_pk_fma_f32 v[38:39], v[12:13], v[86:87], v[38:39] op_sel:[0,1,0] op_sel_hi:[1,1,1]
	s_waitcnt lgkmcnt(1)
	v_pk_mul_f32 v[42:43], v[104:105], v[88:89] op_sel_hi:[1,0]
	v_pk_fma_f32 v[14:15], v[14:15], v[100:101], v[42:43] op_sel:[0,0,0] op_sel_hi:[1,0,1]
	v_pk_fma_f32 v[38:39], v[14:15], v[88:89], v[38:39] op_sel:[0,1,0] op_sel_hi:[1,1,1]
	v_pk_mul_f32 v[44:45], v[104:105], v[90:91] op_sel_hi:[1,0]
	v_pk_fma_f32 v[16:17], v[16:17], v[100:101], v[44:45] op_sel:[0,1,0] op_sel_hi:[1,1,1]
	v_pk_fma_f32 v[38:39], v[16:17], v[90:91], v[38:39] op_sel:[0,1,0] op_sel_hi:[1,1,1]
	s_waitcnt lgkmcnt(0)
	v_pk_mul_f32 v[42:43], v[104:105], v[92:93] op_sel_hi:[1,0]
	v_pk_fma_f32 v[18:19], v[18:19], v[102:103], v[42:43] op_sel:[0,0,0] op_sel_hi:[1,0,1]
	v_pk_fma_f32 v[38:39], v[18:19], v[92:93], v[38:39] op_sel:[0,1,0] op_sel_hi:[1,1,1]
	v_pk_mul_f32 v[44:45], v[104:105], v[94:95] op_sel_hi:[1,0]
	v_pk_fma_f32 v[20:21], v[20:21], v[102:103], v[44:45] op_sel:[0,1,0] op_sel_hi:[1,1,1]
	v_pk_fma_f32 v[38:39], v[20:21], v[94:95], v[38:39] op_sel:[0,1,0] op_sel_hi:[1,1,1]
	s_add_u32 s14, s14, 0x1000
	s_addc_u32 s15, s15, 0
	v_add_f32_dpp v38, v38, v38 row_ror:8 row_mask:0xf bank_mask:0x3 bound_ctrl:1
	v_add_f32_dpp v38, v39, v39 row_ror:8 row_mask:0xf bank_mask:0xc bound_ctrl:1
	ds_read_b64 v[72:73], v23 offset:37632
	ds_read_b128 v[48:51], v2 offset:51456
	v_add_f32_dpp v38, v38, v38 row_half_mirror row_mask:0xf bank_mask:0xf bound_ctrl:1
	ds_read_b128 v[64:67], v22 offset:34048
	ds_read_b128 v[52:55], v2 offset:51712
	v_add_f32_dpp v38, v38, v38 quad_perm:[1,0,3,2] row_mask:0xf bank_mask:0xf bound_ctrl:1
	ds_read_b128 v[56:59], v2 offset:51968
	ds_read_b128 v[68:71], v22 offset:34304
	v_add_f32_dpp v38, v38, v38 quad_perm:[2,3,0,1] row_mask:0xf bank_mask:0xf bound_ctrl:1
	ds_read_b128 v[60:63], v2 offset:52224
	v_cvt_pk_bf16_f32 v47, v38, v38
	s_mov_b64 exec, s[2:3]
	global_store_short v28, v47, s[14:15] offset:-4096
	s_mov_b64 exec, -1
	s_waitcnt lgkmcnt(4)
	v_pk_mul_f32 v[42:43], v[72:73], v[48:49] op_sel_hi:[1,0]
	v_pk_fma_f32 v[6:7], v[6:7], v[64:65], v[42:43] op_sel:[0,0,0] op_sel_hi:[1,0,1]
	v_pk_mul_f32 v[38:39], v[6:7], v[48:49] op_sel:[0,1] op_sel_hi:[1,1]
	v_pk_mul_f32 v[44:45], v[72:73], v[50:51] op_sel_hi:[1,0]
	v_pk_fma_f32 v[8:9], v[8:9], v[64:65], v[44:45] op_sel:[0,1,0] op_sel_hi:[1,1,1]
	v_pk_fma_f32 v[38:39], v[8:9], v[50:51], v[38:39] op_sel:[0,1,0] op_sel_hi:[1,1,1]
	s_waitcnt lgkmcnt(3)
	v_pk_mul_f32 v[42:43], v[72:73], v[52:53] op_sel_hi:[1,0]
	v_pk_fma_f32 v[10:11], v[10:11], v[66:67], v[42:43] op_sel:[0,0,0] op_sel_hi:[1,0,1]
	v_pk_fma_f32 v[38:39], v[10:11], v[52:53], v[38:39] op_sel:[0,1,0] op_sel_hi:[1,1,1]
	v_pk_mul_f32 v[44:45], v[72:73], v[54:55] op_sel_hi:[1,0]
	v_pk_fma_f32 v[12:13], v[12:13], v[66:67], v[44:45] op_sel:[0,1,0] op_sel_hi:[1,1,1]
	v_pk_fma_f32 v[38:39], v[12:13], v[54:55], v[38:39] op_sel:[0,1,0] op_sel_hi:[1,1,1]
	s_waitcnt lgkmcnt(1)
	v_pk_mul_f32 v[42:43], v[72:73], v[56:57] op_sel_hi:[1,0]
	v_pk_fma_f32 v[14:15], v[14:15], v[68:69], v[42:43] op_sel:[0,0,0] op_sel_hi:[1,0,1]
	v_pk_fma_f32 v[38:39], v[14:15], v[56:57], v[38:39] op_sel:[0,1,0] op_sel_hi:[1,1,1]
	v_pk_mul_f32 v[44:45], v[72:73], v[58:59] op_sel_hi:[1,0]
	v_pk_fma_f32 v[16:17], v[16:17], v[68:69], v[44:45] op_sel:[0,1,0] op_sel_hi:[1,1,1]
	v_pk_fma_f32 v[38:39], v[16:17], v[58:59], v[38:39] op_sel:[0,1,0] op_sel_hi:[1,1,1]
	s_waitcnt lgkmcnt(0)
	v_pk_mul_f32 v[42:43], v[72:73], v[60:61] op_sel_hi:[1,0]
	v_pk_fma_f32 v[18:19], v[18:19], v[70:71], v[42:43] op_sel:[0,0,0] op_sel_hi:[1,0,1]
	v_pk_fma_f32 v[38:39], v[18:19], v[60:61], v[38:39] op_sel:[0,1,0] op_sel_hi:[1,1,1]
	v_pk_mul_f32 v[44:45], v[72:73], v[62:63] op_sel_hi:[1,0]
	v_pk_fma_f32 v[20:21], v[20:21], v[70:71], v[44:45] op_sel:[0,1,0] op_sel_hi:[1,1,1]
	v_pk_fma_f32 v[38:39], v[20:21], v[62:63], v[38:39] op_sel:[0,1,0] op_sel_hi:[1,1,1]
	s_add_u32 s14, s14, 0x1000
	s_addc_u32 s15, s15, 0
	v_add_f32_dpp v38, v38, v38 row_ror:8 row_mask:0xf bank_mask:0x3 bound_ctrl:1
	v_add_f32_dpp v38, v39, v39 row_ror:8 row_mask:0xf bank_mask:0xc bound_ctrl:1
	ds_read_b64 v[104:105], v23 offset:37888
	ds_read_b128 v[80:83], v2 offset:52480
	v_add_f32_dpp v38, v38, v38 row_half_mirror row_mask:0xf bank_mask:0xf bound_ctrl:1
	ds_read_b128 v[96:99], v22 offset:34560
	ds_read_b128 v[84:87], v2 offset:52736
	v_add_f32_dpp v38, v38, v38 quad_perm:[1,0,3,2] row_mask:0xf bank_mask:0xf bound_ctrl:1
	ds_read_b128 v[88:91], v2 offset:52992
	ds_read_b128 v[100:103], v22 offset:34816
	v_add_f32_dpp v38, v38, v38 quad_perm:[2,3,0,1] row_mask:0xf bank_mask:0xf bound_ctrl:1
	ds_read_b128 v[92:95], v2 offset:53248
	v_cvt_pk_bf16_f32 v47, v38, v38
	s_mov_b64 exec, s[2:3]
	global_store_short v28, v47, s[14:15] offset:-4096
	s_mov_b64 exec, -1
	s_waitcnt lgkmcnt(4)
	v_pk_mul_f32 v[42:43], v[104:105], v[80:81] op_sel_hi:[1,0]
	v_pk_fma_f32 v[6:7], v[6:7], v[96:97], v[42:43] op_sel:[0,0,0] op_sel_hi:[1,0,1]
	v_pk_mul_f32 v[38:39], v[6:7], v[80:81] op_sel:[0,1] op_sel_hi:[1,1]
	v_pk_mul_f32 v[44:45], v[104:105], v[82:83] op_sel_hi:[1,0]
	v_pk_fma_f32 v[8:9], v[8:9], v[96:97], v[44:45] op_sel:[0,1,0] op_sel_hi:[1,1,1]
	v_pk_fma_f32 v[38:39], v[8:9], v[82:83], v[38:39] op_sel:[0,1,0] op_sel_hi:[1,1,1]
	s_waitcnt lgkmcnt(3)
	v_pk_mul_f32 v[42:43], v[104:105], v[84:85] op_sel_hi:[1,0]
	v_pk_fma_f32 v[10:11], v[10:11], v[98:99], v[42:43] op_sel:[0,0,0] op_sel_hi:[1,0,1]
	v_pk_fma_f32 v[38:39], v[10:11], v[84:85], v[38:39] op_sel:[0,1,0] op_sel_hi:[1,1,1]
	v_pk_mul_f32 v[44:45], v[104:105], v[86:87] op_sel_hi:[1,0]
	v_pk_fma_f32 v[12:13], v[12:13], v[98:99], v[44:45] op_sel:[0,1,0] op_sel_hi:[1,1,1]
	v_pk_fma_f32 v[38:39], v[12:13], v[86:87], v[38:39] op_sel:[0,1,0] op_sel_hi:[1,1,1]
	s_waitcnt lgkmcnt(1)
	v_pk_mul_f32 v[42:43], v[104:105], v[88:89] op_sel_hi:[1,0]
	v_pk_fma_f32 v[14:15], v[14:15], v[100:101], v[42:43] op_sel:[0,0,0] op_sel_hi:[1,0,1]
	v_pk_fma_f32 v[38:39], v[14:15], v[88:89], v[38:39] op_sel:[0,1,0] op_sel_hi:[1,1,1]
	v_pk_mul_f32 v[44:45], v[104:105], v[90:91] op_sel_hi:[1,0]
	v_pk_fma_f32 v[16:17], v[16:17], v[100:101], v[44:45] op_sel:[0,1,0] op_sel_hi:[1,1,1]
	v_pk_fma_f32 v[38:39], v[16:17], v[90:91], v[38:39] op_sel:[0,1,0] op_sel_hi:[1,1,1]
	s_waitcnt lgkmcnt(0)
	v_pk_mul_f32 v[42:43], v[104:105], v[92:93] op_sel_hi:[1,0]
	v_pk_fma_f32 v[18:19], v[18:19], v[102:103], v[42:43] op_sel:[0,0,0] op_sel_hi:[1,0,1]
	v_pk_fma_f32 v[38:39], v[18:19], v[92:93], v[38:39] op_sel:[0,1,0] op_sel_hi:[1,1,1]
	v_pk_mul_f32 v[44:45], v[104:105], v[94:95] op_sel_hi:[1,0]
	v_pk_fma_f32 v[20:21], v[20:21], v[102:103], v[44:45] op_sel:[0,1,0] op_sel_hi:[1,1,1]
	v_pk_fma_f32 v[38:39], v[20:21], v[94:95], v[38:39] op_sel:[0,1,0] op_sel_hi:[1,1,1]
	s_add_u32 s14, s14, 0x1000
	s_addc_u32 s15, s15, 0
	v_add_f32_dpp v38, v38, v38 row_ror:8 row_mask:0xf bank_mask:0x3 bound_ctrl:1
	v_add_f32_dpp v38, v39, v39 row_ror:8 row_mask:0xf bank_mask:0xc bound_ctrl:1
	ds_read_b64 v[72:73], v23 offset:38144
	ds_read_b128 v[48:51], v2 offset:53504
	v_add_f32_dpp v38, v38, v38 row_half_mirror row_mask:0xf bank_mask:0xf bound_ctrl:1
	ds_read_b128 v[64:67], v22 offset:35072
	ds_read_b128 v[52:55], v2 offset:53760
	v_add_f32_dpp v38, v38, v38 quad_perm:[1,0,3,2] row_mask:0xf bank_mask:0xf bound_ctrl:1
	ds_read_b128 v[56:59], v2 offset:54016
	ds_read_b128 v[68:71], v22 offset:35328
	v_add_f32_dpp v38, v38, v38 quad_perm:[2,3,0,1] row_mask:0xf bank_mask:0xf bound_ctrl:1
	ds_read_b128 v[60:63], v2 offset:54272
	v_cvt_pk_bf16_f32 v47, v38, v38
	s_mov_b64 exec, s[2:3]
	global_store_short v28, v47, s[14:15] offset:-4096
	s_mov_b64 exec, -1
	s_waitcnt lgkmcnt(4)
	v_pk_mul_f32 v[42:43], v[72:73], v[48:49] op_sel_hi:[1,0]
	v_pk_fma_f32 v[6:7], v[6:7], v[64:65], v[42:43] op_sel:[0,0,0] op_sel_hi:[1,0,1]
	v_pk_mul_f32 v[38:39], v[6:7], v[48:49] op_sel:[0,1] op_sel_hi:[1,1]
	v_pk_mul_f32 v[44:45], v[72:73], v[50:51] op_sel_hi:[1,0]
	v_pk_fma_f32 v[8:9], v[8:9], v[64:65], v[44:45] op_sel:[0,1,0] op_sel_hi:[1,1,1]
	v_pk_fma_f32 v[38:39], v[8:9], v[50:51], v[38:39] op_sel:[0,1,0] op_sel_hi:[1,1,1]
	s_waitcnt lgkmcnt(3)
	v_pk_mul_f32 v[42:43], v[72:73], v[52:53] op_sel_hi:[1,0]
	v_pk_fma_f32 v[10:11], v[10:11], v[66:67], v[42:43] op_sel:[0,0,0] op_sel_hi:[1,0,1]
	v_pk_fma_f32 v[38:39], v[10:11], v[52:53], v[38:39] op_sel:[0,1,0] op_sel_hi:[1,1,1]
	v_pk_mul_f32 v[44:45], v[72:73], v[54:55] op_sel_hi:[1,0]
	v_pk_fma_f32 v[12:13], v[12:13], v[66:67], v[44:45] op_sel:[0,1,0] op_sel_hi:[1,1,1]
	v_pk_fma_f32 v[38:39], v[12:13], v[54:55], v[38:39] op_sel:[0,1,0] op_sel_hi:[1,1,1]
	s_waitcnt lgkmcnt(1)
	v_pk_mul_f32 v[42:43], v[72:73], v[56:57] op_sel_hi:[1,0]
	v_pk_fma_f32 v[14:15], v[14:15], v[68:69], v[42:43] op_sel:[0,0,0] op_sel_hi:[1,0,1]
	v_pk_fma_f32 v[38:39], v[14:15], v[56:57], v[38:39] op_sel:[0,1,0] op_sel_hi:[1,1,1]
	v_pk_mul_f32 v[44:45], v[72:73], v[58:59] op_sel_hi:[1,0]
	v_pk_fma_f32 v[16:17], v[16:17], v[68:69], v[44:45] op_sel:[0,1,0] op_sel_hi:[1,1,1]
	v_pk_fma_f32 v[38:39], v[16:17], v[58:59], v[38:39] op_sel:[0,1,0] op_sel_hi:[1,1,1]
	s_waitcnt lgkmcnt(0)
	v_pk_mul_f32 v[42:43], v[72:73], v[60:61] op_sel_hi:[1,0]
	v_pk_fma_f32 v[18:19], v[18:19], v[70:71], v[42:43] op_sel:[0,0,0] op_sel_hi:[1,0,1]
	v_pk_fma_f32 v[38:39], v[18:19], v[60:61], v[38:39] op_sel:[0,1,0] op_sel_hi:[1,1,1]
	v_pk_mul_f32 v[44:45], v[72:73], v[62:63] op_sel_hi:[1,0]
	v_pk_fma_f32 v[20:21], v[20:21], v[70:71], v[44:45] op_sel:[0,1,0] op_sel_hi:[1,1,1]
	v_pk_fma_f32 v[38:39], v[20:21], v[62:63], v[38:39] op_sel:[0,1,0] op_sel_hi:[1,1,1]
	s_add_u32 s14, s14, 0x1000
	s_addc_u32 s15, s15, 0
	v_add_f32_dpp v38, v38, v38 row_ror:8 row_mask:0xf bank_mask:0x3 bound_ctrl:1
	v_add_f32_dpp v38, v39, v39 row_ror:8 row_mask:0xf bank_mask:0xc bound_ctrl:1
	ds_read_b64 v[104:105], v23 offset:38400
	ds_read_b128 v[80:83], v2 offset:54528
	v_add_f32_dpp v38, v38, v38 row_half_mirror row_mask:0xf bank_mask:0xf bound_ctrl:1
	ds_read_b128 v[96:99], v22 offset:35584
	ds_read_b128 v[84:87], v2 offset:54784
	v_add_f32_dpp v38, v38, v38 quad_perm:[1,0,3,2] row_mask:0xf bank_mask:0xf bound_ctrl:1
	ds_read_b128 v[88:91], v2 offset:55040
	ds_read_b128 v[100:103], v22 offset:35840
	v_add_f32_dpp v38, v38, v38 quad_perm:[2,3,0,1] row_mask:0xf bank_mask:0xf bound_ctrl:1
	ds_read_b128 v[92:95], v2 offset:55296
	v_cvt_pk_bf16_f32 v47, v38, v38
	s_mov_b64 exec, s[2:3]
	global_store_short v28, v47, s[14:15] offset:-4096
	s_mov_b64 exec, -1
	s_waitcnt lgkmcnt(4)
	v_pk_mul_f32 v[42:43], v[104:105], v[80:81] op_sel_hi:[1,0]
	v_pk_fma_f32 v[6:7], v[6:7], v[96:97], v[42:43] op_sel:[0,0,0] op_sel_hi:[1,0,1]
	v_pk_mul_f32 v[38:39], v[6:7], v[80:81] op_sel:[0,1] op_sel_hi:[1,1]
	v_pk_mul_f32 v[44:45], v[104:105], v[82:83] op_sel_hi:[1,0]
	v_pk_fma_f32 v[8:9], v[8:9], v[96:97], v[44:45] op_sel:[0,1,0] op_sel_hi:[1,1,1]
	v_pk_fma_f32 v[38:39], v[8:9], v[82:83], v[38:39] op_sel:[0,1,0] op_sel_hi:[1,1,1]
	s_waitcnt lgkmcnt(3)
	v_pk_mul_f32 v[42:43], v[104:105], v[84:85] op_sel_hi:[1,0]
	v_pk_fma_f32 v[10:11], v[10:11], v[98:99], v[42:43] op_sel:[0,0,0] op_sel_hi:[1,0,1]
	v_pk_fma_f32 v[38:39], v[10:11], v[84:85], v[38:39] op_sel:[0,1,0] op_sel_hi:[1,1,1]
	v_pk_mul_f32 v[44:45], v[104:105], v[86:87] op_sel_hi:[1,0]
	v_pk_fma_f32 v[12:13], v[12:13], v[98:99], v[44:45] op_sel:[0,1,0] op_sel_hi:[1,1,1]
	v_pk_fma_f32 v[38:39], v[12:13], v[86:87], v[38:39] op_sel:[0,1,0] op_sel_hi:[1,1,1]
	s_waitcnt lgkmcnt(1)
	v_pk_mul_f32 v[42:43], v[104:105], v[88:89] op_sel_hi:[1,0]
	v_pk_fma_f32 v[14:15], v[14:15], v[100:101], v[42:43] op_sel:[0,0,0] op_sel_hi:[1,0,1]
	v_pk_fma_f32 v[38:39], v[14:15], v[88:89], v[38:39] op_sel:[0,1,0] op_sel_hi:[1,1,1]
	v_pk_mul_f32 v[44:45], v[104:105], v[90:91] op_sel_hi:[1,0]
	v_pk_fma_f32 v[16:17], v[16:17], v[100:101], v[44:45] op_sel:[0,1,0] op_sel_hi:[1,1,1]
	v_pk_fma_f32 v[38:39], v[16:17], v[90:91], v[38:39] op_sel:[0,1,0] op_sel_hi:[1,1,1]
	s_waitcnt lgkmcnt(0)
	v_pk_mul_f32 v[42:43], v[104:105], v[92:93] op_sel_hi:[1,0]
	v_pk_fma_f32 v[18:19], v[18:19], v[102:103], v[42:43] op_sel:[0,0,0] op_sel_hi:[1,0,1]
	v_pk_fma_f32 v[38:39], v[18:19], v[92:93], v[38:39] op_sel:[0,1,0] op_sel_hi:[1,1,1]
	v_pk_mul_f32 v[44:45], v[104:105], v[94:95] op_sel_hi:[1,0]
	v_pk_fma_f32 v[20:21], v[20:21], v[102:103], v[44:45] op_sel:[0,1,0] op_sel_hi:[1,1,1]
	v_pk_fma_f32 v[38:39], v[20:21], v[94:95], v[38:39] op_sel:[0,1,0] op_sel_hi:[1,1,1]
	s_add_u32 s14, s14, 0x1000
	s_addc_u32 s15, s15, 0
	v_add_f32_dpp v38, v38, v38 row_ror:8 row_mask:0xf bank_mask:0x3 bound_ctrl:1
	v_add_f32_dpp v38, v39, v39 row_ror:8 row_mask:0xf bank_mask:0xc bound_ctrl:1
	ds_read_b64 v[72:73], v23 offset:38656
	ds_read_b128 v[48:51], v2 offset:55552
	v_add_f32_dpp v38, v38, v38 row_half_mirror row_mask:0xf bank_mask:0xf bound_ctrl:1
	ds_read_b128 v[64:67], v22 offset:36096
	ds_read_b128 v[52:55], v2 offset:55808
	v_add_f32_dpp v38, v38, v38 quad_perm:[1,0,3,2] row_mask:0xf bank_mask:0xf bound_ctrl:1
	ds_read_b128 v[56:59], v2 offset:56064
	ds_read_b128 v[68:71], v22 offset:36352
	v_add_f32_dpp v38, v38, v38 quad_perm:[2,3,0,1] row_mask:0xf bank_mask:0xf bound_ctrl:1
	ds_read_b128 v[60:63], v2 offset:56320
	v_cvt_pk_bf16_f32 v47, v38, v38
	s_mov_b64 exec, s[2:3]
	global_store_short v28, v47, s[14:15] offset:-4096
	s_mov_b64 exec, -1
	s_waitcnt lgkmcnt(4)
	v_pk_mul_f32 v[42:43], v[72:73], v[48:49] op_sel_hi:[1,0]
	v_pk_fma_f32 v[6:7], v[6:7], v[64:65], v[42:43] op_sel:[0,0,0] op_sel_hi:[1,0,1]
	v_pk_mul_f32 v[38:39], v[6:7], v[48:49] op_sel:[0,1] op_sel_hi:[1,1]
	v_pk_mul_f32 v[44:45], v[72:73], v[50:51] op_sel_hi:[1,0]
	v_pk_fma_f32 v[8:9], v[8:9], v[64:65], v[44:45] op_sel:[0,1,0] op_sel_hi:[1,1,1]
	v_pk_fma_f32 v[38:39], v[8:9], v[50:51], v[38:39] op_sel:[0,1,0] op_sel_hi:[1,1,1]
	s_waitcnt lgkmcnt(3)
	v_pk_mul_f32 v[42:43], v[72:73], v[52:53] op_sel_hi:[1,0]
	v_pk_fma_f32 v[10:11], v[10:11], v[66:67], v[42:43] op_sel:[0,0,0] op_sel_hi:[1,0,1]
	v_pk_fma_f32 v[38:39], v[10:11], v[52:53], v[38:39] op_sel:[0,1,0] op_sel_hi:[1,1,1]
	v_pk_mul_f32 v[44:45], v[72:73], v[54:55] op_sel_hi:[1,0]
	v_pk_fma_f32 v[12:13], v[12:13], v[66:67], v[44:45] op_sel:[0,1,0] op_sel_hi:[1,1,1]
	v_pk_fma_f32 v[38:39], v[12:13], v[54:55], v[38:39] op_sel:[0,1,0] op_sel_hi:[1,1,1]
	s_waitcnt lgkmcnt(1)
	v_pk_mul_f32 v[42:43], v[72:73], v[56:57] op_sel_hi:[1,0]
	v_pk_fma_f32 v[14:15], v[14:15], v[68:69], v[42:43] op_sel:[0,0,0] op_sel_hi:[1,0,1]
	v_pk_fma_f32 v[38:39], v[14:15], v[56:57], v[38:39] op_sel:[0,1,0] op_sel_hi:[1,1,1]
	v_pk_mul_f32 v[44:45], v[72:73], v[58:59] op_sel_hi:[1,0]
	v_pk_fma_f32 v[16:17], v[16:17], v[68:69], v[44:45] op_sel:[0,1,0] op_sel_hi:[1,1,1]
	v_pk_fma_f32 v[38:39], v[16:17], v[58:59], v[38:39] op_sel:[0,1,0] op_sel_hi:[1,1,1]
	s_waitcnt lgkmcnt(0)
	v_pk_mul_f32 v[42:43], v[72:73], v[60:61] op_sel_hi:[1,0]
	v_pk_fma_f32 v[18:19], v[18:19], v[70:71], v[42:43] op_sel:[0,0,0] op_sel_hi:[1,0,1]
	v_pk_fma_f32 v[38:39], v[18:19], v[60:61], v[38:39] op_sel:[0,1,0] op_sel_hi:[1,1,1]
	v_pk_mul_f32 v[44:45], v[72:73], v[62:63] op_sel_hi:[1,0]
	v_pk_fma_f32 v[20:21], v[20:21], v[70:71], v[44:45] op_sel:[0,1,0] op_sel_hi:[1,1,1]
	v_pk_fma_f32 v[38:39], v[20:21], v[62:63], v[38:39] op_sel:[0,1,0] op_sel_hi:[1,1,1]
	s_add_u32 s14, s14, 0x1000
	s_addc_u32 s15, s15, 0
	v_add_f32_dpp v38, v38, v38 row_ror:8 row_mask:0xf bank_mask:0x3 bound_ctrl:1
	v_add_f32_dpp v38, v39, v39 row_ror:8 row_mask:0xf bank_mask:0xc bound_ctrl:1
	ds_read_b64 v[104:105], v23 offset:38912
	ds_read_b128 v[80:83], v2 offset:56576
	v_add_f32_dpp v38, v38, v38 row_half_mirror row_mask:0xf bank_mask:0xf bound_ctrl:1
	ds_read_b128 v[96:99], v22 offset:36608
	ds_read_b128 v[84:87], v2 offset:56832
	v_add_f32_dpp v38, v38, v38 quad_perm:[1,0,3,2] row_mask:0xf bank_mask:0xf bound_ctrl:1
	ds_read_b128 v[88:91], v2 offset:57088
	ds_read_b128 v[100:103], v22 offset:36864
	v_add_f32_dpp v38, v38, v38 quad_perm:[2,3,0,1] row_mask:0xf bank_mask:0xf bound_ctrl:1
	ds_read_b128 v[92:95], v2 offset:57344
	v_cvt_pk_bf16_f32 v47, v38, v38
	s_mov_b64 exec, s[2:3]
	global_store_short v28, v47, s[14:15] offset:-4096
	s_mov_b64 exec, -1
	s_waitcnt lgkmcnt(4)
	v_pk_mul_f32 v[42:43], v[104:105], v[80:81] op_sel_hi:[1,0]
	v_pk_fma_f32 v[6:7], v[6:7], v[96:97], v[42:43] op_sel:[0,0,0] op_sel_hi:[1,0,1]
	v_pk_mul_f32 v[38:39], v[6:7], v[80:81] op_sel:[0,1] op_sel_hi:[1,1]
	v_pk_mul_f32 v[44:45], v[104:105], v[82:83] op_sel_hi:[1,0]
	v_pk_fma_f32 v[8:9], v[8:9], v[96:97], v[44:45] op_sel:[0,1,0] op_sel_hi:[1,1,1]
	v_pk_fma_f32 v[38:39], v[8:9], v[82:83], v[38:39] op_sel:[0,1,0] op_sel_hi:[1,1,1]
	s_waitcnt lgkmcnt(3)
	v_pk_mul_f32 v[42:43], v[104:105], v[84:85] op_sel_hi:[1,0]
	v_pk_fma_f32 v[10:11], v[10:11], v[98:99], v[42:43] op_sel:[0,0,0] op_sel_hi:[1,0,1]
	v_pk_fma_f32 v[38:39], v[10:11], v[84:85], v[38:39] op_sel:[0,1,0] op_sel_hi:[1,1,1]
	v_pk_mul_f32 v[44:45], v[104:105], v[86:87] op_sel_hi:[1,0]
	v_pk_fma_f32 v[12:13], v[12:13], v[98:99], v[44:45] op_sel:[0,1,0] op_sel_hi:[1,1,1]
	v_pk_fma_f32 v[38:39], v[12:13], v[86:87], v[38:39] op_sel:[0,1,0] op_sel_hi:[1,1,1]
	s_waitcnt lgkmcnt(1)
	v_pk_mul_f32 v[42:43], v[104:105], v[88:89] op_sel_hi:[1,0]
	v_pk_fma_f32 v[14:15], v[14:15], v[100:101], v[42:43] op_sel:[0,0,0] op_sel_hi:[1,0,1]
	v_pk_fma_f32 v[38:39], v[14:15], v[88:89], v[38:39] op_sel:[0,1,0] op_sel_hi:[1,1,1]
	v_pk_mul_f32 v[44:45], v[104:105], v[90:91] op_sel_hi:[1,0]
	v_pk_fma_f32 v[16:17], v[16:17], v[100:101], v[44:45] op_sel:[0,1,0] op_sel_hi:[1,1,1]
	v_pk_fma_f32 v[38:39], v[16:17], v[90:91], v[38:39] op_sel:[0,1,0] op_sel_hi:[1,1,1]
	s_waitcnt lgkmcnt(0)
	v_pk_mul_f32 v[42:43], v[104:105], v[92:93] op_sel_hi:[1,0]
	v_pk_fma_f32 v[18:19], v[18:19], v[102:103], v[42:43] op_sel:[0,0,0] op_sel_hi:[1,0,1]
	v_pk_fma_f32 v[38:39], v[18:19], v[92:93], v[38:39] op_sel:[0,1,0] op_sel_hi:[1,1,1]
	v_pk_mul_f32 v[44:45], v[104:105], v[94:95] op_sel_hi:[1,0]
	v_pk_fma_f32 v[20:21], v[20:21], v[102:103], v[44:45] op_sel:[0,1,0] op_sel_hi:[1,1,1]
	v_pk_fma_f32 v[38:39], v[20:21], v[94:95], v[38:39] op_sel:[0,1,0] op_sel_hi:[1,1,1]
	s_add_u32 s14, s14, 0x1000
	s_addc_u32 s15, s15, 0
	v_add_f32_dpp v38, v38, v38 row_ror:8 row_mask:0xf bank_mask:0x3 bound_ctrl:1
	v_add_f32_dpp v38, v39, v39 row_ror:8 row_mask:0xf bank_mask:0xc bound_ctrl:1
	ds_read_b64 v[72:73], v3 offset:20736
	ds_read_b128 v[48:51], v2 offset:256
	v_add_f32_dpp v38, v38, v38 row_half_mirror row_mask:0xf bank_mask:0xf bound_ctrl:1
	ds_read_b128 v[64:67], v2 offset:16640
	ds_read_b128 v[52:55], v2 offset:512
	v_add_f32_dpp v38, v38, v38 quad_perm:[1,0,3,2] row_mask:0xf bank_mask:0xf bound_ctrl:1
	ds_read_b128 v[56:59], v2 offset:768
	ds_read_b128 v[68:71], v2 offset:16896
	v_add_f32_dpp v38, v38, v38 quad_perm:[2,3,0,1] row_mask:0xf bank_mask:0xf bound_ctrl:1
	ds_read_b128 v[60:63], v2 offset:1024
	v_cvt_pk_bf16_f32 v47, v38, v38
	s_mov_b64 exec, s[2:3]
	global_store_short v28, v47, s[14:15] offset:-4096
	s_mov_b64 exec, -1
	s_waitcnt vmcnt(8)
	v_lshlrev_b32_e32 v144, 16, v110
	v_lshlrev_b32_e32 v145, 16, v111
	v_and_b32_e32 v146, s17, v110
	v_and_b32_e32 v147, s17, v111
	v_lshlrev_b32_e32 v148, 16, v112
	v_lshlrev_b32_e32 v149, 16, v113
	v_and_b32_e32 v150, s17, v112
	v_and_b32_e32 v151, s17, v113
	v_lshlrev_b32_e32 v152, 16, v114
	v_and_b32_e32 v153, s17, v114
	v_rcp_f32_e32 v25, v24
	v_mul_f32_e32 v149, v24, v149
	v_mul_f32_e32 v151, v24, v151
	v_mul_f32_e32 v145, 0x3db504f3, v145
	v_mul_f32_e32 v147, 0x3db504f3, v147
	v_cndmask_b32_e64 v27, 1.0, v25, s[20:21]
	v_mul_f32_e32 v24, v24, v26
	v_mul_f32_e32 v152, v27, v152
	v_mul_f32_e32 v153, v27, v153
	ds_write_b128 v29, v[144:147] offset:24832
	ds_write_b128 v29, v[148:151] offset:33024
	ds_write_b64 v30, v[116:117] offset:24832
	ds_write_b64 v31, v[152:153] offset:24832
	s_add_i32 s16, s16, 8
	s_waitcnt lgkmcnt(0)
	s_barrier
	s_cmpk_lt_u32 s16, 0x800
	s_cbranch_scc1 .Lgla2_loop
